# removed the already-satisfied second lgkmcnt(0) wait at the head of each MFMA compute segment (40 sites)
# baseline (speedup 1.0000x reference)
; #define PG8_STAGE(bufoff, gbase, voff) do { _Pragma("unroll") for (int _i = 0; _i < 2; ++_i) \
;         __builtin_amdgcn_global_load_lds((const unsigned*)((const char*)(gbase) + (voff)[_i]), (PG8_LAS unsigned*)(lds + (bufoff) + ldsw + _i * 8192), 16, 0, 0); } while (0)
; #define PG8_LDA(dst, b, h) do { _Pragma("unroll") for (int m = 0; m < 4; ++m) _Pragma("unroll") for (int k = 0; k < 2; ++k) dst[m][k] = *(const PG8_LAS bf16x8*)(lds + PG8_SA(b, h) + aoff + m * 2048 + k * 1024); } while (0)
; #define PG8_LDB(dst, b, h) do { _Pragma("unroll") for (int n = 0; n < 2; ++n) _Pragma("unroll") for (int k = 0; k < 2; ++k) dst[n][k] = *(const PG8_LAS bf16x8*)(lds + PG8_SB(b, h) + boff + n * 2048 + k * 1024); } while (0)
; #define PG8_MMA(ai, bj, At, Bt) do { __builtin_amdgcn_s_setprio(1); _Pragma("unroll") for (int m = 0; m < 4; ++m) _Pragma("unroll") for (int n = 0; n < 2; ++n) _Pragma("unroll") for (int k = 0; k < 2; ++k) \
;         acc[ai][bj][m][n] = __builtin_amdgcn_mfma_f32_16x16x32_bf16(Bt[n][k], At[m][k], acc[ai][bj][m][n], 0, 0, 0); __builtin_amdgcn_s_setprio(0); } while (0)
; #define PG8_WAIT_V(n) asm volatile("s_waitcnt vmcnt(" #n ")" ::: "memory")
; #define PG8_WAIT_L(n) asm volatile("s_waitcnt lgkmcnt(" #n ")" ::: "memory")
; #define PG8_BAR __builtin_amdgcn_s_barrier()
; #define PG8_SCHED __builtin_amdgcn_sched_barrier(0)
; template <class Epi, class Sched, bool ALIGN_EPI = false, bool SP2 = false>
; __device__ __forceinline__ void gemm_phase(PG8_LAS unsigned char* lds, const Gemm g, const Sched& S, const Epi& E) {
;     ...
;             const char* a1 = cA + (size_t)(t + 1) * kstep;
;             const char* a2 = last ? nA : cA + (size_t)(t + 2) * kstep; const char* b2 = last ? nB : cB + (size_t)(t + 2) * kstep;
;             const char* a3 = a2 + kstep; const char* b3 = b2 + kstep;
;             if (last && has_next) S.a_ready(nxt);
;             if constexpr (SP2) {
;             PG8_LDB(B0, 0, 0); PG8_LDB(B1, 0, 1); PG8_SCHED; PG8_LDA(At, 0, 0); PG8_STAGE(PG8_SA(1, 1), a1 + hstepA, voffA);
;             PG8_WAIT_V(8); PG8_WAIT_L(0); PG8_BAR; PG8_MMA(0, 0, At, B0); PG8_MMA(0, 1, At, B1); PG8_BAR; PG8_SCHED;
;             PG8_LDA(At, 0, 1); PG8_STAGE(PG8_SB(0, 0), b2, voffB); PG8_STAGE(PG8_SB(0, 1), b2 + hstepB, voffB); PG8_STAGE(PG8_SA(0, 0), a2, voffA);
.LBB0_288:
	ds_read_b128 v[144:147], v159
	ds_read_b128 v[148:151], v159 offset:1024
	ds_read_b128 v[152:155], v159 offset:2048
	ds_read_b128 v[168:171], v159 offset:3072
	ds_read_b128 v[172:175], v160
	ds_read_b128 v[176:179], v160 offset:1024
	ds_read_b128 v[180:183], v160 offset:2048
	ds_read_b128 v[184:187], v160 offset:3072
	s_add_u32 s4, s36, 0xfff80080
	s_addc_u32 s5, s37, -1
	s_cmp_eq_u32 s59, 28
	s_cselect_b32 s41, s9, s5
	s_cselect_b32 s40, s11, s4
	s_cselect_b32 s39, s27, s51
	s_cselect_b32 s38, s29, s50
	v_lshl_add_u64 v[156:157], s[36:37], 0, v[136:137]
	s_add_i32 m0, s25, 0xc000
	ds_read_b128 v[188:191], v161
	ds_read_b128 v[192:195], v161 offset:1024
	ds_read_b128 v[196:199], v161 offset:2048
	ds_read_b128 v[200:203], v161 offset:3072
	ds_read_b128 v[204:207], v161 offset:4096
	ds_read_b128 v[208:211], v161 offset:5120
	ds_read_b128 v[212:215], v161 offset:6144
	ds_read_b128 v[216:219], v161 offset:7168
	global_load_lds_dwordx4 v[156:157], off
	v_lshl_add_u64 v[156:157], s[36:37], 0, v[138:139]
	s_add_i32 m0, s25, 0xe000
	s_nop 0
	global_load_lds_dwordx4 v[156:157], off
	s_waitcnt vmcnt(8)
	s_waitcnt lgkmcnt(0)
	s_barrier
	s_setprio 1
	v_mfma_f32_16x16x32_bf16 v[124:127], v[144:147], v[188:191], v[124:127]
	v_mfma_f32_16x16x32_bf16 v[120:123], v[152:155], v[188:191], v[120:123]
	v_mfma_f32_16x16x32_bf16 v[108:111], v[144:147], v[196:199], v[108:111]
	v_mfma_f32_16x16x32_bf16 v[104:107], v[152:155], v[196:199], v[104:107]
	v_mfma_f32_16x16x32_bf16 v[92:95], v[144:147], v[204:207], v[92:95]
	v_mfma_f32_16x16x32_bf16 v[88:91], v[152:155], v[204:207], v[88:91]
	v_mfma_f32_16x16x32_bf16 v[76:79], v[144:147], v[212:215], v[76:79]
	v_mfma_f32_16x16x32_bf16 v[72:75], v[152:155], v[212:215], v[72:75]
	v_mfma_f32_16x16x32_bf16 v[124:127], v[148:151], v[192:195], v[124:127]
	v_mfma_f32_16x16x32_bf16 v[120:123], v[168:171], v[192:195], v[120:123]
	v_mfma_f32_16x16x32_bf16 v[108:111], v[148:151], v[200:203], v[108:111]
	v_mfma_f32_16x16x32_bf16 v[104:107], v[168:171], v[200:203], v[104:107]
	v_mfma_f32_16x16x32_bf16 v[92:95], v[148:151], v[208:211], v[92:95]
	v_mfma_f32_16x16x32_bf16 v[88:91], v[168:171], v[208:211], v[88:91]
	v_mfma_f32_16x16x32_bf16 v[76:79], v[148:151], v[216:219], v[76:79]
	v_mfma_f32_16x16x32_bf16 v[72:75], v[168:171], v[216:219], v[72:75]
	v_mfma_f32_16x16x32_bf16 v[116:119], v[172:175], v[188:191], v[116:119]
	v_mfma_f32_16x16x32_bf16 v[112:115], v[180:183], v[188:191], v[112:115]
	v_mfma_f32_16x16x32_bf16 v[100:103], v[172:175], v[196:199], v[100:103]
	v_mfma_f32_16x16x32_bf16 v[96:99], v[180:183], v[196:199], v[96:99]
	v_mfma_f32_16x16x32_bf16 v[84:87], v[172:175], v[204:207], v[84:87]
	v_mfma_f32_16x16x32_bf16 v[80:83], v[180:183], v[204:207], v[80:83]
	v_mfma_f32_16x16x32_bf16 v[68:71], v[172:175], v[212:215], v[68:71]
	v_mfma_f32_16x16x32_bf16 v[64:67], v[180:183], v[212:215], v[64:67]
	v_mfma_f32_16x16x32_bf16 v[116:119], v[176:179], v[192:195], v[116:119]
	v_mfma_f32_16x16x32_bf16 v[112:115], v[184:187], v[192:195], v[112:115]
	v_mfma_f32_16x16x32_bf16 v[100:103], v[176:179], v[200:203], v[100:103]
	v_mfma_f32_16x16x32_bf16 v[96:99], v[184:187], v[200:203], v[96:99]
	v_mfma_f32_16x16x32_bf16 v[84:87], v[176:179], v[208:211], v[84:87]
	v_mfma_f32_16x16x32_bf16 v[80:83], v[184:187], v[208:211], v[80:83]
	v_mfma_f32_16x16x32_bf16 v[68:71], v[176:179], v[216:219], v[68:71]
	v_mfma_f32_16x16x32_bf16 v[64:67], v[184:187], v[216:219], v[64:67]
	s_setprio 0
	s_barrier
	s_add_i32 s4, s55, s47
	v_lshl_add_u64 v[156:157], s[38:39], 0, v[130:131]
	s_mov_b32 m0, s4
	ds_read_b128 v[188:191], v161 offset:16384
	ds_read_b128 v[192:195], v161 offset:17408
	ds_read_b128 v[196:199], v161 offset:18432
	ds_read_b128 v[200:203], v161 offset:19456
	ds_read_b128 v[204:207], v161 offset:20480
	ds_read_b128 v[208:211], v161 offset:21504
	ds_read_b128 v[212:215], v161 offset:22528
	ds_read_b128 v[216:219], v161 offset:23552
	global_load_lds_dwordx4 v[156:157], off
	s_add_i32 m0, s4, 0x2000
	s_add_u32 s60, s38, 0x80000
	v_lshl_add_u64 v[164:165], s[38:39], 0, v[134:135]
	s_addc_u32 s61, s39, 0
	s_add_i32 s4, s56, s47
	global_load_lds_dwordx4 v[164:165], off
	v_lshl_add_u64 v[220:221], s[60:61], 0, v[130:131]
	s_mov_b32 m0, s4
	v_lshl_add_u64 v[222:223], s[40:41], 0, v[132:133]
	global_load_lds_dwordx4 v[220:221], off
	v_lshl_add_u64 v[220:221], s[60:61], 0, v[134:135]
	s_add_i32 m0, s4, 0x2000
	s_nop 0
	global_load_lds_dwordx4 v[220:221], off
	v_lshl_add_u64 v[220:221], s[40:41], 0, v[128:129]
	s_mov_b32 m0, s25
	s_nop 0
	global_load_lds_dwordx4 v[220:221], off
	s_mov_b32 m0, s33
	s_nop 0
	global_load_lds_dwordx4 v[222:223], off
	s_waitcnt vmcnt(8)
	s_waitcnt lgkmcnt(0)
	s_barrier
; #define PG8_STAGE(bufoff, gbase, voff) do { _Pragma("unroll") for (int _i = 0; _i < 2; ++_i) \
;         __builtin_amdgcn_global_load_lds((const unsigned*)((const char*)(gbase) + (voff)[_i]), (PG8_LAS unsigned*)(lds + (bufoff) + ldsw + _i * 8192), 16, 0, 0); } while (0)
; #define PG8_LDA(dst, b, h) do { _Pragma("unroll") for (int m = 0; m < 4; ++m) _Pragma("unroll") for (int k = 0; k < 2; ++k) dst[m][k] = *(const PG8_LAS bf16x8*)(lds + PG8_SA(b, h) + aoff + m * 2048 + k * 1024); } while (0)
; #define PG8_LDB(dst, b, h) do { _Pragma("unroll") for (int n = 0; n < 2; ++n) _Pragma("unroll") for (int k = 0; k < 2; ++k) dst[n][k] = *(const PG8_LAS bf16x8*)(lds + PG8_SB(b, h) + boff + n * 2048 + k * 1024); } while (0)
; #define PG8_MMA(ai, bj, At, Bt) do { __builtin_amdgcn_s_setprio(1); _Pragma("unroll") for (int m = 0; m < 4; ++m) _Pragma("unroll") for (int n = 0; n < 2; ++n) _Pragma("unroll") for (int k = 0; k < 2; ++k) \
;         acc[ai][bj][m][n] = __builtin_amdgcn_mfma_f32_16x16x32_bf16(Bt[n][k], At[m][k], acc[ai][bj][m][n], 0, 0, 0); __builtin_amdgcn_s_setprio(0); } while (0)
; #define PG8_WAIT_V(n) asm volatile("s_waitcnt vmcnt(" #n ")" ::: "memory")
; #define PG8_WAIT_L(n) asm volatile("s_waitcnt lgkmcnt(" #n ")" ::: "memory")
; #define PG8_BAR __builtin_amdgcn_s_barrier()
; #define PG8_SCHED __builtin_amdgcn_sched_barrier(0)
; template <class Epi, class Sched, bool ALIGN_EPI = false, bool SP2 = false>
; __device__ __forceinline__ void gemm_phase(PG8_LAS unsigned char* lds, const Gemm g, const Sched& S, const Epi& E) {
;     ...
;             PG8_WAIT_V(8); PG8_WAIT_L(0); PG8_BAR; PG8_MMA(1, 0, At, B0); PG8_MMA(1, 1, At, B1); PG8_BAR; PG8_SCHED;
;             PG8_LDB(B0, 1, 0); PG8_LDB(B1, 1, 1); PG8_SCHED; PG8_LDA(At, 1, 0); PG8_STAGE(PG8_SA(0, 1), a2 + hstepA, voffA);
;             PG8_WAIT_V(8); PG8_WAIT_L(0); PG8_BAR; PG8_MMA(0, 0, At, B0); PG8_MMA(0, 1, At, B1); PG8_BAR; PG8_SCHED;
	s_setprio 1
	v_mfma_f32_16x16x32_bf16 v[60:63], v[144:147], v[188:191], v[60:63]
	v_mfma_f32_16x16x32_bf16 v[56:59], v[152:155], v[188:191], v[56:59]
	v_mfma_f32_16x16x32_bf16 v[44:47], v[144:147], v[196:199], v[44:47]
	v_mfma_f32_16x16x32_bf16 v[40:43], v[152:155], v[196:199], v[40:43]
	v_mfma_f32_16x16x32_bf16 v[28:31], v[144:147], v[204:207], v[28:31]
	v_mfma_f32_16x16x32_bf16 v[24:27], v[152:155], v[204:207], v[24:27]
	v_mfma_f32_16x16x32_bf16 v[12:15], v[144:147], v[212:215], v[12:15]
	v_mfma_f32_16x16x32_bf16 v[8:11], v[152:155], v[212:215], v[8:11]
	v_mfma_f32_16x16x32_bf16 v[60:63], v[148:151], v[192:195], v[60:63]
	v_mfma_f32_16x16x32_bf16 v[56:59], v[168:171], v[192:195], v[56:59]
	v_mfma_f32_16x16x32_bf16 v[44:47], v[148:151], v[200:203], v[44:47]
	v_mfma_f32_16x16x32_bf16 v[40:43], v[168:171], v[200:203], v[40:43]
	v_mfma_f32_16x16x32_bf16 v[28:31], v[148:151], v[208:211], v[28:31]
	v_mfma_f32_16x16x32_bf16 v[24:27], v[168:171], v[208:211], v[24:27]
	v_mfma_f32_16x16x32_bf16 v[12:15], v[148:151], v[216:219], v[12:15]
	v_mfma_f32_16x16x32_bf16 v[8:11], v[168:171], v[216:219], v[8:11]
	v_mfma_f32_16x16x32_bf16 v[52:55], v[172:175], v[188:191], v[52:55]
	v_mfma_f32_16x16x32_bf16 v[48:51], v[180:183], v[188:191], v[48:51]
	v_mfma_f32_16x16x32_bf16 v[36:39], v[172:175], v[196:199], v[36:39]
	v_mfma_f32_16x16x32_bf16 v[32:35], v[180:183], v[196:199], v[32:35]
	v_mfma_f32_16x16x32_bf16 v[20:23], v[172:175], v[204:207], v[20:23]
	v_mfma_f32_16x16x32_bf16 v[16:19], v[180:183], v[204:207], v[16:19]
	v_mfma_f32_16x16x32_bf16 v[4:7], v[172:175], v[212:215], v[4:7]
	v_mfma_f32_16x16x32_bf16 v[0:3], v[180:183], v[212:215], v[0:3]
	v_mfma_f32_16x16x32_bf16 v[52:55], v[176:179], v[192:195], v[52:55]
	v_mfma_f32_16x16x32_bf16 v[48:51], v[184:187], v[192:195], v[48:51]
	v_mfma_f32_16x16x32_bf16 v[36:39], v[176:179], v[200:203], v[36:39]
	v_mfma_f32_16x16x32_bf16 v[32:35], v[184:187], v[200:203], v[32:35]
	v_mfma_f32_16x16x32_bf16 v[20:23], v[176:179], v[208:211], v[20:23]
	v_mfma_f32_16x16x32_bf16 v[16:19], v[184:187], v[208:211], v[16:19]
	v_mfma_f32_16x16x32_bf16 v[4:7], v[176:179], v[216:219], v[4:7]
	v_mfma_f32_16x16x32_bf16 v[0:3], v[184:187], v[216:219], v[0:3]
	s_setprio 0
	s_barrier
	s_add_i32 s4, 0, 0x18000
	v_add_u32_e32 v163, s4, v158
	s_add_i32 s5, 0, 0x1c000
	ds_read_b128 v[144:147], v163
	ds_read_b128 v[148:151], v163 offset:1024
	ds_read_b128 v[152:155], v163 offset:2048
	ds_read_b128 v[168:171], v163 offset:3072
	v_add_u32_e32 v163, s5, v158
	ds_read_b128 v[172:175], v163
	ds_read_b128 v[176:179], v163 offset:1024
	ds_read_b128 v[180:183], v163 offset:2048
	ds_read_b128 v[184:187], v163 offset:3072
	s_add_u32 s40, s40, 0x80000
	s_addc_u32 s41, s41, 0
	s_mov_b32 m0, s44
	v_lshl_add_u64 v[224:225], s[40:41], 0, v[128:129]
	ds_read_b128 v[188:191], v161 offset:32768
	ds_read_b128 v[192:195], v161 offset:33792
	ds_read_b128 v[196:199], v161 offset:34816
	ds_read_b128 v[200:203], v161 offset:35840
	ds_read_b128 v[204:207], v161 offset:36864
	ds_read_b128 v[208:211], v161 offset:37888
	ds_read_b128 v[212:215], v161 offset:38912
	ds_read_b128 v[216:219], v161 offset:39936
	global_load_lds_dwordx4 v[224:225], off
	v_lshl_add_u64 v[224:225], s[40:41], 0, v[132:133]
	s_mov_b32 m0, s45
	s_nop 0
	global_load_lds_dwordx4 v[224:225], off
	s_waitcnt vmcnt(8)
	s_waitcnt lgkmcnt(0)
	s_barrier
	s_setprio 1
	v_mfma_f32_16x16x32_bf16 v[124:127], v[144:147], v[188:191], v[124:127]
	v_mfma_f32_16x16x32_bf16 v[120:123], v[152:155], v[188:191], v[120:123]
	v_mfma_f32_16x16x32_bf16 v[108:111], v[144:147], v[196:199], v[108:111]
	v_mfma_f32_16x16x32_bf16 v[104:107], v[152:155], v[196:199], v[104:107]
	v_mfma_f32_16x16x32_bf16 v[92:95], v[144:147], v[204:207], v[92:95]
	v_mfma_f32_16x16x32_bf16 v[88:91], v[152:155], v[204:207], v[88:91]
	v_mfma_f32_16x16x32_bf16 v[76:79], v[144:147], v[212:215], v[76:79]
	v_mfma_f32_16x16x32_bf16 v[72:75], v[152:155], v[212:215], v[72:75]
	v_mfma_f32_16x16x32_bf16 v[124:127], v[148:151], v[192:195], v[124:127]
	v_mfma_f32_16x16x32_bf16 v[120:123], v[168:171], v[192:195], v[120:123]
	v_mfma_f32_16x16x32_bf16 v[108:111], v[148:151], v[200:203], v[108:111]
	v_mfma_f32_16x16x32_bf16 v[104:107], v[168:171], v[200:203], v[104:107]
	v_mfma_f32_16x16x32_bf16 v[92:95], v[148:151], v[208:211], v[92:95]
	v_mfma_f32_16x16x32_bf16 v[88:91], v[168:171], v[208:211], v[88:91]
	v_mfma_f32_16x16x32_bf16 v[76:79], v[148:151], v[216:219], v[76:79]
	v_mfma_f32_16x16x32_bf16 v[72:75], v[168:171], v[216:219], v[72:75]
	v_mfma_f32_16x16x32_bf16 v[116:119], v[172:175], v[188:191], v[116:119]
	v_mfma_f32_16x16x32_bf16 v[112:115], v[180:183], v[188:191], v[112:115]
	v_mfma_f32_16x16x32_bf16 v[100:103], v[172:175], v[196:199], v[100:103]
	v_mfma_f32_16x16x32_bf16 v[96:99], v[180:183], v[196:199], v[96:99]
	v_mfma_f32_16x16x32_bf16 v[84:87], v[172:175], v[204:207], v[84:87]
	v_mfma_f32_16x16x32_bf16 v[80:83], v[180:183], v[204:207], v[80:83]
	v_mfma_f32_16x16x32_bf16 v[68:71], v[172:175], v[212:215], v[68:71]
	v_mfma_f32_16x16x32_bf16 v[64:67], v[180:183], v[212:215], v[64:67]
	v_mfma_f32_16x16x32_bf16 v[116:119], v[176:179], v[192:195], v[116:119]
	v_mfma_f32_16x16x32_bf16 v[112:115], v[184:187], v[192:195], v[112:115]
	v_mfma_f32_16x16x32_bf16 v[100:103], v[176:179], v[200:203], v[100:103]
	v_mfma_f32_16x16x32_bf16 v[96:99], v[184:187], v[200:203], v[96:99]
	v_mfma_f32_16x16x32_bf16 v[84:87], v[176:179], v[208:211], v[84:87]
	v_mfma_f32_16x16x32_bf16 v[80:83], v[184:187], v[208:211], v[80:83]
	v_mfma_f32_16x16x32_bf16 v[68:71], v[176:179], v[216:219], v[68:71]
	v_mfma_f32_16x16x32_bf16 v[64:67], v[184:187], v[216:219], v[64:67]
	s_setprio 0
	s_barrier
; #define PG8_STAGE(bufoff, gbase, voff) do { _Pragma("unroll") for (int _i = 0; _i < 2; ++_i) \
;         __builtin_amdgcn_global_load_lds((const unsigned*)((const char*)(gbase) + (voff)[_i]), (PG8_LAS unsigned*)(lds + (bufoff) + ldsw + _i * 8192), 16, 0, 0); } while (0)
; #define PG8_LDA(dst, b, h) do { _Pragma("unroll") for (int m = 0; m < 4; ++m) _Pragma("unroll") for (int k = 0; k < 2; ++k) dst[m][k] = *(const PG8_LAS bf16x8*)(lds + PG8_SA(b, h) + aoff + m * 2048 + k * 1024); } while (0)
; #define PG8_LDB(dst, b, h) do { _Pragma("unroll") for (int n = 0; n < 2; ++n) _Pragma("unroll") for (int k = 0; k < 2; ++k) dst[n][k] = *(const PG8_LAS bf16x8*)(lds + PG8_SB(b, h) + boff + n * 2048 + k * 1024); } while (0)
; #define PG8_MMA(ai, bj, At, Bt) do { __builtin_amdgcn_s_setprio(1); _Pragma("unroll") for (int m = 0; m < 4; ++m) _Pragma("unroll") for (int n = 0; n < 2; ++n) _Pragma("unroll") for (int k = 0; k < 2; ++k) \
;         acc[ai][bj][m][n] = __builtin_amdgcn_mfma_f32_16x16x32_bf16(Bt[n][k], At[m][k], acc[ai][bj][m][n], 0, 0, 0); __builtin_amdgcn_s_setprio(0); } while (0)
; #define PG8_WAIT_V(n) asm volatile("s_waitcnt vmcnt(" #n ")" ::: "memory")
; template <class Epi, class Sched, bool ALIGN_EPI = false, bool SP2 = false>
; __device__ __forceinline__ void gemm_phase(PG8_LAS unsigned char* lds, const Gemm g, const Sched& S, const Epi& E) {
;     ...
;             PG8_LDB(B0, 0, 0); PG8_LDB(B1, 0, 1); PG8_SCHED; PG8_LDA(At, 0, 0); PG8_STAGE(PG8_SA(1, 1), a1 + hstepA, voffA);
;             PG8_WAIT_V(8); PG8_WAIT_L(0); PG8_BAR; PG8_MMA(0, 0, At, B0); PG8_MMA(0, 1, At, B1); PG8_BAR; PG8_SCHED;
;             PG8_LDA(At, 0, 1); PG8_STAGE(PG8_SB(0, 0), b2, voffB); PG8_STAGE(PG8_SB(0, 1), b2 + hstepB, voffB); PG8_STAGE(PG8_SA(0, 0), a2, voffA);
;             PG8_WAIT_V(8); PG8_WAIT_L(0); PG8_BAR; PG8_MMA(1, 0, At, B0); PG8_MMA(1, 1, At, B1); PG8_BAR; PG8_SCHED;
;             PG8_LDB(B0, 1, 0); PG8_LDB(B1, 1, 1); PG8_SCHED; PG8_LDA(At, 1, 0); PG8_STAGE(PG8_SA(0, 1), a2 + hstepA, voffA);
;             PG8_WAIT_V(8); PG8_WAIT_L(0); PG8_BAR; PG8_MMA(0, 0, At, B0); PG8_MMA(0, 1, At, B1); PG8_BAR; PG8_SCHED;
;             PG8_LDA(At, 1, 1); PG8_STAGE(PG8_SB(1, 0), b3, voffB); PG8_STAGE(PG8_SB(1, 1), b3 + hstepB, voffB); PG8_STAGE(PG8_SA(1, 0), a3, voffA);
;             PG8_WAIT_V(8); PG8_WAIT_L(0); PG8_BAR; PG8_MMA(1, 0, At, B0); PG8_MMA(1, 1, At, B1); PG8_BAR; PG8_SCHED;
	s_add_i32 s4, s4, s47
	v_lshl_add_u64 v[156:157], v[156:157], 0, s[22:23]
	s_mov_b32 m0, s4
	ds_read_b128 v[188:191], v161 offset:49152
	ds_read_b128 v[192:195], v161 offset:50176
	ds_read_b128 v[196:199], v161 offset:51200
	ds_read_b128 v[200:203], v161 offset:52224
	ds_read_b128 v[204:207], v161 offset:53248
	ds_read_b128 v[208:211], v161 offset:54272
	ds_read_b128 v[212:215], v161 offset:55296
	ds_read_b128 v[216:219], v161 offset:56320
	global_load_lds_dwordx4 v[156:157], off
	s_add_i32 m0, s4, 0x2000
	s_add_u32 s38, s38, 0x80080
	v_lshl_add_u64 v[156:157], v[164:165], 0, s[22:23]
	s_addc_u32 s39, s39, 0
	s_add_i32 s4, s5, s47
	global_load_lds_dwordx4 v[156:157], off
	v_lshl_add_u64 v[156:157], s[38:39], 0, v[130:131]
	s_mov_b32 m0, s4
	s_nop 0
	global_load_lds_dwordx4 v[156:157], off
	v_lshl_add_u64 v[156:157], s[38:39], 0, v[134:135]
	s_add_i32 m0, s4, 0x2000
	s_nop 0
	global_load_lds_dwordx4 v[156:157], off
	v_lshl_add_u64 v[156:157], v[220:221], 0, s[22:23]
	s_mov_b32 m0, s46
	s_nop 0
	global_load_lds_dwordx4 v[156:157], off
	v_lshl_add_u64 v[156:157], v[222:223], 0, s[22:23]
	s_mov_b32 m0, s53
	s_nop 0
	global_load_lds_dwordx4 v[156:157], off
	s_waitcnt vmcnt(8)
	s_waitcnt lgkmcnt(0)
	s_barrier
	s_setprio 1
	v_mfma_f32_16x16x32_bf16 v[60:63], v[144:147], v[188:191], v[60:63]
	v_mfma_f32_16x16x32_bf16 v[56:59], v[152:155], v[188:191], v[56:59]
	v_mfma_f32_16x16x32_bf16 v[44:47], v[144:147], v[196:199], v[44:47]
	v_mfma_f32_16x16x32_bf16 v[40:43], v[152:155], v[196:199], v[40:43]
	v_mfma_f32_16x16x32_bf16 v[28:31], v[144:147], v[204:207], v[28:31]
	v_mfma_f32_16x16x32_bf16 v[24:27], v[152:155], v[204:207], v[24:27]
	v_mfma_f32_16x16x32_bf16 v[12:15], v[144:147], v[212:215], v[12:15]
	v_mfma_f32_16x16x32_bf16 v[8:11], v[152:155], v[212:215], v[8:11]
	v_mfma_f32_16x16x32_bf16 v[60:63], v[148:151], v[192:195], v[60:63]
	v_mfma_f32_16x16x32_bf16 v[56:59], v[168:171], v[192:195], v[56:59]
	v_mfma_f32_16x16x32_bf16 v[44:47], v[148:151], v[200:203], v[44:47]
	v_mfma_f32_16x16x32_bf16 v[40:43], v[168:171], v[200:203], v[40:43]
	v_mfma_f32_16x16x32_bf16 v[28:31], v[148:151], v[208:211], v[28:31]
	v_mfma_f32_16x16x32_bf16 v[24:27], v[168:171], v[208:211], v[24:27]
	v_mfma_f32_16x16x32_bf16 v[12:15], v[148:151], v[216:219], v[12:15]
	v_mfma_f32_16x16x32_bf16 v[8:11], v[168:171], v[216:219], v[8:11]
	v_mfma_f32_16x16x32_bf16 v[52:55], v[172:175], v[188:191], v[52:55]
	v_mfma_f32_16x16x32_bf16 v[48:51], v[180:183], v[188:191], v[48:51]
	v_mfma_f32_16x16x32_bf16 v[36:39], v[172:175], v[196:199], v[36:39]
	v_mfma_f32_16x16x32_bf16 v[32:35], v[180:183], v[196:199], v[32:35]
	v_mfma_f32_16x16x32_bf16 v[20:23], v[172:175], v[204:207], v[20:23]
	v_mfma_f32_16x16x32_bf16 v[16:19], v[180:183], v[204:207], v[16:19]
	v_mfma_f32_16x16x32_bf16 v[4:7], v[172:175], v[212:215], v[4:7]
	v_mfma_f32_16x16x32_bf16 v[0:3], v[180:183], v[212:215], v[0:3]
	v_mfma_f32_16x16x32_bf16 v[52:55], v[176:179], v[192:195], v[52:55]
	v_mfma_f32_16x16x32_bf16 v[48:51], v[184:187], v[192:195], v[48:51]
	v_mfma_f32_16x16x32_bf16 v[36:39], v[176:179], v[200:203], v[36:39]
	v_mfma_f32_16x16x32_bf16 v[32:35], v[184:187], v[200:203], v[32:35]
	v_mfma_f32_16x16x32_bf16 v[20:23], v[176:179], v[208:211], v[20:23]
	v_mfma_f32_16x16x32_bf16 v[16:19], v[184:187], v[208:211], v[16:19]
	v_mfma_f32_16x16x32_bf16 v[4:7], v[176:179], v[216:219], v[4:7]
	v_mfma_f32_16x16x32_bf16 v[0:3], v[184:187], v[216:219], v[0:3]
	s_setprio 0
	s_barrier
	s_add_i32 s59, s59, 2
	s_add_u32 s36, s36, 0x100
	s_addc_u32 s37, s37, 0
	s_add_u32 s50, s50, 0x100
	s_addc_u32 s51, s51, 0
	s_cmp_gt_u32 s59, 29
	s_cbranch_scc0 .LBB0_288
	s_and_b64 vcc, exec, s[48:49]
	s_cbranch_vccz .LBB0_291
	s_barrier

; #define PG8_STAGE(bufoff, gbase, voff) do { _Pragma("unroll") for (int _i = 0; _i < 2; ++_i) \
;         __builtin_amdgcn_global_load_lds((const unsigned*)((const char*)(gbase) + (voff)[_i]), (PG8_LAS unsigned*)(lds + (bufoff) + ldsw + _i * 8192), 16, 0, 0); } while (0)
; #define PG8_LDA(dst, b, h) do { _Pragma("unroll") for (int m = 0; m < 4; ++m) _Pragma("unroll") for (int k = 0; k < 2; ++k) dst[m][k] = *(const PG8_LAS bf16x8*)(lds + PG8_SA(b, h) + aoff + m * 2048 + k * 1024); } while (0)
; #define PG8_LDB(dst, b, h) do { _Pragma("unroll") for (int n = 0; n < 2; ++n) _Pragma("unroll") for (int k = 0; k < 2; ++k) dst[n][k] = *(const PG8_LAS bf16x8*)(lds + PG8_SB(b, h) + boff + n * 2048 + k * 1024); } while (0)
; #define PG8_MMA(ai, bj, At, Bt) do { __builtin_amdgcn_s_setprio(1); _Pragma("unroll") for (int m = 0; m < 4; ++m) _Pragma("unroll") for (int n = 0; n < 2; ++n) _Pragma("unroll") for (int k = 0; k < 2; ++k) \
;         acc[ai][bj][m][n] = __builtin_amdgcn_mfma_f32_16x16x32_bf16(Bt[n][k], At[m][k], acc[ai][bj][m][n], 0, 0, 0); __builtin_amdgcn_s_setprio(0); } while (0)
; #define PG8_WAIT_V(n) asm volatile("s_waitcnt vmcnt(" #n ")" ::: "memory")
; #define PG8_WAIT_L(n) asm volatile("s_waitcnt lgkmcnt(" #n ")" ::: "memory")
; #define PG8_BAR __builtin_amdgcn_s_barrier()
; #define PG8_SCHED __builtin_amdgcn_sched_barrier(0)
; template <class Epi, class Sched, bool ALIGN_EPI = false, bool SP2 = false>
; __device__ __forceinline__ void gemm_phase(PG8_LAS unsigned char* lds, const Gemm g, const Sched& S, const Epi& E) {
;     ...
;             const char* a1 = cA + (size_t)(t + 1) * kstep;
;             const char* a2 = last ? nA : cA + (size_t)(t + 2) * kstep; const char* b2 = last ? nB : cB + (size_t)(t + 2) * kstep;
;             const char* a3 = a2 + kstep; const char* b3 = b2 + kstep;
;             if (last && has_next) S.a_ready(nxt);
;             if constexpr (SP2) {
;             PG8_LDB(B0, 0, 0); PG8_LDB(B1, 0, 1); PG8_SCHED; PG8_LDA(At, 0, 0); PG8_STAGE(PG8_SA(1, 1), a1 + hstepA, voffA);
;             PG8_WAIT_V(8); PG8_WAIT_L(0); PG8_BAR; PG8_MMA(0, 0, At, B0); PG8_MMA(0, 1, At, B1); PG8_BAR; PG8_SCHED;
;             PG8_LDA(At, 0, 1); PG8_STAGE(PG8_SB(0, 0), b2, voffB); PG8_STAGE(PG8_SB(0, 1), b2 + hstepB, voffB); PG8_STAGE(PG8_SA(0, 0), a2, voffA);
.LBB0_660:
	ds_read_b128 v[144:147], v149
	ds_read_b128 v[152:155], v149 offset:1024
	ds_read_b128 v[156:159], v149 offset:2048
	ds_read_b128 v[160:163], v149 offset:3072
	ds_read_b128 v[168:171], v150
	ds_read_b128 v[172:175], v150 offset:1024
	ds_read_b128 v[176:179], v150 offset:2048
	ds_read_b128 v[180:183], v150 offset:3072
	s_add_u32 s4, s30, 0xfff80080
	s_addc_u32 s5, s31, -1
	s_cmp_eq_u32 s56, 28
	s_cselect_b32 s37, s21, s5
	s_cselect_b32 s36, s29, s4
	s_cselect_b32 s35, s19, s55
	s_cselect_b32 s34, s53, s54
	v_lshl_add_u64 v[164:165], s[30:31], 0, v[136:137]
	s_add_i32 m0, s25, 0xc000
	ds_read_b128 v[184:187], v151
	ds_read_b128 v[188:191], v151 offset:1024
	ds_read_b128 v[192:195], v151 offset:2048
	ds_read_b128 v[196:199], v151 offset:3072
	ds_read_b128 v[200:203], v151 offset:4096
	ds_read_b128 v[204:207], v151 offset:5120
	ds_read_b128 v[208:211], v151 offset:6144
	ds_read_b128 v[212:215], v151 offset:7168
	global_load_lds_dwordx4 v[164:165], off
	v_lshl_add_u64 v[164:165], s[30:31], 0, v[138:139]
	s_add_i32 m0, s25, 0xe000
	s_nop 0
	global_load_lds_dwordx4 v[164:165], off
	s_waitcnt vmcnt(8)
	s_waitcnt lgkmcnt(0)
	s_barrier
	s_setprio 1
	v_mfma_f32_16x16x32_bf16 v[124:127], v[144:147], v[184:187], v[124:127]
	v_mfma_f32_16x16x32_bf16 v[120:123], v[156:159], v[184:187], v[120:123]
	v_mfma_f32_16x16x32_bf16 v[108:111], v[144:147], v[192:195], v[108:111]
	v_mfma_f32_16x16x32_bf16 v[104:107], v[156:159], v[192:195], v[104:107]
	v_mfma_f32_16x16x32_bf16 v[92:95], v[144:147], v[200:203], v[92:95]
	v_mfma_f32_16x16x32_bf16 v[88:91], v[156:159], v[200:203], v[88:91]
	v_mfma_f32_16x16x32_bf16 v[76:79], v[144:147], v[208:211], v[76:79]
	v_mfma_f32_16x16x32_bf16 v[72:75], v[156:159], v[208:211], v[72:75]
	v_mfma_f32_16x16x32_bf16 v[124:127], v[152:155], v[188:191], v[124:127]
	v_mfma_f32_16x16x32_bf16 v[120:123], v[160:163], v[188:191], v[120:123]
	v_mfma_f32_16x16x32_bf16 v[108:111], v[152:155], v[196:199], v[108:111]
	v_mfma_f32_16x16x32_bf16 v[104:107], v[160:163], v[196:199], v[104:107]
	v_mfma_f32_16x16x32_bf16 v[92:95], v[152:155], v[204:207], v[92:95]
	v_mfma_f32_16x16x32_bf16 v[88:91], v[160:163], v[204:207], v[88:91]
	v_mfma_f32_16x16x32_bf16 v[76:79], v[152:155], v[212:215], v[76:79]
	v_mfma_f32_16x16x32_bf16 v[72:75], v[160:163], v[212:215], v[72:75]
	v_mfma_f32_16x16x32_bf16 v[116:119], v[168:171], v[184:187], v[116:119]
	v_mfma_f32_16x16x32_bf16 v[112:115], v[176:179], v[184:187], v[112:115]
	v_mfma_f32_16x16x32_bf16 v[100:103], v[168:171], v[192:195], v[100:103]
	v_mfma_f32_16x16x32_bf16 v[96:99], v[176:179], v[192:195], v[96:99]
	v_mfma_f32_16x16x32_bf16 v[84:87], v[168:171], v[200:203], v[84:87]
	v_mfma_f32_16x16x32_bf16 v[80:83], v[176:179], v[200:203], v[80:83]
	v_mfma_f32_16x16x32_bf16 v[68:71], v[168:171], v[208:211], v[68:71]
	v_mfma_f32_16x16x32_bf16 v[64:67], v[176:179], v[208:211], v[64:67]
	v_mfma_f32_16x16x32_bf16 v[116:119], v[172:175], v[188:191], v[116:119]
	v_mfma_f32_16x16x32_bf16 v[112:115], v[180:183], v[188:191], v[112:115]
	v_mfma_f32_16x16x32_bf16 v[100:103], v[172:175], v[196:199], v[100:103]
	v_mfma_f32_16x16x32_bf16 v[96:99], v[180:183], v[196:199], v[96:99]
	v_mfma_f32_16x16x32_bf16 v[84:87], v[172:175], v[204:207], v[84:87]
	v_mfma_f32_16x16x32_bf16 v[80:83], v[180:183], v[204:207], v[80:83]
	v_mfma_f32_16x16x32_bf16 v[68:71], v[172:175], v[212:215], v[68:71]
	v_mfma_f32_16x16x32_bf16 v[64:67], v[180:183], v[212:215], v[64:67]
	s_setprio 0
	s_barrier
	s_add_i32 s4, s44, s47
	v_lshl_add_u64 v[164:165], s[34:35], 0, v[130:131]
	s_mov_b32 m0, s4
	ds_read_b128 v[184:187], v151 offset:16384
	ds_read_b128 v[188:191], v151 offset:17408
	ds_read_b128 v[192:195], v151 offset:18432
	ds_read_b128 v[196:199], v151 offset:19456
	ds_read_b128 v[200:203], v151 offset:20480
	ds_read_b128 v[204:207], v151 offset:21504
	ds_read_b128 v[208:211], v151 offset:22528
	ds_read_b128 v[212:215], v151 offset:23552
	global_load_lds_dwordx4 v[164:165], off
	s_add_i32 m0, s4, 0x2000
	s_add_u32 s58, s34, 0x80000
	v_lshl_add_u64 v[216:217], s[34:35], 0, v[134:135]
	s_addc_u32 s59, s35, 0
	s_add_i32 s4, s45, s47
	global_load_lds_dwordx4 v[216:217], off
	v_lshl_add_u64 v[218:219], s[58:59], 0, v[130:131]
	s_mov_b32 m0, s4
	v_lshl_add_u64 v[220:221], s[36:37], 0, v[132:133]
	global_load_lds_dwordx4 v[218:219], off
	v_lshl_add_u64 v[218:219], s[58:59], 0, v[134:135]
	s_add_i32 m0, s4, 0x2000
	s_nop 0
	global_load_lds_dwordx4 v[218:219], off
	v_lshl_add_u64 v[218:219], s[36:37], 0, v[128:129]
	s_mov_b32 m0, s25
	s_nop 0
	global_load_lds_dwordx4 v[218:219], off
	s_mov_b32 m0, s33
	s_nop 0
	global_load_lds_dwordx4 v[220:221], off
	s_waitcnt vmcnt(8)
	s_waitcnt lgkmcnt(0)
	s_barrier
; #define PG8_STAGE(bufoff, gbase, voff) do { _Pragma("unroll") for (int _i = 0; _i < 2; ++_i) \
;         __builtin_amdgcn_global_load_lds((const unsigned*)((const char*)(gbase) + (voff)[_i]), (PG8_LAS unsigned*)(lds + (bufoff) + ldsw + _i * 8192), 16, 0, 0); } while (0)
; #define PG8_LDA(dst, b, h) do { _Pragma("unroll") for (int m = 0; m < 4; ++m) _Pragma("unroll") for (int k = 0; k < 2; ++k) dst[m][k] = *(const PG8_LAS bf16x8*)(lds + PG8_SA(b, h) + aoff + m * 2048 + k * 1024); } while (0)
; #define PG8_LDB(dst, b, h) do { _Pragma("unroll") for (int n = 0; n < 2; ++n) _Pragma("unroll") for (int k = 0; k < 2; ++k) dst[n][k] = *(const PG8_LAS bf16x8*)(lds + PG8_SB(b, h) + boff + n * 2048 + k * 1024); } while (0)
; #define PG8_MMA(ai, bj, At, Bt) do { __builtin_amdgcn_s_setprio(1); _Pragma("unroll") for (int m = 0; m < 4; ++m) _Pragma("unroll") for (int n = 0; n < 2; ++n) _Pragma("unroll") for (int k = 0; k < 2; ++k) \
;         acc[ai][bj][m][n] = __builtin_amdgcn_mfma_f32_16x16x32_bf16(Bt[n][k], At[m][k], acc[ai][bj][m][n], 0, 0, 0); __builtin_amdgcn_s_setprio(0); } while (0)
; #define PG8_WAIT_V(n) asm volatile("s_waitcnt vmcnt(" #n ")" ::: "memory")
; #define PG8_WAIT_L(n) asm volatile("s_waitcnt lgkmcnt(" #n ")" ::: "memory")
; #define PG8_BAR __builtin_amdgcn_s_barrier()
; #define PG8_SCHED __builtin_amdgcn_sched_barrier(0)
; template <class Epi, class Sched, bool ALIGN_EPI = false, bool SP2 = false>
; __device__ __forceinline__ void gemm_phase(PG8_LAS unsigned char* lds, const Gemm g, const Sched& S, const Epi& E) {
;     ...
;             PG8_WAIT_V(8); PG8_WAIT_L(0); PG8_BAR; PG8_MMA(1, 0, At, B0); PG8_MMA(1, 1, At, B1); PG8_BAR; PG8_SCHED;
;             PG8_LDB(B0, 1, 0); PG8_LDB(B1, 1, 1); PG8_SCHED; PG8_LDA(At, 1, 0); PG8_STAGE(PG8_SA(0, 1), a2 + hstepA, voffA);
;             PG8_WAIT_V(8); PG8_WAIT_L(0); PG8_BAR; PG8_MMA(0, 0, At, B0); PG8_MMA(0, 1, At, B1); PG8_BAR; PG8_SCHED;
	s_setprio 1
	v_mfma_f32_16x16x32_bf16 v[60:63], v[144:147], v[184:187], v[60:63]
	v_mfma_f32_16x16x32_bf16 v[56:59], v[156:159], v[184:187], v[56:59]
	v_mfma_f32_16x16x32_bf16 v[44:47], v[144:147], v[192:195], v[44:47]
	v_mfma_f32_16x16x32_bf16 v[40:43], v[156:159], v[192:195], v[40:43]
	v_mfma_f32_16x16x32_bf16 v[28:31], v[144:147], v[200:203], v[28:31]
	v_mfma_f32_16x16x32_bf16 v[24:27], v[156:159], v[200:203], v[24:27]
	v_mfma_f32_16x16x32_bf16 v[12:15], v[144:147], v[208:211], v[12:15]
	v_mfma_f32_16x16x32_bf16 v[8:11], v[156:159], v[208:211], v[8:11]
	v_mfma_f32_16x16x32_bf16 v[60:63], v[152:155], v[188:191], v[60:63]
	v_mfma_f32_16x16x32_bf16 v[56:59], v[160:163], v[188:191], v[56:59]
	v_mfma_f32_16x16x32_bf16 v[44:47], v[152:155], v[196:199], v[44:47]
	v_mfma_f32_16x16x32_bf16 v[40:43], v[160:163], v[196:199], v[40:43]
	v_mfma_f32_16x16x32_bf16 v[28:31], v[152:155], v[204:207], v[28:31]
	v_mfma_f32_16x16x32_bf16 v[24:27], v[160:163], v[204:207], v[24:27]
	v_mfma_f32_16x16x32_bf16 v[12:15], v[152:155], v[212:215], v[12:15]
	v_mfma_f32_16x16x32_bf16 v[8:11], v[160:163], v[212:215], v[8:11]
	v_mfma_f32_16x16x32_bf16 v[52:55], v[168:171], v[184:187], v[52:55]
	v_mfma_f32_16x16x32_bf16 v[48:51], v[176:179], v[184:187], v[48:51]
	v_mfma_f32_16x16x32_bf16 v[36:39], v[168:171], v[192:195], v[36:39]
	v_mfma_f32_16x16x32_bf16 v[32:35], v[176:179], v[192:195], v[32:35]
	v_mfma_f32_16x16x32_bf16 v[20:23], v[168:171], v[200:203], v[20:23]
	v_mfma_f32_16x16x32_bf16 v[16:19], v[176:179], v[200:203], v[16:19]
	v_mfma_f32_16x16x32_bf16 v[4:7], v[168:171], v[208:211], v[4:7]
	v_mfma_f32_16x16x32_bf16 v[0:3], v[176:179], v[208:211], v[0:3]
	v_mfma_f32_16x16x32_bf16 v[52:55], v[172:175], v[188:191], v[52:55]
	v_mfma_f32_16x16x32_bf16 v[48:51], v[180:183], v[188:191], v[48:51]
	v_mfma_f32_16x16x32_bf16 v[36:39], v[172:175], v[196:199], v[36:39]
	v_mfma_f32_16x16x32_bf16 v[32:35], v[180:183], v[196:199], v[32:35]
	v_mfma_f32_16x16x32_bf16 v[20:23], v[172:175], v[204:207], v[20:23]
	v_mfma_f32_16x16x32_bf16 v[16:19], v[180:183], v[204:207], v[16:19]
	v_mfma_f32_16x16x32_bf16 v[4:7], v[172:175], v[212:215], v[4:7]
	v_mfma_f32_16x16x32_bf16 v[0:3], v[180:183], v[212:215], v[0:3]
	s_setprio 0
	s_barrier
	s_add_i32 s4, 0, 0x18000
	s_add_i32 s5, 0, 0x1c000
	v_add_u32_e32 v160, s4, v148
	v_add_u32_e32 v166, s5, v148
	ds_read_b128 v[144:147], v160
	ds_read_b128 v[152:155], v160 offset:1024
	ds_read_b128 v[156:159], v160 offset:2048
	ds_read_b128 v[160:163], v160 offset:3072
	ds_read_b128 v[168:171], v166
	ds_read_b128 v[172:175], v166 offset:1024
	ds_read_b128 v[176:179], v166 offset:2048
	ds_read_b128 v[180:183], v166 offset:3072
	s_add_u32 s36, s36, 0x80000
	s_addc_u32 s37, s37, 0
	s_mov_b32 m0, s38
	v_lshl_add_u64 v[222:223], s[36:37], 0, v[128:129]
	ds_read_b128 v[184:187], v151 offset:32768
	ds_read_b128 v[188:191], v151 offset:33792
	ds_read_b128 v[192:195], v151 offset:34816
	ds_read_b128 v[196:199], v151 offset:35840
	ds_read_b128 v[200:203], v151 offset:36864
	ds_read_b128 v[204:207], v151 offset:37888
	ds_read_b128 v[208:211], v151 offset:38912
	ds_read_b128 v[212:215], v151 offset:39936
	global_load_lds_dwordx4 v[222:223], off
	v_lshl_add_u64 v[222:223], s[36:37], 0, v[132:133]
	s_mov_b32 m0, s39
	s_nop 0
	global_load_lds_dwordx4 v[222:223], off
	s_waitcnt vmcnt(8)
	s_waitcnt lgkmcnt(0)
	s_barrier
	s_setprio 1
	v_mfma_f32_16x16x32_bf16 v[124:127], v[144:147], v[184:187], v[124:127]
	v_mfma_f32_16x16x32_bf16 v[120:123], v[156:159], v[184:187], v[120:123]
	v_mfma_f32_16x16x32_bf16 v[108:111], v[144:147], v[192:195], v[108:111]
	v_mfma_f32_16x16x32_bf16 v[104:107], v[156:159], v[192:195], v[104:107]
	v_mfma_f32_16x16x32_bf16 v[92:95], v[144:147], v[200:203], v[92:95]
	v_mfma_f32_16x16x32_bf16 v[88:91], v[156:159], v[200:203], v[88:91]
	v_mfma_f32_16x16x32_bf16 v[76:79], v[144:147], v[208:211], v[76:79]
	v_mfma_f32_16x16x32_bf16 v[72:75], v[156:159], v[208:211], v[72:75]
	v_mfma_f32_16x16x32_bf16 v[124:127], v[152:155], v[188:191], v[124:127]
	v_mfma_f32_16x16x32_bf16 v[120:123], v[160:163], v[188:191], v[120:123]
	v_mfma_f32_16x16x32_bf16 v[108:111], v[152:155], v[196:199], v[108:111]
	v_mfma_f32_16x16x32_bf16 v[104:107], v[160:163], v[196:199], v[104:107]
	v_mfma_f32_16x16x32_bf16 v[92:95], v[152:155], v[204:207], v[92:95]
	v_mfma_f32_16x16x32_bf16 v[88:91], v[160:163], v[204:207], v[88:91]
	v_mfma_f32_16x16x32_bf16 v[76:79], v[152:155], v[212:215], v[76:79]
	v_mfma_f32_16x16x32_bf16 v[72:75], v[160:163], v[212:215], v[72:75]
	v_mfma_f32_16x16x32_bf16 v[116:119], v[168:171], v[184:187], v[116:119]
	v_mfma_f32_16x16x32_bf16 v[112:115], v[176:179], v[184:187], v[112:115]
	v_mfma_f32_16x16x32_bf16 v[100:103], v[168:171], v[192:195], v[100:103]
	v_mfma_f32_16x16x32_bf16 v[96:99], v[176:179], v[192:195], v[96:99]
	v_mfma_f32_16x16x32_bf16 v[84:87], v[168:171], v[200:203], v[84:87]
	v_mfma_f32_16x16x32_bf16 v[80:83], v[176:179], v[200:203], v[80:83]
	v_mfma_f32_16x16x32_bf16 v[68:71], v[168:171], v[208:211], v[68:71]
	v_mfma_f32_16x16x32_bf16 v[64:67], v[176:179], v[208:211], v[64:67]
	v_mfma_f32_16x16x32_bf16 v[116:119], v[172:175], v[188:191], v[116:119]
	v_mfma_f32_16x16x32_bf16 v[112:115], v[180:183], v[188:191], v[112:115]
	v_mfma_f32_16x16x32_bf16 v[100:103], v[172:175], v[196:199], v[100:103]
	v_mfma_f32_16x16x32_bf16 v[96:99], v[180:183], v[196:199], v[96:99]
	v_mfma_f32_16x16x32_bf16 v[84:87], v[172:175], v[204:207], v[84:87]
	v_mfma_f32_16x16x32_bf16 v[80:83], v[180:183], v[204:207], v[80:83]
	v_mfma_f32_16x16x32_bf16 v[68:71], v[172:175], v[212:215], v[68:71]
	v_mfma_f32_16x16x32_bf16 v[64:67], v[180:183], v[212:215], v[64:67]
	s_setprio 0
	s_barrier
; #define PG8_STAGE(bufoff, gbase, voff) do { _Pragma("unroll") for (int _i = 0; _i < 2; ++_i) \
;         __builtin_amdgcn_global_load_lds((const unsigned*)((const char*)(gbase) + (voff)[_i]), (PG8_LAS unsigned*)(lds + (bufoff) + ldsw + _i * 8192), 16, 0, 0); } while (0)
; #define PG8_LDA(dst, b, h) do { _Pragma("unroll") for (int m = 0; m < 4; ++m) _Pragma("unroll") for (int k = 0; k < 2; ++k) dst[m][k] = *(const PG8_LAS bf16x8*)(lds + PG8_SA(b, h) + aoff + m * 2048 + k * 1024); } while (0)
; #define PG8_LDB(dst, b, h) do { _Pragma("unroll") for (int n = 0; n < 2; ++n) _Pragma("unroll") for (int k = 0; k < 2; ++k) dst[n][k] = *(const PG8_LAS bf16x8*)(lds + PG8_SB(b, h) + boff + n * 2048 + k * 1024); } while (0)
; #define PG8_MMA(ai, bj, At, Bt) do { __builtin_amdgcn_s_setprio(1); _Pragma("unroll") for (int m = 0; m < 4; ++m) _Pragma("unroll") for (int n = 0; n < 2; ++n) _Pragma("unroll") for (int k = 0; k < 2; ++k) \
;         acc[ai][bj][m][n] = __builtin_amdgcn_mfma_f32_16x16x32_bf16(Bt[n][k], At[m][k], acc[ai][bj][m][n], 0, 0, 0); __builtin_amdgcn_s_setprio(0); } while (0)
; #define PG8_WAIT_V(n) asm volatile("s_waitcnt vmcnt(" #n ")" ::: "memory")
; template <class Epi, class Sched, bool ALIGN_EPI = false, bool SP2 = false>
; __device__ __forceinline__ void gemm_phase(PG8_LAS unsigned char* lds, const Gemm g, const Sched& S, const Epi& E) {
;     ...
;             PG8_LDB(B0, 0, 0); PG8_LDB(B1, 0, 1); PG8_SCHED; PG8_LDA(At, 0, 0); PG8_STAGE(PG8_SA(1, 1), a1 + hstepA, voffA);
;             PG8_WAIT_V(8); PG8_WAIT_L(0); PG8_BAR; PG8_MMA(0, 0, At, B0); PG8_MMA(0, 1, At, B1); PG8_BAR; PG8_SCHED;
;             PG8_LDA(At, 0, 1); PG8_STAGE(PG8_SB(0, 0), b2, voffB); PG8_STAGE(PG8_SB(0, 1), b2 + hstepB, voffB); PG8_STAGE(PG8_SA(0, 0), a2, voffA);
;             PG8_WAIT_V(8); PG8_WAIT_L(0); PG8_BAR; PG8_MMA(1, 0, At, B0); PG8_MMA(1, 1, At, B1); PG8_BAR; PG8_SCHED;
;             PG8_LDB(B0, 1, 0); PG8_LDB(B1, 1, 1); PG8_SCHED; PG8_LDA(At, 1, 0); PG8_STAGE(PG8_SA(0, 1), a2 + hstepA, voffA);
;             PG8_WAIT_V(8); PG8_WAIT_L(0); PG8_BAR; PG8_MMA(0, 0, At, B0); PG8_MMA(0, 1, At, B1); PG8_BAR; PG8_SCHED;
;             PG8_LDA(At, 1, 1); PG8_STAGE(PG8_SB(1, 0), b3, voffB); PG8_STAGE(PG8_SB(1, 1), b3 + hstepB, voffB); PG8_STAGE(PG8_SA(1, 0), a3, voffA);
;             PG8_WAIT_V(8); PG8_WAIT_L(0); PG8_BAR; PG8_MMA(1, 0, At, B0); PG8_MMA(1, 1, At, B1); PG8_BAR; PG8_SCHED;
	s_add_i32 s4, s4, s47
	v_lshl_add_u64 v[164:165], v[164:165], 0, s[16:17]
	s_mov_b32 m0, s4
	ds_read_b128 v[184:187], v151 offset:49152
	ds_read_b128 v[188:191], v151 offset:50176
	ds_read_b128 v[192:195], v151 offset:51200
	ds_read_b128 v[196:199], v151 offset:52224
	ds_read_b128 v[200:203], v151 offset:53248
	ds_read_b128 v[204:207], v151 offset:54272
	ds_read_b128 v[208:211], v151 offset:55296
	ds_read_b128 v[212:215], v151 offset:56320
	global_load_lds_dwordx4 v[164:165], off
	s_add_i32 m0, s4, 0x2000
	s_add_u32 s34, s34, 0x80080
	v_lshl_add_u64 v[164:165], v[216:217], 0, s[16:17]
	s_addc_u32 s35, s35, 0
	s_add_i32 s4, s5, s47
	global_load_lds_dwordx4 v[164:165], off
	v_lshl_add_u64 v[164:165], s[34:35], 0, v[130:131]
	s_mov_b32 m0, s4
	s_nop 0
	global_load_lds_dwordx4 v[164:165], off
	v_lshl_add_u64 v[164:165], s[34:35], 0, v[134:135]
	s_add_i32 m0, s4, 0x2000
	s_nop 0
	global_load_lds_dwordx4 v[164:165], off
	v_lshl_add_u64 v[164:165], v[218:219], 0, s[16:17]
	s_mov_b32 m0, s40
	s_nop 0
	global_load_lds_dwordx4 v[164:165], off
	v_lshl_add_u64 v[164:165], v[220:221], 0, s[16:17]
	s_mov_b32 m0, s41
	s_nop 0
	global_load_lds_dwordx4 v[164:165], off
	s_waitcnt vmcnt(8)
	s_waitcnt lgkmcnt(0)
	s_barrier
	s_setprio 1
	v_mfma_f32_16x16x32_bf16 v[60:63], v[144:147], v[184:187], v[60:63]
	v_mfma_f32_16x16x32_bf16 v[56:59], v[156:159], v[184:187], v[56:59]
	v_mfma_f32_16x16x32_bf16 v[44:47], v[144:147], v[192:195], v[44:47]
	v_mfma_f32_16x16x32_bf16 v[40:43], v[156:159], v[192:195], v[40:43]
	v_mfma_f32_16x16x32_bf16 v[28:31], v[144:147], v[200:203], v[28:31]
	v_mfma_f32_16x16x32_bf16 v[24:27], v[156:159], v[200:203], v[24:27]
	v_mfma_f32_16x16x32_bf16 v[12:15], v[144:147], v[208:211], v[12:15]
	v_mfma_f32_16x16x32_bf16 v[8:11], v[156:159], v[208:211], v[8:11]
	v_mfma_f32_16x16x32_bf16 v[60:63], v[152:155], v[188:191], v[60:63]
	v_mfma_f32_16x16x32_bf16 v[56:59], v[160:163], v[188:191], v[56:59]
	v_mfma_f32_16x16x32_bf16 v[44:47], v[152:155], v[196:199], v[44:47]
	v_mfma_f32_16x16x32_bf16 v[40:43], v[160:163], v[196:199], v[40:43]
	v_mfma_f32_16x16x32_bf16 v[28:31], v[152:155], v[204:207], v[28:31]
	v_mfma_f32_16x16x32_bf16 v[24:27], v[160:163], v[204:207], v[24:27]
	v_mfma_f32_16x16x32_bf16 v[12:15], v[152:155], v[212:215], v[12:15]
	v_mfma_f32_16x16x32_bf16 v[8:11], v[160:163], v[212:215], v[8:11]
	v_mfma_f32_16x16x32_bf16 v[52:55], v[168:171], v[184:187], v[52:55]
	v_mfma_f32_16x16x32_bf16 v[48:51], v[176:179], v[184:187], v[48:51]
	v_mfma_f32_16x16x32_bf16 v[36:39], v[168:171], v[192:195], v[36:39]
	v_mfma_f32_16x16x32_bf16 v[32:35], v[176:179], v[192:195], v[32:35]
	v_mfma_f32_16x16x32_bf16 v[20:23], v[168:171], v[200:203], v[20:23]
	v_mfma_f32_16x16x32_bf16 v[16:19], v[176:179], v[200:203], v[16:19]
	v_mfma_f32_16x16x32_bf16 v[4:7], v[168:171], v[208:211], v[4:7]
	v_mfma_f32_16x16x32_bf16 v[0:3], v[176:179], v[208:211], v[0:3]
	v_mfma_f32_16x16x32_bf16 v[52:55], v[172:175], v[188:191], v[52:55]
	v_mfma_f32_16x16x32_bf16 v[48:51], v[180:183], v[188:191], v[48:51]
	v_mfma_f32_16x16x32_bf16 v[36:39], v[172:175], v[196:199], v[36:39]
	v_mfma_f32_16x16x32_bf16 v[32:35], v[180:183], v[196:199], v[32:35]
	v_mfma_f32_16x16x32_bf16 v[20:23], v[172:175], v[204:207], v[20:23]
	v_mfma_f32_16x16x32_bf16 v[16:19], v[180:183], v[204:207], v[16:19]
	v_mfma_f32_16x16x32_bf16 v[4:7], v[172:175], v[212:215], v[4:7]
	v_mfma_f32_16x16x32_bf16 v[0:3], v[180:183], v[212:215], v[0:3]
	s_setprio 0
	s_barrier
	s_add_i32 s56, s56, 2
	s_add_u32 s30, s30, 0x100
	s_addc_u32 s31, s31, 0
	s_add_u32 s54, s54, 0x100
	s_addc_u32 s55, s55, 0
	s_cmp_gt_u32 s56, 29
	s_cbranch_scc0 .LBB0_660
	s_and_b64 vcc, exec, s[48:49]
	s_cbranch_vccz .LBB0_663
	s_barrier

; #define PG8_STAGE(bufoff, gbase, voff) do { _Pragma("unroll") for (int _i = 0; _i < 2; ++_i) \
;         __builtin_amdgcn_global_load_lds((const unsigned*)((const char*)(gbase) + (voff)[_i]), (PG8_LAS unsigned*)(lds + (bufoff) + ldsw + _i * 8192), 16, 0, 0); } while (0)
; #define PG8_LDA(dst, b, h) do { _Pragma("unroll") for (int m = 0; m < 4; ++m) _Pragma("unroll") for (int k = 0; k < 2; ++k) dst[m][k] = *(const PG8_LAS bf16x8*)(lds + PG8_SA(b, h) + aoff + m * 2048 + k * 1024); } while (0)
; #define PG8_LDB(dst, b, h) do { _Pragma("unroll") for (int n = 0; n < 2; ++n) _Pragma("unroll") for (int k = 0; k < 2; ++k) dst[n][k] = *(const PG8_LAS bf16x8*)(lds + PG8_SB(b, h) + boff + n * 2048 + k * 1024); } while (0)
; #define PG8_MMA(ai, bj, At, Bt) do { __builtin_amdgcn_s_setprio(1); _Pragma("unroll") for (int m = 0; m < 4; ++m) _Pragma("unroll") for (int n = 0; n < 2; ++n) _Pragma("unroll") for (int k = 0; k < 2; ++k) \
;         acc[ai][bj][m][n] = __builtin_amdgcn_mfma_f32_16x16x32_bf16(Bt[n][k], At[m][k], acc[ai][bj][m][n], 0, 0, 0); __builtin_amdgcn_s_setprio(0); } while (0)
; #define PG8_WAIT_V(n) asm volatile("s_waitcnt vmcnt(" #n ")" ::: "memory")
; #define PG8_WAIT_L(n) asm volatile("s_waitcnt lgkmcnt(" #n ")" ::: "memory")
; #define PG8_BAR __builtin_amdgcn_s_barrier()
; #define PG8_SCHED __builtin_amdgcn_sched_barrier(0)
; template <class Epi, class Sched, bool ALIGN_EPI = false, bool SP2 = false>
; __device__ __forceinline__ void gemm_phase(PG8_LAS unsigned char* lds, const Gemm g, const Sched& S, const Epi& E) {
;     ...
;             const char* a1 = cA + (size_t)(t + 1) * kstep;
;             const char* a2 = last ? nA : cA + (size_t)(t + 2) * kstep; const char* b2 = last ? nB : cB + (size_t)(t + 2) * kstep;
;             const char* a3 = a2 + kstep; const char* b3 = b2 + kstep;
;             if (last && has_next) S.a_ready(nxt);
;             if constexpr (SP2) {
;             PG8_LDB(B0, 0, 0); PG8_LDB(B1, 0, 1); PG8_SCHED; PG8_LDA(At, 0, 0); PG8_STAGE(PG8_SA(1, 1), a1 + hstepA, voffA);
;             PG8_WAIT_V(8); PG8_WAIT_L(0); PG8_BAR; PG8_MMA(0, 0, At, B0); PG8_MMA(0, 1, At, B1); PG8_BAR; PG8_SCHED;
;             PG8_LDA(At, 0, 1); PG8_STAGE(PG8_SB(0, 0), b2, voffB); PG8_STAGE(PG8_SB(0, 1), b2 + hstepB, voffB); PG8_STAGE(PG8_SA(0, 0), a2, voffA);
.LBB0_736:
	ds_read_b128 v[144:147], v149
	ds_read_b128 v[154:157], v149 offset:1024
	ds_read_b128 v[158:161], v149 offset:2048
	ds_read_b128 v[162:165], v149 offset:3072
	ds_read_b128 v[168:171], v150
	ds_read_b128 v[172:175], v150 offset:1024
	ds_read_b128 v[176:179], v150 offset:2048
	ds_read_b128 v[180:183], v150 offset:3072
	s_add_u32 s4, s28, 0xfff80080
	s_addc_u32 s5, s29, -1
	s_cmp_eq_u32 s60, 28
	s_cselect_b32 s35, s19, s5
	s_cselect_b32 s34, s56, s4
	s_cselect_b32 s31, s17, s59
	s_cselect_b32 s30, s57, s58
	v_lshl_add_u64 v[216:217], s[28:29], 0, v[136:137]
	s_add_i32 m0, s27, 0xc000
	ds_read_b128 v[184:187], v151
	ds_read_b128 v[188:191], v151 offset:1024
	ds_read_b128 v[192:195], v151 offset:2048
	ds_read_b128 v[196:199], v151 offset:3072
	ds_read_b128 v[200:203], v151 offset:4096
	ds_read_b128 v[204:207], v151 offset:5120
	ds_read_b128 v[208:211], v151 offset:6144
	ds_read_b128 v[212:215], v151 offset:7168
	global_load_lds_dwordx4 v[216:217], off
	v_lshl_add_u64 v[216:217], s[28:29], 0, v[138:139]
	s_add_i32 m0, s27, 0xe000
	s_nop 0
	global_load_lds_dwordx4 v[216:217], off
	s_waitcnt vmcnt(8)
	s_waitcnt lgkmcnt(0)
	s_barrier
	s_setprio 1
	v_mfma_f32_16x16x32_bf16 v[116:119], v[144:147], v[184:187], v[116:119]
	v_mfma_f32_16x16x32_bf16 v[112:115], v[158:161], v[184:187], v[112:115]
	v_mfma_f32_16x16x32_bf16 v[100:103], v[144:147], v[192:195], v[100:103]
	v_mfma_f32_16x16x32_bf16 v[96:99], v[158:161], v[192:195], v[96:99]
	v_mfma_f32_16x16x32_bf16 v[84:87], v[144:147], v[200:203], v[84:87]
	v_mfma_f32_16x16x32_bf16 v[80:83], v[158:161], v[200:203], v[80:83]
	v_mfma_f32_16x16x32_bf16 v[68:71], v[144:147], v[208:211], v[68:71]
	v_mfma_f32_16x16x32_bf16 v[64:67], v[158:161], v[208:211], v[64:67]
	v_mfma_f32_16x16x32_bf16 v[116:119], v[154:157], v[188:191], v[116:119]
	v_mfma_f32_16x16x32_bf16 v[112:115], v[162:165], v[188:191], v[112:115]
	v_mfma_f32_16x16x32_bf16 v[100:103], v[154:157], v[196:199], v[100:103]
	v_mfma_f32_16x16x32_bf16 v[96:99], v[162:165], v[196:199], v[96:99]
	v_mfma_f32_16x16x32_bf16 v[84:87], v[154:157], v[204:207], v[84:87]
	v_mfma_f32_16x16x32_bf16 v[80:83], v[162:165], v[204:207], v[80:83]
	v_mfma_f32_16x16x32_bf16 v[68:71], v[154:157], v[212:215], v[68:71]
	v_mfma_f32_16x16x32_bf16 v[64:67], v[162:165], v[212:215], v[64:67]
	v_mfma_f32_16x16x32_bf16 v[124:127], v[168:171], v[184:187], v[124:127]
	v_mfma_f32_16x16x32_bf16 v[120:123], v[176:179], v[184:187], v[120:123]
	v_mfma_f32_16x16x32_bf16 v[108:111], v[168:171], v[192:195], v[108:111]
	v_mfma_f32_16x16x32_bf16 v[104:107], v[176:179], v[192:195], v[104:107]
	v_mfma_f32_16x16x32_bf16 v[92:95], v[168:171], v[200:203], v[92:95]
	v_mfma_f32_16x16x32_bf16 v[88:91], v[176:179], v[200:203], v[88:91]
	v_mfma_f32_16x16x32_bf16 v[76:79], v[168:171], v[208:211], v[76:79]
	v_mfma_f32_16x16x32_bf16 v[72:75], v[176:179], v[208:211], v[72:75]
	v_mfma_f32_16x16x32_bf16 v[124:127], v[172:175], v[188:191], v[124:127]
	v_mfma_f32_16x16x32_bf16 v[120:123], v[180:183], v[188:191], v[120:123]
	v_mfma_f32_16x16x32_bf16 v[108:111], v[172:175], v[196:199], v[108:111]
	v_mfma_f32_16x16x32_bf16 v[104:107], v[180:183], v[196:199], v[104:107]
	v_mfma_f32_16x16x32_bf16 v[92:95], v[172:175], v[204:207], v[92:95]
	v_mfma_f32_16x16x32_bf16 v[88:91], v[180:183], v[204:207], v[88:91]
	v_mfma_f32_16x16x32_bf16 v[76:79], v[172:175], v[212:215], v[76:79]
	v_mfma_f32_16x16x32_bf16 v[72:75], v[180:183], v[212:215], v[72:75]
	s_setprio 0
	s_barrier
	s_add_i32 s4, s41, s47
	v_lshl_add_u64 v[216:217], s[30:31], 0, v[132:133]
	s_mov_b32 m0, s4
	ds_read_b128 v[184:187], v151 offset:16384
	ds_read_b128 v[188:191], v151 offset:17408
	ds_read_b128 v[192:195], v151 offset:18432
	ds_read_b128 v[196:199], v151 offset:19456
	ds_read_b128 v[200:203], v151 offset:20480
	ds_read_b128 v[204:207], v151 offset:21504
	ds_read_b128 v[208:211], v151 offset:22528
	ds_read_b128 v[212:215], v151 offset:23552
	global_load_lds_dwordx4 v[216:217], off
	s_add_i32 m0, s4, 0x2000
	s_add_u32 s4, s30, 0x80000
	v_lshl_add_u64 v[218:219], s[30:31], 0, v[128:129]
	s_addc_u32 s5, s31, 0
	s_add_i32 s61, s44, s47
	global_load_lds_dwordx4 v[218:219], off
	v_lshl_add_u64 v[220:221], s[4:5], 0, v[132:133]
	s_mov_b32 m0, s61
	v_lshl_add_u64 v[222:223], s[34:35], 0, v[130:131]
	global_load_lds_dwordx4 v[220:221], off
	v_lshl_add_u64 v[220:221], s[4:5], 0, v[128:129]
	s_add_i32 m0, s61, 0x2000
	s_nop 0
	global_load_lds_dwordx4 v[220:221], off
	v_lshl_add_u64 v[220:221], s[34:35], 0, v[134:135]
	s_mov_b32 m0, s27
	s_nop 0
	global_load_lds_dwordx4 v[220:221], off
	s_mov_b32 m0, s33
	s_nop 0
	global_load_lds_dwordx4 v[222:223], off
	s_waitcnt vmcnt(8)
	s_waitcnt lgkmcnt(0)
	s_barrier
; #define PG8_STAGE(bufoff, gbase, voff) do { _Pragma("unroll") for (int _i = 0; _i < 2; ++_i) \
;         __builtin_amdgcn_global_load_lds((const unsigned*)((const char*)(gbase) + (voff)[_i]), (PG8_LAS unsigned*)(lds + (bufoff) + ldsw + _i * 8192), 16, 0, 0); } while (0)
; #define PG8_LDA(dst, b, h) do { _Pragma("unroll") for (int m = 0; m < 4; ++m) _Pragma("unroll") for (int k = 0; k < 2; ++k) dst[m][k] = *(const PG8_LAS bf16x8*)(lds + PG8_SA(b, h) + aoff + m * 2048 + k * 1024); } while (0)
; #define PG8_LDB(dst, b, h) do { _Pragma("unroll") for (int n = 0; n < 2; ++n) _Pragma("unroll") for (int k = 0; k < 2; ++k) dst[n][k] = *(const PG8_LAS bf16x8*)(lds + PG8_SB(b, h) + boff + n * 2048 + k * 1024); } while (0)
; #define PG8_MMA(ai, bj, At, Bt) do { __builtin_amdgcn_s_setprio(1); _Pragma("unroll") for (int m = 0; m < 4; ++m) _Pragma("unroll") for (int n = 0; n < 2; ++n) _Pragma("unroll") for (int k = 0; k < 2; ++k) \
;         acc[ai][bj][m][n] = __builtin_amdgcn_mfma_f32_16x16x32_bf16(Bt[n][k], At[m][k], acc[ai][bj][m][n], 0, 0, 0); __builtin_amdgcn_s_setprio(0); } while (0)
; #define PG8_WAIT_V(n) asm volatile("s_waitcnt vmcnt(" #n ")" ::: "memory")
; #define PG8_WAIT_L(n) asm volatile("s_waitcnt lgkmcnt(" #n ")" ::: "memory")
; #define PG8_BAR __builtin_amdgcn_s_barrier()
; #define PG8_SCHED __builtin_amdgcn_sched_barrier(0)
; template <class Epi, class Sched, bool ALIGN_EPI = false, bool SP2 = false>
; __device__ __forceinline__ void gemm_phase(PG8_LAS unsigned char* lds, const Gemm g, const Sched& S, const Epi& E) {
;     ...
;             PG8_WAIT_V(8); PG8_WAIT_L(0); PG8_BAR; PG8_MMA(1, 0, At, B0); PG8_MMA(1, 1, At, B1); PG8_BAR; PG8_SCHED;
;             PG8_LDB(B0, 1, 0); PG8_LDB(B1, 1, 1); PG8_SCHED; PG8_LDA(At, 1, 0); PG8_STAGE(PG8_SA(0, 1), a2 + hstepA, voffA);
;             PG8_WAIT_V(8); PG8_WAIT_L(0); PG8_BAR; PG8_MMA(0, 0, At, B0); PG8_MMA(0, 1, At, B1); PG8_BAR; PG8_SCHED;
	s_setprio 1
	v_mfma_f32_16x16x32_bf16 v[52:55], v[144:147], v[184:187], v[52:55]
	v_mfma_f32_16x16x32_bf16 v[48:51], v[158:161], v[184:187], v[48:51]
	v_mfma_f32_16x16x32_bf16 v[36:39], v[144:147], v[192:195], v[36:39]
	v_mfma_f32_16x16x32_bf16 v[32:35], v[158:161], v[192:195], v[32:35]
	v_mfma_f32_16x16x32_bf16 v[20:23], v[144:147], v[200:203], v[20:23]
	v_mfma_f32_16x16x32_bf16 v[16:19], v[158:161], v[200:203], v[16:19]
	v_mfma_f32_16x16x32_bf16 v[8:11], v[144:147], v[208:211], v[8:11]
	v_mfma_f32_16x16x32_bf16 v[4:7], v[158:161], v[208:211], v[4:7]
	v_mfma_f32_16x16x32_bf16 v[52:55], v[154:157], v[188:191], v[52:55]
	v_mfma_f32_16x16x32_bf16 v[48:51], v[162:165], v[188:191], v[48:51]
	v_mfma_f32_16x16x32_bf16 v[36:39], v[154:157], v[196:199], v[36:39]
	v_mfma_f32_16x16x32_bf16 v[32:35], v[162:165], v[196:199], v[32:35]
	v_mfma_f32_16x16x32_bf16 v[20:23], v[154:157], v[204:207], v[20:23]
	v_mfma_f32_16x16x32_bf16 v[16:19], v[162:165], v[204:207], v[16:19]
	v_mfma_f32_16x16x32_bf16 v[8:11], v[154:157], v[212:215], v[8:11]
	v_mfma_f32_16x16x32_bf16 v[4:7], v[162:165], v[212:215], v[4:7]
	v_mfma_f32_16x16x32_bf16 v[60:63], v[168:171], v[184:187], v[60:63]
	v_mfma_f32_16x16x32_bf16 v[56:59], v[176:179], v[184:187], v[56:59]
	v_mfma_f32_16x16x32_bf16 v[44:47], v[168:171], v[192:195], v[44:47]
	v_mfma_f32_16x16x32_bf16 v[40:43], v[176:179], v[192:195], v[40:43]
	v_mfma_f32_16x16x32_bf16 v[28:31], v[168:171], v[200:203], v[28:31]
	v_mfma_f32_16x16x32_bf16 v[24:27], v[176:179], v[200:203], v[24:27]
	v_mfma_f32_16x16x32_bf16 v[12:15], v[168:171], v[208:211], v[12:15]
	v_mfma_f32_16x16x32_bf16 v[0:3], v[176:179], v[208:211], v[0:3]
	v_mfma_f32_16x16x32_bf16 v[60:63], v[172:175], v[188:191], v[60:63]
	v_mfma_f32_16x16x32_bf16 v[56:59], v[180:183], v[188:191], v[56:59]
	v_mfma_f32_16x16x32_bf16 v[44:47], v[172:175], v[196:199], v[44:47]
	v_mfma_f32_16x16x32_bf16 v[40:43], v[180:183], v[196:199], v[40:43]
	v_mfma_f32_16x16x32_bf16 v[28:31], v[172:175], v[204:207], v[28:31]
	v_mfma_f32_16x16x32_bf16 v[24:27], v[180:183], v[204:207], v[24:27]
	v_mfma_f32_16x16x32_bf16 v[12:15], v[172:175], v[212:215], v[12:15]
	v_mfma_f32_16x16x32_bf16 v[0:3], v[180:183], v[212:215], v[0:3]
	s_setprio 0
	s_barrier
	s_add_i32 s61, 0, 0x18000
	v_add_u32_e32 v153, s61, v148
	s_add_i32 s62, 0, 0x1c000
	ds_read_b128 v[144:147], v153
	ds_read_b128 v[154:157], v153 offset:1024
	ds_read_b128 v[158:161], v153 offset:2048
	ds_read_b128 v[162:165], v153 offset:3072
	v_add_u32_e32 v153, s62, v148
	ds_read_b128 v[168:171], v153
	ds_read_b128 v[172:175], v153 offset:1024
	ds_read_b128 v[176:179], v153 offset:2048
	ds_read_b128 v[180:183], v153 offset:3072
	s_add_u32 s4, s34, 0x80000
	s_addc_u32 s5, s35, 0
	s_mov_b32 m0, s36
	v_lshl_add_u64 v[224:225], s[4:5], 0, v[134:135]
	ds_read_b128 v[184:187], v151 offset:32768
	ds_read_b128 v[188:191], v151 offset:33792
	ds_read_b128 v[192:195], v151 offset:34816
	ds_read_b128 v[196:199], v151 offset:35840
	ds_read_b128 v[200:203], v151 offset:36864
	ds_read_b128 v[204:207], v151 offset:37888
	ds_read_b128 v[208:211], v151 offset:38912
	ds_read_b128 v[212:215], v151 offset:39936
	global_load_lds_dwordx4 v[224:225], off
	v_lshl_add_u64 v[224:225], s[4:5], 0, v[130:131]
	s_mov_b32 m0, s37
	s_nop 0
	global_load_lds_dwordx4 v[224:225], off
	s_waitcnt vmcnt(8)
	s_waitcnt lgkmcnt(0)
	s_barrier
	s_setprio 1
	v_mfma_f32_16x16x32_bf16 v[116:119], v[144:147], v[184:187], v[116:119]
	v_mfma_f32_16x16x32_bf16 v[112:115], v[158:161], v[184:187], v[112:115]
	v_mfma_f32_16x16x32_bf16 v[100:103], v[144:147], v[192:195], v[100:103]
	v_mfma_f32_16x16x32_bf16 v[96:99], v[158:161], v[192:195], v[96:99]
	v_mfma_f32_16x16x32_bf16 v[84:87], v[144:147], v[200:203], v[84:87]
	v_mfma_f32_16x16x32_bf16 v[80:83], v[158:161], v[200:203], v[80:83]
	v_mfma_f32_16x16x32_bf16 v[68:71], v[144:147], v[208:211], v[68:71]
	v_mfma_f32_16x16x32_bf16 v[64:67], v[158:161], v[208:211], v[64:67]
	v_mfma_f32_16x16x32_bf16 v[116:119], v[154:157], v[188:191], v[116:119]
	v_mfma_f32_16x16x32_bf16 v[112:115], v[162:165], v[188:191], v[112:115]
	v_mfma_f32_16x16x32_bf16 v[100:103], v[154:157], v[196:199], v[100:103]
	v_mfma_f32_16x16x32_bf16 v[96:99], v[162:165], v[196:199], v[96:99]
	v_mfma_f32_16x16x32_bf16 v[84:87], v[154:157], v[204:207], v[84:87]
	v_mfma_f32_16x16x32_bf16 v[80:83], v[162:165], v[204:207], v[80:83]
	v_mfma_f32_16x16x32_bf16 v[68:71], v[154:157], v[212:215], v[68:71]
	v_mfma_f32_16x16x32_bf16 v[64:67], v[162:165], v[212:215], v[64:67]
	v_mfma_f32_16x16x32_bf16 v[124:127], v[168:171], v[184:187], v[124:127]
	v_mfma_f32_16x16x32_bf16 v[120:123], v[176:179], v[184:187], v[120:123]
	v_mfma_f32_16x16x32_bf16 v[108:111], v[168:171], v[192:195], v[108:111]
	v_mfma_f32_16x16x32_bf16 v[104:107], v[176:179], v[192:195], v[104:107]
	v_mfma_f32_16x16x32_bf16 v[92:95], v[168:171], v[200:203], v[92:95]
	v_mfma_f32_16x16x32_bf16 v[88:91], v[176:179], v[200:203], v[88:91]
	v_mfma_f32_16x16x32_bf16 v[76:79], v[168:171], v[208:211], v[76:79]
	v_mfma_f32_16x16x32_bf16 v[72:75], v[176:179], v[208:211], v[72:75]
	v_mfma_f32_16x16x32_bf16 v[124:127], v[172:175], v[188:191], v[124:127]
	v_mfma_f32_16x16x32_bf16 v[120:123], v[180:183], v[188:191], v[120:123]
	v_mfma_f32_16x16x32_bf16 v[108:111], v[172:175], v[196:199], v[108:111]
	v_mfma_f32_16x16x32_bf16 v[104:107], v[180:183], v[196:199], v[104:107]
	v_mfma_f32_16x16x32_bf16 v[92:95], v[172:175], v[204:207], v[92:95]
	v_mfma_f32_16x16x32_bf16 v[88:91], v[180:183], v[204:207], v[88:91]
	v_mfma_f32_16x16x32_bf16 v[76:79], v[172:175], v[212:215], v[76:79]
	v_mfma_f32_16x16x32_bf16 v[72:75], v[180:183], v[212:215], v[72:75]
	s_setprio 0
	s_barrier
; #define PG8_STAGE(bufoff, gbase, voff) do { _Pragma("unroll") for (int _i = 0; _i < 2; ++_i) \
;         __builtin_amdgcn_global_load_lds((const unsigned*)((const char*)(gbase) + (voff)[_i]), (PG8_LAS unsigned*)(lds + (bufoff) + ldsw + _i * 8192), 16, 0, 0); } while (0)
; #define PG8_LDA(dst, b, h) do { _Pragma("unroll") for (int m = 0; m < 4; ++m) _Pragma("unroll") for (int k = 0; k < 2; ++k) dst[m][k] = *(const PG8_LAS bf16x8*)(lds + PG8_SA(b, h) + aoff + m * 2048 + k * 1024); } while (0)
; #define PG8_LDB(dst, b, h) do { _Pragma("unroll") for (int n = 0; n < 2; ++n) _Pragma("unroll") for (int k = 0; k < 2; ++k) dst[n][k] = *(const PG8_LAS bf16x8*)(lds + PG8_SB(b, h) + boff + n * 2048 + k * 1024); } while (0)
; #define PG8_MMA(ai, bj, At, Bt) do { __builtin_amdgcn_s_setprio(1); _Pragma("unroll") for (int m = 0; m < 4; ++m) _Pragma("unroll") for (int n = 0; n < 2; ++n) _Pragma("unroll") for (int k = 0; k < 2; ++k) \
;         acc[ai][bj][m][n] = __builtin_amdgcn_mfma_f32_16x16x32_bf16(Bt[n][k], At[m][k], acc[ai][bj][m][n], 0, 0, 0); __builtin_amdgcn_s_setprio(0); } while (0)
; #define PG8_WAIT_V(n) asm volatile("s_waitcnt vmcnt(" #n ")" ::: "memory")
; template <class Epi, class Sched, bool ALIGN_EPI = false, bool SP2 = false>
; __device__ __forceinline__ void gemm_phase(PG8_LAS unsigned char* lds, const Gemm g, const Sched& S, const Epi& E) {
;     ...
;             PG8_LDB(B0, 0, 0); PG8_LDB(B1, 0, 1); PG8_SCHED; PG8_LDA(At, 0, 0); PG8_STAGE(PG8_SA(1, 1), a1 + hstepA, voffA);
;             PG8_WAIT_V(8); PG8_WAIT_L(0); PG8_BAR; PG8_MMA(0, 0, At, B0); PG8_MMA(0, 1, At, B1); PG8_BAR; PG8_SCHED;
;             PG8_LDA(At, 0, 1); PG8_STAGE(PG8_SB(0, 0), b2, voffB); PG8_STAGE(PG8_SB(0, 1), b2 + hstepB, voffB); PG8_STAGE(PG8_SA(0, 0), a2, voffA);
;             PG8_WAIT_V(8); PG8_WAIT_L(0); PG8_BAR; PG8_MMA(1, 0, At, B0); PG8_MMA(1, 1, At, B1); PG8_BAR; PG8_SCHED;
;             PG8_LDB(B0, 1, 0); PG8_LDB(B1, 1, 1); PG8_SCHED; PG8_LDA(At, 1, 0); PG8_STAGE(PG8_SA(0, 1), a2 + hstepA, voffA);
;             PG8_WAIT_V(8); PG8_WAIT_L(0); PG8_BAR; PG8_MMA(0, 0, At, B0); PG8_MMA(0, 1, At, B1); PG8_BAR; PG8_SCHED;
;             PG8_LDA(At, 1, 1); PG8_STAGE(PG8_SB(1, 0), b3, voffB); PG8_STAGE(PG8_SB(1, 1), b3 + hstepB, voffB); PG8_STAGE(PG8_SA(1, 0), a3, voffA);
;             PG8_WAIT_V(8); PG8_WAIT_L(0); PG8_BAR; PG8_MMA(1, 0, At, B0); PG8_MMA(1, 1, At, B1); PG8_BAR; PG8_SCHED;
	s_add_i32 s4, s61, s47
	v_lshl_add_u64 v[216:217], v[216:217], 0, s[14:15]
	s_mov_b32 m0, s4
	ds_read_b128 v[184:187], v151 offset:49152
	ds_read_b128 v[188:191], v151 offset:50176
	ds_read_b128 v[192:195], v151 offset:51200
	ds_read_b128 v[196:199], v151 offset:52224
	ds_read_b128 v[200:203], v151 offset:53248
	ds_read_b128 v[204:207], v151 offset:54272
	ds_read_b128 v[208:211], v151 offset:55296
	ds_read_b128 v[212:215], v151 offset:56320
	global_load_lds_dwordx4 v[216:217], off
	s_add_i32 m0, s4, 0x2000
	s_add_u32 s4, s30, 0x80080
	v_lshl_add_u64 v[216:217], v[218:219], 0, s[14:15]
	s_addc_u32 s5, s31, 0
	s_add_i32 s30, s62, s47
	global_load_lds_dwordx4 v[216:217], off
	v_lshl_add_u64 v[216:217], s[4:5], 0, v[132:133]
	s_mov_b32 m0, s30
	s_nop 0
	global_load_lds_dwordx4 v[216:217], off
	v_lshl_add_u64 v[216:217], s[4:5], 0, v[128:129]
	s_add_i32 m0, s30, 0x2000
	s_nop 0
	global_load_lds_dwordx4 v[216:217], off
	v_lshl_add_u64 v[216:217], v[220:221], 0, s[14:15]
	s_mov_b32 m0, s39
	s_nop 0
	global_load_lds_dwordx4 v[216:217], off
	v_lshl_add_u64 v[216:217], v[222:223], 0, s[14:15]
	s_mov_b32 m0, s40
	s_nop 0
	global_load_lds_dwordx4 v[216:217], off
	s_waitcnt vmcnt(8)
	s_waitcnt lgkmcnt(0)
	s_barrier
	s_setprio 1
	v_mfma_f32_16x16x32_bf16 v[52:55], v[144:147], v[184:187], v[52:55]
	v_mfma_f32_16x16x32_bf16 v[48:51], v[158:161], v[184:187], v[48:51]
	v_mfma_f32_16x16x32_bf16 v[36:39], v[144:147], v[192:195], v[36:39]
	v_mfma_f32_16x16x32_bf16 v[32:35], v[158:161], v[192:195], v[32:35]
	v_mfma_f32_16x16x32_bf16 v[20:23], v[144:147], v[200:203], v[20:23]
	v_mfma_f32_16x16x32_bf16 v[16:19], v[158:161], v[200:203], v[16:19]
	v_mfma_f32_16x16x32_bf16 v[8:11], v[144:147], v[208:211], v[8:11]
	v_mfma_f32_16x16x32_bf16 v[4:7], v[158:161], v[208:211], v[4:7]
	v_mfma_f32_16x16x32_bf16 v[52:55], v[154:157], v[188:191], v[52:55]
	v_mfma_f32_16x16x32_bf16 v[48:51], v[162:165], v[188:191], v[48:51]
	v_mfma_f32_16x16x32_bf16 v[36:39], v[154:157], v[196:199], v[36:39]
	v_mfma_f32_16x16x32_bf16 v[32:35], v[162:165], v[196:199], v[32:35]
	v_mfma_f32_16x16x32_bf16 v[20:23], v[154:157], v[204:207], v[20:23]
	v_mfma_f32_16x16x32_bf16 v[16:19], v[162:165], v[204:207], v[16:19]
	v_mfma_f32_16x16x32_bf16 v[8:11], v[154:157], v[212:215], v[8:11]
	v_mfma_f32_16x16x32_bf16 v[4:7], v[162:165], v[212:215], v[4:7]
	v_mfma_f32_16x16x32_bf16 v[60:63], v[168:171], v[184:187], v[60:63]
	v_mfma_f32_16x16x32_bf16 v[56:59], v[176:179], v[184:187], v[56:59]
	v_mfma_f32_16x16x32_bf16 v[44:47], v[168:171], v[192:195], v[44:47]
	v_mfma_f32_16x16x32_bf16 v[40:43], v[176:179], v[192:195], v[40:43]
	v_mfma_f32_16x16x32_bf16 v[28:31], v[168:171], v[200:203], v[28:31]
	v_mfma_f32_16x16x32_bf16 v[24:27], v[176:179], v[200:203], v[24:27]
	v_mfma_f32_16x16x32_bf16 v[12:15], v[168:171], v[208:211], v[12:15]
	v_mfma_f32_16x16x32_bf16 v[0:3], v[176:179], v[208:211], v[0:3]
	v_mfma_f32_16x16x32_bf16 v[60:63], v[172:175], v[188:191], v[60:63]
	v_mfma_f32_16x16x32_bf16 v[56:59], v[180:183], v[188:191], v[56:59]
	v_mfma_f32_16x16x32_bf16 v[44:47], v[172:175], v[196:199], v[44:47]
	v_mfma_f32_16x16x32_bf16 v[40:43], v[180:183], v[196:199], v[40:43]
	v_mfma_f32_16x16x32_bf16 v[28:31], v[172:175], v[204:207], v[28:31]
	v_mfma_f32_16x16x32_bf16 v[24:27], v[180:183], v[204:207], v[24:27]
	v_mfma_f32_16x16x32_bf16 v[12:15], v[172:175], v[212:215], v[12:15]
	v_mfma_f32_16x16x32_bf16 v[0:3], v[180:183], v[212:215], v[0:3]
	s_setprio 0
	s_barrier
	s_add_i32 s60, s60, 2
	s_add_u32 s28, s28, 0x100
	s_addc_u32 s29, s29, 0
	s_add_u32 s58, s58, 0x100
	s_addc_u32 s59, s59, 0
	s_cmp_gt_u32 s60, 29
	s_cbranch_scc0 .LBB0_736
	s_and_b64 vcc, exec, s[48:49]
	s_cbranch_vccz .LBB0_739
	s_barrier

; #define PG8_STAGE(bufoff, gbase, voff) do { _Pragma("unroll") for (int _i = 0; _i < 2; ++_i) \
;         __builtin_amdgcn_global_load_lds((const unsigned*)((const char*)(gbase) + (voff)[_i]), (PG8_LAS unsigned*)(lds + (bufoff) + ldsw + _i * 8192), 16, 0, 0); } while (0)
; #define PG8_LDA(dst, b, h) do { _Pragma("unroll") for (int m = 0; m < 4; ++m) _Pragma("unroll") for (int k = 0; k < 2; ++k) dst[m][k] = *(const PG8_LAS bf16x8*)(lds + PG8_SA(b, h) + aoff + m * 2048 + k * 1024); } while (0)
; #define PG8_LDB(dst, b, h) do { _Pragma("unroll") for (int n = 0; n < 2; ++n) _Pragma("unroll") for (int k = 0; k < 2; ++k) dst[n][k] = *(const PG8_LAS bf16x8*)(lds + PG8_SB(b, h) + boff + n * 2048 + k * 1024); } while (0)
; #define PG8_MMA(ai, bj, At, Bt) do { __builtin_amdgcn_s_setprio(1); _Pragma("unroll") for (int m = 0; m < 4; ++m) _Pragma("unroll") for (int n = 0; n < 2; ++n) _Pragma("unroll") for (int k = 0; k < 2; ++k) \
;         acc[ai][bj][m][n] = __builtin_amdgcn_mfma_f32_16x16x32_bf16(Bt[n][k], At[m][k], acc[ai][bj][m][n], 0, 0, 0); __builtin_amdgcn_s_setprio(0); } while (0)
; #define PG8_WAIT_V(n) asm volatile("s_waitcnt vmcnt(" #n ")" ::: "memory")
; #define PG8_WAIT_L(n) asm volatile("s_waitcnt lgkmcnt(" #n ")" ::: "memory")
; #define PG8_BAR __builtin_amdgcn_s_barrier()
; #define PG8_SCHED __builtin_amdgcn_sched_barrier(0)
; template <class Epi, class Sched, bool ALIGN_EPI = false, bool SP2 = false>
; __device__ __forceinline__ void gemm_phase(PG8_LAS unsigned char* lds, const Gemm g, const Sched& S, const Epi& E) {
;     ...
;             const char* a1 = cA + (size_t)(t + 1) * kstep;
;             const char* a2 = last ? nA : cA + (size_t)(t + 2) * kstep; const char* b2 = last ? nB : cB + (size_t)(t + 2) * kstep;
;             const char* a3 = a2 + kstep; const char* b3 = b2 + kstep;
;             if (last && has_next) S.a_ready(nxt);
;             if constexpr (SP2) {
;             PG8_LDB(B0, 0, 0); PG8_LDB(B1, 0, 1); PG8_SCHED; PG8_LDA(At, 0, 0); PG8_STAGE(PG8_SA(1, 1), a1 + hstepA, voffA);
;             PG8_WAIT_V(8); PG8_WAIT_L(0); PG8_BAR; PG8_MMA(0, 0, At, B0); PG8_MMA(0, 1, At, B1); PG8_BAR; PG8_SCHED;
;             PG8_LDA(At, 0, 1); PG8_STAGE(PG8_SB(0, 0), b2, voffB); PG8_STAGE(PG8_SB(0, 1), b2 + hstepB, voffB); PG8_STAGE(PG8_SA(0, 0), a2, voffA);
.LBB0_810:
	ds_read_b128 v[144:147], v149
	ds_read_b128 v[152:155], v149 offset:1024
	ds_read_b128 v[156:159], v149 offset:2048
	ds_read_b128 v[160:163], v149 offset:3072
	ds_read_b128 v[168:171], v150
	ds_read_b128 v[172:175], v150 offset:1024
	ds_read_b128 v[176:179], v150 offset:2048
	ds_read_b128 v[180:183], v150 offset:3072
	s_add_u32 s26, s22, 0x100
	s_addc_u32 s27, s23, 0
	s_cmpk_eq_i32 s56, 0x54
	s_cselect_b32 s31, s11, s27
	s_cselect_b32 s30, s10, s26
	s_cselect_b32 s29, s21, s55
	s_cselect_b32 s28, s20, s54
	v_lshl_add_u64 v[164:165], s[22:23], 0, v[136:137]
	s_add_i32 m0, s25, 0xc000
	ds_read_b128 v[184:187], v151
	ds_read_b128 v[188:191], v151 offset:1024
	ds_read_b128 v[192:195], v151 offset:2048
	ds_read_b128 v[196:199], v151 offset:3072
	ds_read_b128 v[200:203], v151 offset:4096
	ds_read_b128 v[204:207], v151 offset:5120
	ds_read_b128 v[208:211], v151 offset:6144
	ds_read_b128 v[212:215], v151 offset:7168
	global_load_lds_dwordx4 v[164:165], off
	v_lshl_add_u64 v[164:165], s[22:23], 0, v[138:139]
	s_add_i32 m0, s25, 0xe000
	s_nop 0
	global_load_lds_dwordx4 v[164:165], off
	s_waitcnt vmcnt(8)
	s_waitcnt lgkmcnt(0)
	s_barrier
	s_setprio 1
	v_mfma_f32_16x16x32_bf16 v[124:127], v[144:147], v[184:187], v[124:127]
	v_mfma_f32_16x16x32_bf16 v[120:123], v[156:159], v[184:187], v[120:123]
	v_mfma_f32_16x16x32_bf16 v[108:111], v[144:147], v[192:195], v[108:111]
	v_mfma_f32_16x16x32_bf16 v[104:107], v[156:159], v[192:195], v[104:107]
	v_mfma_f32_16x16x32_bf16 v[92:95], v[144:147], v[200:203], v[92:95]
	v_mfma_f32_16x16x32_bf16 v[88:91], v[156:159], v[200:203], v[88:91]
	v_mfma_f32_16x16x32_bf16 v[76:79], v[144:147], v[208:211], v[76:79]
	v_mfma_f32_16x16x32_bf16 v[72:75], v[156:159], v[208:211], v[72:75]
	v_mfma_f32_16x16x32_bf16 v[124:127], v[152:155], v[188:191], v[124:127]
	v_mfma_f32_16x16x32_bf16 v[120:123], v[160:163], v[188:191], v[120:123]
	v_mfma_f32_16x16x32_bf16 v[108:111], v[152:155], v[196:199], v[108:111]
	v_mfma_f32_16x16x32_bf16 v[104:107], v[160:163], v[196:199], v[104:107]
	v_mfma_f32_16x16x32_bf16 v[92:95], v[152:155], v[204:207], v[92:95]
	v_mfma_f32_16x16x32_bf16 v[88:91], v[160:163], v[204:207], v[88:91]
	v_mfma_f32_16x16x32_bf16 v[76:79], v[152:155], v[212:215], v[76:79]
	v_mfma_f32_16x16x32_bf16 v[72:75], v[160:163], v[212:215], v[72:75]
	v_mfma_f32_16x16x32_bf16 v[116:119], v[168:171], v[184:187], v[116:119]
	v_mfma_f32_16x16x32_bf16 v[112:115], v[176:179], v[184:187], v[112:115]
	v_mfma_f32_16x16x32_bf16 v[100:103], v[168:171], v[192:195], v[100:103]
	v_mfma_f32_16x16x32_bf16 v[96:99], v[176:179], v[192:195], v[96:99]
	v_mfma_f32_16x16x32_bf16 v[84:87], v[168:171], v[200:203], v[84:87]
	v_mfma_f32_16x16x32_bf16 v[80:83], v[176:179], v[200:203], v[80:83]
	v_mfma_f32_16x16x32_bf16 v[68:71], v[168:171], v[208:211], v[68:71]
	v_mfma_f32_16x16x32_bf16 v[64:67], v[176:179], v[208:211], v[64:67]
	v_mfma_f32_16x16x32_bf16 v[116:119], v[172:175], v[188:191], v[116:119]
	v_mfma_f32_16x16x32_bf16 v[112:115], v[180:183], v[188:191], v[112:115]
	v_mfma_f32_16x16x32_bf16 v[100:103], v[172:175], v[196:199], v[100:103]
	v_mfma_f32_16x16x32_bf16 v[96:99], v[180:183], v[196:199], v[96:99]
	v_mfma_f32_16x16x32_bf16 v[84:87], v[172:175], v[204:207], v[84:87]
	v_mfma_f32_16x16x32_bf16 v[80:83], v[180:183], v[204:207], v[80:83]
	v_mfma_f32_16x16x32_bf16 v[68:71], v[172:175], v[212:215], v[68:71]
	v_mfma_f32_16x16x32_bf16 v[64:67], v[180:183], v[212:215], v[64:67]
	s_setprio 0
	s_barrier
	s_add_i32 s4, s38, s47
	v_lshl_add_u64 v[164:165], s[28:29], 0, v[130:131]
	s_mov_b32 m0, s4
	ds_read_b128 v[184:187], v151 offset:16384
	ds_read_b128 v[188:191], v151 offset:17408
	ds_read_b128 v[192:195], v151 offset:18432
	ds_read_b128 v[196:199], v151 offset:19456
	ds_read_b128 v[200:203], v151 offset:20480
	ds_read_b128 v[204:207], v151 offset:21504
	ds_read_b128 v[208:211], v151 offset:22528
	ds_read_b128 v[212:215], v151 offset:23552
	global_load_lds_dwordx4 v[164:165], off
	s_add_i32 m0, s4, 0x2000
	s_add_u32 s4, s28, 0x160000
	v_lshl_add_u64 v[216:217], s[28:29], 0, v[134:135]
	s_addc_u32 s5, s29, 0
	s_add_i32 s22, s39, s47
	global_load_lds_dwordx4 v[216:217], off
	v_lshl_add_u64 v[218:219], s[4:5], 0, v[130:131]
	s_mov_b32 m0, s22
	v_lshl_add_u64 v[220:221], s[30:31], 0, v[132:133]
	global_load_lds_dwordx4 v[218:219], off
	v_lshl_add_u64 v[218:219], s[4:5], 0, v[134:135]
	s_add_i32 m0, s22, 0x2000
	s_nop 0
	global_load_lds_dwordx4 v[218:219], off
	v_lshl_add_u64 v[218:219], s[30:31], 0, v[128:129]
	s_mov_b32 m0, s25
	s_nop 0
	global_load_lds_dwordx4 v[218:219], off
	s_mov_b32 m0, s33
	s_nop 0
	global_load_lds_dwordx4 v[220:221], off
	s_waitcnt vmcnt(8)
	s_waitcnt lgkmcnt(0)
	s_barrier
; #define PG8_STAGE(bufoff, gbase, voff) do { _Pragma("unroll") for (int _i = 0; _i < 2; ++_i) \
;         __builtin_amdgcn_global_load_lds((const unsigned*)((const char*)(gbase) + (voff)[_i]), (PG8_LAS unsigned*)(lds + (bufoff) + ldsw + _i * 8192), 16, 0, 0); } while (0)
; #define PG8_LDA(dst, b, h) do { _Pragma("unroll") for (int m = 0; m < 4; ++m) _Pragma("unroll") for (int k = 0; k < 2; ++k) dst[m][k] = *(const PG8_LAS bf16x8*)(lds + PG8_SA(b, h) + aoff + m * 2048 + k * 1024); } while (0)
; #define PG8_LDB(dst, b, h) do { _Pragma("unroll") for (int n = 0; n < 2; ++n) _Pragma("unroll") for (int k = 0; k < 2; ++k) dst[n][k] = *(const PG8_LAS bf16x8*)(lds + PG8_SB(b, h) + boff + n * 2048 + k * 1024); } while (0)
; #define PG8_MMA(ai, bj, At, Bt) do { __builtin_amdgcn_s_setprio(1); _Pragma("unroll") for (int m = 0; m < 4; ++m) _Pragma("unroll") for (int n = 0; n < 2; ++n) _Pragma("unroll") for (int k = 0; k < 2; ++k) \
;         acc[ai][bj][m][n] = __builtin_amdgcn_mfma_f32_16x16x32_bf16(Bt[n][k], At[m][k], acc[ai][bj][m][n], 0, 0, 0); __builtin_amdgcn_s_setprio(0); } while (0)
; #define PG8_WAIT_V(n) asm volatile("s_waitcnt vmcnt(" #n ")" ::: "memory")
; #define PG8_WAIT_L(n) asm volatile("s_waitcnt lgkmcnt(" #n ")" ::: "memory")
; #define PG8_BAR __builtin_amdgcn_s_barrier()
; #define PG8_SCHED __builtin_amdgcn_sched_barrier(0)
; template <class Epi, class Sched, bool ALIGN_EPI = false, bool SP2 = false>
; __device__ __forceinline__ void gemm_phase(PG8_LAS unsigned char* lds, const Gemm g, const Sched& S, const Epi& E) {
;     ...
;             PG8_WAIT_V(8); PG8_WAIT_L(0); PG8_BAR; PG8_MMA(1, 0, At, B0); PG8_MMA(1, 1, At, B1); PG8_BAR; PG8_SCHED;
;             PG8_LDB(B0, 1, 0); PG8_LDB(B1, 1, 1); PG8_SCHED; PG8_LDA(At, 1, 0); PG8_STAGE(PG8_SA(0, 1), a2 + hstepA, voffA);
;             PG8_WAIT_V(8); PG8_WAIT_L(0); PG8_BAR; PG8_MMA(0, 0, At, B0); PG8_MMA(0, 1, At, B1); PG8_BAR; PG8_SCHED;
	s_setprio 1
	v_mfma_f32_16x16x32_bf16 v[60:63], v[144:147], v[184:187], v[60:63]
	v_mfma_f32_16x16x32_bf16 v[56:59], v[156:159], v[184:187], v[56:59]
	v_mfma_f32_16x16x32_bf16 v[44:47], v[144:147], v[192:195], v[44:47]
	v_mfma_f32_16x16x32_bf16 v[40:43], v[156:159], v[192:195], v[40:43]
	v_mfma_f32_16x16x32_bf16 v[28:31], v[144:147], v[200:203], v[28:31]
	v_mfma_f32_16x16x32_bf16 v[24:27], v[156:159], v[200:203], v[24:27]
	v_mfma_f32_16x16x32_bf16 v[12:15], v[144:147], v[208:211], v[12:15]
	v_mfma_f32_16x16x32_bf16 v[8:11], v[156:159], v[208:211], v[8:11]
	v_mfma_f32_16x16x32_bf16 v[60:63], v[152:155], v[188:191], v[60:63]
	v_mfma_f32_16x16x32_bf16 v[56:59], v[160:163], v[188:191], v[56:59]
	v_mfma_f32_16x16x32_bf16 v[44:47], v[152:155], v[196:199], v[44:47]
	v_mfma_f32_16x16x32_bf16 v[40:43], v[160:163], v[196:199], v[40:43]
	v_mfma_f32_16x16x32_bf16 v[28:31], v[152:155], v[204:207], v[28:31]
	v_mfma_f32_16x16x32_bf16 v[24:27], v[160:163], v[204:207], v[24:27]
	v_mfma_f32_16x16x32_bf16 v[12:15], v[152:155], v[212:215], v[12:15]
	v_mfma_f32_16x16x32_bf16 v[8:11], v[160:163], v[212:215], v[8:11]
	v_mfma_f32_16x16x32_bf16 v[52:55], v[168:171], v[184:187], v[52:55]
	v_mfma_f32_16x16x32_bf16 v[48:51], v[176:179], v[184:187], v[48:51]
	v_mfma_f32_16x16x32_bf16 v[36:39], v[168:171], v[192:195], v[36:39]
	v_mfma_f32_16x16x32_bf16 v[32:35], v[176:179], v[192:195], v[32:35]
	v_mfma_f32_16x16x32_bf16 v[20:23], v[168:171], v[200:203], v[20:23]
	v_mfma_f32_16x16x32_bf16 v[16:19], v[176:179], v[200:203], v[16:19]
	v_mfma_f32_16x16x32_bf16 v[4:7], v[168:171], v[208:211], v[4:7]
	v_mfma_f32_16x16x32_bf16 v[0:3], v[176:179], v[208:211], v[0:3]
	v_mfma_f32_16x16x32_bf16 v[52:55], v[172:175], v[188:191], v[52:55]
	v_mfma_f32_16x16x32_bf16 v[48:51], v[180:183], v[188:191], v[48:51]
	v_mfma_f32_16x16x32_bf16 v[36:39], v[172:175], v[196:199], v[36:39]
	v_mfma_f32_16x16x32_bf16 v[32:35], v[180:183], v[196:199], v[32:35]
	v_mfma_f32_16x16x32_bf16 v[20:23], v[172:175], v[204:207], v[20:23]
	v_mfma_f32_16x16x32_bf16 v[16:19], v[180:183], v[204:207], v[16:19]
	v_mfma_f32_16x16x32_bf16 v[4:7], v[172:175], v[212:215], v[4:7]
	v_mfma_f32_16x16x32_bf16 v[0:3], v[180:183], v[212:215], v[0:3]
	s_setprio 0
	s_barrier
	s_add_i32 s22, 0, 0x18000
	s_add_i32 s23, 0, 0x1c000
	v_add_u32_e32 v160, s22, v148
	v_add_u32_e32 v166, s23, v148
	ds_read_b128 v[144:147], v160
	ds_read_b128 v[152:155], v160 offset:1024
	ds_read_b128 v[156:159], v160 offset:2048
	ds_read_b128 v[160:163], v160 offset:3072
	ds_read_b128 v[168:171], v166
	ds_read_b128 v[172:175], v166 offset:1024
	ds_read_b128 v[176:179], v166 offset:2048
	ds_read_b128 v[180:183], v166 offset:3072
	s_add_u32 s4, s30, 0x160000
	s_addc_u32 s5, s31, 0
	s_mov_b32 m0, s34
	v_lshl_add_u64 v[222:223], s[4:5], 0, v[128:129]
	ds_read_b128 v[184:187], v151 offset:32768
	ds_read_b128 v[188:191], v151 offset:33792
	ds_read_b128 v[192:195], v151 offset:34816
	ds_read_b128 v[196:199], v151 offset:35840
	ds_read_b128 v[200:203], v151 offset:36864
	ds_read_b128 v[204:207], v151 offset:37888
	ds_read_b128 v[208:211], v151 offset:38912
	ds_read_b128 v[212:215], v151 offset:39936
	global_load_lds_dwordx4 v[222:223], off
	v_lshl_add_u64 v[222:223], s[4:5], 0, v[132:133]
	s_mov_b32 m0, s35
	s_nop 0
	global_load_lds_dwordx4 v[222:223], off
	s_waitcnt vmcnt(8)
	s_waitcnt lgkmcnt(0)
	s_barrier
	s_setprio 1
	v_mfma_f32_16x16x32_bf16 v[124:127], v[144:147], v[184:187], v[124:127]
	v_mfma_f32_16x16x32_bf16 v[120:123], v[156:159], v[184:187], v[120:123]
	v_mfma_f32_16x16x32_bf16 v[108:111], v[144:147], v[192:195], v[108:111]
	v_mfma_f32_16x16x32_bf16 v[104:107], v[156:159], v[192:195], v[104:107]
	v_mfma_f32_16x16x32_bf16 v[92:95], v[144:147], v[200:203], v[92:95]
	v_mfma_f32_16x16x32_bf16 v[88:91], v[156:159], v[200:203], v[88:91]
	v_mfma_f32_16x16x32_bf16 v[76:79], v[144:147], v[208:211], v[76:79]
	v_mfma_f32_16x16x32_bf16 v[72:75], v[156:159], v[208:211], v[72:75]
	v_mfma_f32_16x16x32_bf16 v[124:127], v[152:155], v[188:191], v[124:127]
	v_mfma_f32_16x16x32_bf16 v[120:123], v[160:163], v[188:191], v[120:123]
	v_mfma_f32_16x16x32_bf16 v[108:111], v[152:155], v[196:199], v[108:111]
	v_mfma_f32_16x16x32_bf16 v[104:107], v[160:163], v[196:199], v[104:107]
	v_mfma_f32_16x16x32_bf16 v[92:95], v[152:155], v[204:207], v[92:95]
	v_mfma_f32_16x16x32_bf16 v[88:91], v[160:163], v[204:207], v[88:91]
	v_mfma_f32_16x16x32_bf16 v[76:79], v[152:155], v[212:215], v[76:79]
	v_mfma_f32_16x16x32_bf16 v[72:75], v[160:163], v[212:215], v[72:75]
	v_mfma_f32_16x16x32_bf16 v[116:119], v[168:171], v[184:187], v[116:119]
	v_mfma_f32_16x16x32_bf16 v[112:115], v[176:179], v[184:187], v[112:115]
	v_mfma_f32_16x16x32_bf16 v[100:103], v[168:171], v[192:195], v[100:103]
	v_mfma_f32_16x16x32_bf16 v[96:99], v[176:179], v[192:195], v[96:99]
	v_mfma_f32_16x16x32_bf16 v[84:87], v[168:171], v[200:203], v[84:87]
	v_mfma_f32_16x16x32_bf16 v[80:83], v[176:179], v[200:203], v[80:83]
	v_mfma_f32_16x16x32_bf16 v[68:71], v[168:171], v[208:211], v[68:71]
	v_mfma_f32_16x16x32_bf16 v[64:67], v[176:179], v[208:211], v[64:67]
	v_mfma_f32_16x16x32_bf16 v[116:119], v[172:175], v[188:191], v[116:119]
	v_mfma_f32_16x16x32_bf16 v[112:115], v[180:183], v[188:191], v[112:115]
	v_mfma_f32_16x16x32_bf16 v[100:103], v[172:175], v[196:199], v[100:103]
	v_mfma_f32_16x16x32_bf16 v[96:99], v[180:183], v[196:199], v[96:99]
	v_mfma_f32_16x16x32_bf16 v[84:87], v[172:175], v[204:207], v[84:87]
	v_mfma_f32_16x16x32_bf16 v[80:83], v[180:183], v[204:207], v[80:83]
	v_mfma_f32_16x16x32_bf16 v[68:71], v[172:175], v[212:215], v[68:71]
	v_mfma_f32_16x16x32_bf16 v[64:67], v[180:183], v[212:215], v[64:67]
	s_setprio 0
	s_barrier
; #define PG8_STAGE(bufoff, gbase, voff) do { _Pragma("unroll") for (int _i = 0; _i < 2; ++_i) \
;         __builtin_amdgcn_global_load_lds((const unsigned*)((const char*)(gbase) + (voff)[_i]), (PG8_LAS unsigned*)(lds + (bufoff) + ldsw + _i * 8192), 16, 0, 0); } while (0)
; #define PG8_LDA(dst, b, h) do { _Pragma("unroll") for (int m = 0; m < 4; ++m) _Pragma("unroll") for (int k = 0; k < 2; ++k) dst[m][k] = *(const PG8_LAS bf16x8*)(lds + PG8_SA(b, h) + aoff + m * 2048 + k * 1024); } while (0)
; #define PG8_LDB(dst, b, h) do { _Pragma("unroll") for (int n = 0; n < 2; ++n) _Pragma("unroll") for (int k = 0; k < 2; ++k) dst[n][k] = *(const PG8_LAS bf16x8*)(lds + PG8_SB(b, h) + boff + n * 2048 + k * 1024); } while (0)
; #define PG8_MMA(ai, bj, At, Bt) do { __builtin_amdgcn_s_setprio(1); _Pragma("unroll") for (int m = 0; m < 4; ++m) _Pragma("unroll") for (int n = 0; n < 2; ++n) _Pragma("unroll") for (int k = 0; k < 2; ++k) \
;         acc[ai][bj][m][n] = __builtin_amdgcn_mfma_f32_16x16x32_bf16(Bt[n][k], At[m][k], acc[ai][bj][m][n], 0, 0, 0); __builtin_amdgcn_s_setprio(0); } while (0)
; #define PG8_WAIT_V(n) asm volatile("s_waitcnt vmcnt(" #n ")" ::: "memory")
; template <class Epi, class Sched, bool ALIGN_EPI = false, bool SP2 = false>
; __device__ __forceinline__ void gemm_phase(PG8_LAS unsigned char* lds, const Gemm g, const Sched& S, const Epi& E) {
;     ...
;             PG8_LDB(B0, 0, 0); PG8_LDB(B1, 0, 1); PG8_SCHED; PG8_LDA(At, 0, 0); PG8_STAGE(PG8_SA(1, 1), a1 + hstepA, voffA);
;             PG8_WAIT_V(8); PG8_WAIT_L(0); PG8_BAR; PG8_MMA(0, 0, At, B0); PG8_MMA(0, 1, At, B1); PG8_BAR; PG8_SCHED;
;             PG8_LDA(At, 0, 1); PG8_STAGE(PG8_SB(0, 0), b2, voffB); PG8_STAGE(PG8_SB(0, 1), b2 + hstepB, voffB); PG8_STAGE(PG8_SA(0, 0), a2, voffA);
;             PG8_WAIT_V(8); PG8_WAIT_L(0); PG8_BAR; PG8_MMA(1, 0, At, B0); PG8_MMA(1, 1, At, B1); PG8_BAR; PG8_SCHED;
;             PG8_LDB(B0, 1, 0); PG8_LDB(B1, 1, 1); PG8_SCHED; PG8_LDA(At, 1, 0); PG8_STAGE(PG8_SA(0, 1), a2 + hstepA, voffA);
;             PG8_WAIT_V(8); PG8_WAIT_L(0); PG8_BAR; PG8_MMA(0, 0, At, B0); PG8_MMA(0, 1, At, B1); PG8_BAR; PG8_SCHED;
;             PG8_LDA(At, 1, 1); PG8_STAGE(PG8_SB(1, 0), b3, voffB); PG8_STAGE(PG8_SB(1, 1), b3 + hstepB, voffB); PG8_STAGE(PG8_SA(1, 0), a3, voffA);
;             PG8_WAIT_V(8); PG8_WAIT_L(0); PG8_BAR; PG8_MMA(1, 0, At, B0); PG8_MMA(1, 1, At, B1); PG8_BAR; PG8_SCHED;
	s_add_i32 s4, s22, s47
	v_lshl_add_u64 v[164:165], v[164:165], 0, s[18:19]
	s_mov_b32 m0, s4
	ds_read_b128 v[184:187], v151 offset:49152
	ds_read_b128 v[188:191], v151 offset:50176
	ds_read_b128 v[192:195], v151 offset:51200
	ds_read_b128 v[196:199], v151 offset:52224
	ds_read_b128 v[200:203], v151 offset:53248
	ds_read_b128 v[204:207], v151 offset:54272
	ds_read_b128 v[208:211], v151 offset:55296
	ds_read_b128 v[212:215], v151 offset:56320
	global_load_lds_dwordx4 v[164:165], off
	s_add_i32 m0, s4, 0x2000
	s_add_u32 s4, s28, 0x160080
	v_lshl_add_u64 v[164:165], v[216:217], 0, s[18:19]
	s_addc_u32 s5, s29, 0
	s_add_i32 s22, s23, s47
	global_load_lds_dwordx4 v[164:165], off
	v_lshl_add_u64 v[164:165], s[4:5], 0, v[130:131]
	s_mov_b32 m0, s22
	s_nop 0
	global_load_lds_dwordx4 v[164:165], off
	v_lshl_add_u64 v[164:165], s[4:5], 0, v[134:135]
	s_add_i32 m0, s22, 0x2000
	s_nop 0
	global_load_lds_dwordx4 v[164:165], off
	v_lshl_add_u64 v[164:165], v[218:219], 0, s[18:19]
	s_mov_b32 m0, s36
	s_nop 0
	global_load_lds_dwordx4 v[164:165], off
	v_lshl_add_u64 v[164:165], v[220:221], 0, s[18:19]
	s_mov_b32 m0, s37
	s_nop 0
	global_load_lds_dwordx4 v[164:165], off
	s_waitcnt vmcnt(8)
	s_waitcnt lgkmcnt(0)
	s_barrier
	s_setprio 1
	v_mfma_f32_16x16x32_bf16 v[60:63], v[144:147], v[184:187], v[60:63]
	v_mfma_f32_16x16x32_bf16 v[56:59], v[156:159], v[184:187], v[56:59]
	v_mfma_f32_16x16x32_bf16 v[44:47], v[144:147], v[192:195], v[44:47]
	v_mfma_f32_16x16x32_bf16 v[40:43], v[156:159], v[192:195], v[40:43]
	v_mfma_f32_16x16x32_bf16 v[28:31], v[144:147], v[200:203], v[28:31]
	v_mfma_f32_16x16x32_bf16 v[24:27], v[156:159], v[200:203], v[24:27]
	v_mfma_f32_16x16x32_bf16 v[12:15], v[144:147], v[208:211], v[12:15]
	v_mfma_f32_16x16x32_bf16 v[8:11], v[156:159], v[208:211], v[8:11]
	v_mfma_f32_16x16x32_bf16 v[60:63], v[152:155], v[188:191], v[60:63]
	v_mfma_f32_16x16x32_bf16 v[56:59], v[160:163], v[188:191], v[56:59]
	v_mfma_f32_16x16x32_bf16 v[44:47], v[152:155], v[196:199], v[44:47]
	v_mfma_f32_16x16x32_bf16 v[40:43], v[160:163], v[196:199], v[40:43]
	v_mfma_f32_16x16x32_bf16 v[28:31], v[152:155], v[204:207], v[28:31]
	v_mfma_f32_16x16x32_bf16 v[24:27], v[160:163], v[204:207], v[24:27]
	v_mfma_f32_16x16x32_bf16 v[12:15], v[152:155], v[212:215], v[12:15]
	v_mfma_f32_16x16x32_bf16 v[8:11], v[160:163], v[212:215], v[8:11]
	v_mfma_f32_16x16x32_bf16 v[52:55], v[168:171], v[184:187], v[52:55]
	v_mfma_f32_16x16x32_bf16 v[48:51], v[176:179], v[184:187], v[48:51]
	v_mfma_f32_16x16x32_bf16 v[36:39], v[168:171], v[192:195], v[36:39]
	v_mfma_f32_16x16x32_bf16 v[32:35], v[176:179], v[192:195], v[32:35]
	v_mfma_f32_16x16x32_bf16 v[20:23], v[168:171], v[200:203], v[20:23]
	v_mfma_f32_16x16x32_bf16 v[16:19], v[176:179], v[200:203], v[16:19]
	v_mfma_f32_16x16x32_bf16 v[4:7], v[168:171], v[208:211], v[4:7]
	v_mfma_f32_16x16x32_bf16 v[0:3], v[176:179], v[208:211], v[0:3]
	v_mfma_f32_16x16x32_bf16 v[52:55], v[172:175], v[188:191], v[52:55]
	v_mfma_f32_16x16x32_bf16 v[48:51], v[180:183], v[188:191], v[48:51]
	v_mfma_f32_16x16x32_bf16 v[36:39], v[172:175], v[196:199], v[36:39]
	v_mfma_f32_16x16x32_bf16 v[32:35], v[180:183], v[196:199], v[32:35]
	v_mfma_f32_16x16x32_bf16 v[20:23], v[172:175], v[204:207], v[20:23]
	v_mfma_f32_16x16x32_bf16 v[16:19], v[180:183], v[204:207], v[16:19]
	v_mfma_f32_16x16x32_bf16 v[4:7], v[172:175], v[212:215], v[4:7]
	v_mfma_f32_16x16x32_bf16 v[0:3], v[180:183], v[212:215], v[0:3]
	s_setprio 0
	s_barrier
	s_add_i32 s56, s56, 2
	s_add_u32 s54, s54, 0x100
	s_addc_u32 s55, s55, 0
	s_cmpk_gt_u32 s56, 0x55
	s_mov_b64 s[22:23], s[26:27]
	s_cbranch_scc0 .LBB0_810
	s_and_b64 vcc, exec, s[48:49]
	s_cbranch_vccz .LBB0_813
	s_barrier

; #define PG8_STAGE(bufoff, gbase, voff) do { _Pragma("unroll") for (int _i = 0; _i < 2; ++_i) \
;         __builtin_amdgcn_global_load_lds((const unsigned*)((const char*)(gbase) + (voff)[_i]), (PG8_LAS unsigned*)(lds + (bufoff) + ldsw + _i * 8192), 16, 0, 0); } while (0)
; #define PG8_LDA(dst, b, h) do { _Pragma("unroll") for (int m = 0; m < 4; ++m) _Pragma("unroll") for (int k = 0; k < 2; ++k) dst[m][k] = *(const PG8_LAS bf16x8*)(lds + PG8_SA(b, h) + aoff + m * 2048 + k * 1024); } while (0)
; #define PG8_LDB(dst, b, h) do { _Pragma("unroll") for (int n = 0; n < 2; ++n) _Pragma("unroll") for (int k = 0; k < 2; ++k) dst[n][k] = *(const PG8_LAS bf16x8*)(lds + PG8_SB(b, h) + boff + n * 2048 + k * 1024); } while (0)
; #define PG8_MMA(ai, bj, At, Bt) do { __builtin_amdgcn_s_setprio(1); _Pragma("unroll") for (int m = 0; m < 4; ++m) _Pragma("unroll") for (int n = 0; n < 2; ++n) _Pragma("unroll") for (int k = 0; k < 2; ++k) \
;         acc[ai][bj][m][n] = __builtin_amdgcn_mfma_f32_16x16x32_bf16(Bt[n][k], At[m][k], acc[ai][bj][m][n], 0, 0, 0); __builtin_amdgcn_s_setprio(0); } while (0)
; #define PG8_WAIT_V(n) asm volatile("s_waitcnt vmcnt(" #n ")" ::: "memory")
; #define PG8_WAIT_L(n) asm volatile("s_waitcnt lgkmcnt(" #n ")" ::: "memory")
; #define PG8_BAR __builtin_amdgcn_s_barrier()
; #define PG8_SCHED __builtin_amdgcn_sched_barrier(0)
; template <class Epi, class Sched, bool ALIGN_EPI = false, bool SP2 = false>
; __device__ __forceinline__ void gemm_phase(PG8_LAS unsigned char* lds, const Gemm g, const Sched& S, const Epi& E) {
;     ...
;             const bool last = (t == nt - 2);
;             const char* a1 = cA + (size_t)(t + 1) * kstep;
;             const char* a2 = last ? nA : cA + (size_t)(t + 2) * kstep; const char* b2 = last ? nB : cB + (size_t)(t + 2) * kstep;
;             const char* a3 = a2 + kstep; const char* b3 = b2 + kstep;
;             if (last && has_next) S.a_ready(nxt);
;             if constexpr (SP2) {
;             PG8_LDB(B0, 0, 0); PG8_LDB(B1, 0, 1); PG8_SCHED; PG8_LDA(At, 0, 0); PG8_STAGE(PG8_SA(1, 1), a1 + hstepA, voffA);
;             PG8_WAIT_V(8); PG8_WAIT_L(0); PG8_BAR; PG8_MMA(0, 0, At, B0); PG8_MMA(0, 1, At, B1); PG8_BAR; PG8_SCHED;
;             PG8_LDA(At, 0, 1); PG8_STAGE(PG8_SB(0, 0), b2, voffB); PG8_STAGE(PG8_SB(0, 1), b2 + hstepB, voffB); PG8_STAGE(PG8_SA(0, 0), a2, voffA);
.LBB0_892:
	ds_read_b128 v[144:147], v155
	ds_read_b128 v[148:151], v155 offset:1024
	ds_read_b128 v[160:163], v155 offset:2048
	ds_read_b128 v[168:171], v155 offset:3072
	ds_read_b128 v[172:175], v156
	ds_read_b128 v[176:179], v156 offset:1024
	ds_read_b128 v[180:183], v156 offset:2048
	ds_read_b128 v[184:187], v156 offset:3072
	s_add_u32 s4, s30, 0xfff80080
	s_addc_u32 s5, s31, -1
	s_cmp_eq_u32 s61, 28
	s_cselect_b32 s37, s11, s5
	s_cselect_b32 s36, s13, s4
	s_cselect_b32 s35, s21, s60
	s_cselect_b32 s34, s23, s59
	v_lshl_add_u64 v[152:153], s[30:31], 0, v[136:137]
	s_add_i32 m0, s25, 0xc000
	ds_read_b128 v[188:191], v157
	ds_read_b128 v[192:195], v157 offset:1024
	ds_read_b128 v[196:199], v157 offset:2048
	ds_read_b128 v[200:203], v157 offset:3072
	ds_read_b128 v[204:207], v157 offset:4096
	ds_read_b128 v[208:211], v157 offset:5120
	ds_read_b128 v[212:215], v157 offset:6144
	ds_read_b128 v[216:219], v157 offset:7168
	global_load_lds_dwordx4 v[152:153], off
	v_lshl_add_u64 v[152:153], s[30:31], 0, v[138:139]
	s_add_i32 m0, s25, 0xe000
	s_nop 0
	global_load_lds_dwordx4 v[152:153], off
	s_waitcnt vmcnt(8)
	s_waitcnt lgkmcnt(0)
	s_barrier
	s_setprio 1
	v_mfma_f32_16x16x32_bf16 v[124:127], v[144:147], v[188:191], v[124:127]
	v_mfma_f32_16x16x32_bf16 v[120:123], v[160:163], v[188:191], v[120:123]
	v_mfma_f32_16x16x32_bf16 v[108:111], v[144:147], v[196:199], v[108:111]
	v_mfma_f32_16x16x32_bf16 v[104:107], v[160:163], v[196:199], v[104:107]
	v_mfma_f32_16x16x32_bf16 v[92:95], v[144:147], v[204:207], v[92:95]
	v_mfma_f32_16x16x32_bf16 v[88:91], v[160:163], v[204:207], v[88:91]
	v_mfma_f32_16x16x32_bf16 v[76:79], v[144:147], v[212:215], v[76:79]
	v_mfma_f32_16x16x32_bf16 v[72:75], v[160:163], v[212:215], v[72:75]
	v_mfma_f32_16x16x32_bf16 v[124:127], v[148:151], v[192:195], v[124:127]
	v_mfma_f32_16x16x32_bf16 v[120:123], v[168:171], v[192:195], v[120:123]
	v_mfma_f32_16x16x32_bf16 v[108:111], v[148:151], v[200:203], v[108:111]
	v_mfma_f32_16x16x32_bf16 v[104:107], v[168:171], v[200:203], v[104:107]
	v_mfma_f32_16x16x32_bf16 v[92:95], v[148:151], v[208:211], v[92:95]
	v_mfma_f32_16x16x32_bf16 v[88:91], v[168:171], v[208:211], v[88:91]
	v_mfma_f32_16x16x32_bf16 v[76:79], v[148:151], v[216:219], v[76:79]
	v_mfma_f32_16x16x32_bf16 v[72:75], v[168:171], v[216:219], v[72:75]
	v_mfma_f32_16x16x32_bf16 v[116:119], v[172:175], v[188:191], v[116:119]
	v_mfma_f32_16x16x32_bf16 v[112:115], v[180:183], v[188:191], v[112:115]
	v_mfma_f32_16x16x32_bf16 v[100:103], v[172:175], v[196:199], v[100:103]
	v_mfma_f32_16x16x32_bf16 v[96:99], v[180:183], v[196:199], v[96:99]
	v_mfma_f32_16x16x32_bf16 v[84:87], v[172:175], v[204:207], v[84:87]
	v_mfma_f32_16x16x32_bf16 v[80:83], v[180:183], v[204:207], v[80:83]
	v_mfma_f32_16x16x32_bf16 v[68:71], v[172:175], v[212:215], v[68:71]
	v_mfma_f32_16x16x32_bf16 v[64:67], v[180:183], v[212:215], v[64:67]
	v_mfma_f32_16x16x32_bf16 v[116:119], v[176:179], v[192:195], v[116:119]
	v_mfma_f32_16x16x32_bf16 v[112:115], v[184:187], v[192:195], v[112:115]
	v_mfma_f32_16x16x32_bf16 v[100:103], v[176:179], v[200:203], v[100:103]
	v_mfma_f32_16x16x32_bf16 v[96:99], v[184:187], v[200:203], v[96:99]
	v_mfma_f32_16x16x32_bf16 v[84:87], v[176:179], v[208:211], v[84:87]
	v_mfma_f32_16x16x32_bf16 v[80:83], v[184:187], v[208:211], v[80:83]
	v_mfma_f32_16x16x32_bf16 v[68:71], v[176:179], v[216:219], v[68:71]
	v_mfma_f32_16x16x32_bf16 v[64:67], v[184:187], v[216:219], v[64:67]
	s_setprio 0
	s_barrier
	s_add_i32 s4, s45, s47
	v_lshl_add_u64 v[152:153], s[34:35], 0, v[130:131]
	s_mov_b32 m0, s4
	ds_read_b128 v[188:191], v157 offset:16384
	ds_read_b128 v[192:195], v157 offset:17408
	ds_read_b128 v[196:199], v157 offset:18432
	ds_read_b128 v[200:203], v157 offset:19456
	ds_read_b128 v[204:207], v157 offset:20480
	ds_read_b128 v[208:211], v157 offset:21504
	ds_read_b128 v[212:215], v157 offset:22528
	ds_read_b128 v[216:219], v157 offset:23552
	global_load_lds_dwordx4 v[152:153], off
	s_add_i32 m0, s4, 0x2000
	s_add_u32 s4, s34, 0x80000
	v_lshl_add_u64 v[164:165], s[34:35], 0, v[134:135]
	s_addc_u32 s5, s35, 0
	s_add_i32 s62, s46, s47
	global_load_lds_dwordx4 v[164:165], off
	v_lshl_add_u64 v[220:221], s[4:5], 0, v[130:131]
	s_mov_b32 m0, s62
	v_lshl_add_u64 v[222:223], s[36:37], 0, v[132:133]
	global_load_lds_dwordx4 v[220:221], off
	v_lshl_add_u64 v[220:221], s[4:5], 0, v[134:135]
	s_add_i32 m0, s62, 0x2000
	s_nop 0
	global_load_lds_dwordx4 v[220:221], off
	v_lshl_add_u64 v[220:221], s[36:37], 0, v[128:129]
	s_mov_b32 m0, s25
	s_nop 0
	global_load_lds_dwordx4 v[220:221], off
	s_mov_b32 m0, s33
	s_nop 0
	global_load_lds_dwordx4 v[222:223], off
	s_waitcnt vmcnt(8)
	s_waitcnt lgkmcnt(0)
	s_barrier
; #define PG8_STAGE(bufoff, gbase, voff) do { _Pragma("unroll") for (int _i = 0; _i < 2; ++_i) \
;         __builtin_amdgcn_global_load_lds((const unsigned*)((const char*)(gbase) + (voff)[_i]), (PG8_LAS unsigned*)(lds + (bufoff) + ldsw + _i * 8192), 16, 0, 0); } while (0)
; #define PG8_LDA(dst, b, h) do { _Pragma("unroll") for (int m = 0; m < 4; ++m) _Pragma("unroll") for (int k = 0; k < 2; ++k) dst[m][k] = *(const PG8_LAS bf16x8*)(lds + PG8_SA(b, h) + aoff + m * 2048 + k * 1024); } while (0)
; #define PG8_LDB(dst, b, h) do { _Pragma("unroll") for (int n = 0; n < 2; ++n) _Pragma("unroll") for (int k = 0; k < 2; ++k) dst[n][k] = *(const PG8_LAS bf16x8*)(lds + PG8_SB(b, h) + boff + n * 2048 + k * 1024); } while (0)
; #define PG8_MMA(ai, bj, At, Bt) do { __builtin_amdgcn_s_setprio(1); _Pragma("unroll") for (int m = 0; m < 4; ++m) _Pragma("unroll") for (int n = 0; n < 2; ++n) _Pragma("unroll") for (int k = 0; k < 2; ++k) \
;         acc[ai][bj][m][n] = __builtin_amdgcn_mfma_f32_16x16x32_bf16(Bt[n][k], At[m][k], acc[ai][bj][m][n], 0, 0, 0); __builtin_amdgcn_s_setprio(0); } while (0)
; #define PG8_WAIT_V(n) asm volatile("s_waitcnt vmcnt(" #n ")" ::: "memory")
; #define PG8_WAIT_L(n) asm volatile("s_waitcnt lgkmcnt(" #n ")" ::: "memory")
; #define PG8_BAR __builtin_amdgcn_s_barrier()
; #define PG8_SCHED __builtin_amdgcn_sched_barrier(0)
; template <class Epi, class Sched, bool ALIGN_EPI = false, bool SP2 = false>
; __device__ __forceinline__ void gemm_phase(PG8_LAS unsigned char* lds, const Gemm g, const Sched& S, const Epi& E) {
;     ...
;             PG8_WAIT_V(8); PG8_WAIT_L(0); PG8_BAR; PG8_MMA(1, 0, At, B0); PG8_MMA(1, 1, At, B1); PG8_BAR; PG8_SCHED;
;             PG8_LDB(B0, 1, 0); PG8_LDB(B1, 1, 1); PG8_SCHED; PG8_LDA(At, 1, 0); PG8_STAGE(PG8_SA(0, 1), a2 + hstepA, voffA);
;             PG8_WAIT_V(8); PG8_WAIT_L(0); PG8_BAR; PG8_MMA(0, 0, At, B0); PG8_MMA(0, 1, At, B1); PG8_BAR; PG8_SCHED;
	s_setprio 1
	v_mfma_f32_16x16x32_bf16 v[60:63], v[144:147], v[188:191], v[60:63]
	v_mfma_f32_16x16x32_bf16 v[56:59], v[160:163], v[188:191], v[56:59]
	v_mfma_f32_16x16x32_bf16 v[44:47], v[144:147], v[196:199], v[44:47]
	v_mfma_f32_16x16x32_bf16 v[40:43], v[160:163], v[196:199], v[40:43]
	v_mfma_f32_16x16x32_bf16 v[28:31], v[144:147], v[204:207], v[28:31]
	v_mfma_f32_16x16x32_bf16 v[24:27], v[160:163], v[204:207], v[24:27]
	v_mfma_f32_16x16x32_bf16 v[12:15], v[144:147], v[212:215], v[12:15]
	v_mfma_f32_16x16x32_bf16 v[8:11], v[160:163], v[212:215], v[8:11]
	v_mfma_f32_16x16x32_bf16 v[60:63], v[148:151], v[192:195], v[60:63]
	v_mfma_f32_16x16x32_bf16 v[56:59], v[168:171], v[192:195], v[56:59]
	v_mfma_f32_16x16x32_bf16 v[44:47], v[148:151], v[200:203], v[44:47]
	v_mfma_f32_16x16x32_bf16 v[40:43], v[168:171], v[200:203], v[40:43]
	v_mfma_f32_16x16x32_bf16 v[28:31], v[148:151], v[208:211], v[28:31]
	v_mfma_f32_16x16x32_bf16 v[24:27], v[168:171], v[208:211], v[24:27]
	v_mfma_f32_16x16x32_bf16 v[12:15], v[148:151], v[216:219], v[12:15]
	v_mfma_f32_16x16x32_bf16 v[8:11], v[168:171], v[216:219], v[8:11]
	v_mfma_f32_16x16x32_bf16 v[52:55], v[172:175], v[188:191], v[52:55]
	v_mfma_f32_16x16x32_bf16 v[48:51], v[180:183], v[188:191], v[48:51]
	v_mfma_f32_16x16x32_bf16 v[36:39], v[172:175], v[196:199], v[36:39]
	v_mfma_f32_16x16x32_bf16 v[32:35], v[180:183], v[196:199], v[32:35]
	v_mfma_f32_16x16x32_bf16 v[20:23], v[172:175], v[204:207], v[20:23]
	v_mfma_f32_16x16x32_bf16 v[16:19], v[180:183], v[204:207], v[16:19]
	v_mfma_f32_16x16x32_bf16 v[4:7], v[172:175], v[212:215], v[4:7]
	v_mfma_f32_16x16x32_bf16 v[0:3], v[180:183], v[212:215], v[0:3]
	v_mfma_f32_16x16x32_bf16 v[52:55], v[176:179], v[192:195], v[52:55]
	v_mfma_f32_16x16x32_bf16 v[48:51], v[184:187], v[192:195], v[48:51]
	v_mfma_f32_16x16x32_bf16 v[36:39], v[176:179], v[200:203], v[36:39]
	v_mfma_f32_16x16x32_bf16 v[32:35], v[184:187], v[200:203], v[32:35]
	v_mfma_f32_16x16x32_bf16 v[20:23], v[176:179], v[208:211], v[20:23]
	v_mfma_f32_16x16x32_bf16 v[16:19], v[184:187], v[208:211], v[16:19]
	v_mfma_f32_16x16x32_bf16 v[4:7], v[176:179], v[216:219], v[4:7]
	v_mfma_f32_16x16x32_bf16 v[0:3], v[184:187], v[216:219], v[0:3]
	s_setprio 0
	s_barrier
	s_add_i32 s62, 0, 0x18000
	v_add_u32_e32 v166, s62, v154
	s_add_i32 s63, 0, 0x1c000
	ds_read_b128 v[144:147], v166
	ds_read_b128 v[148:151], v166 offset:1024
	ds_read_b128 v[160:163], v166 offset:2048
	ds_read_b128 v[168:171], v166 offset:3072
	v_add_u32_e32 v166, s63, v154
	ds_read_b128 v[172:175], v166
	ds_read_b128 v[176:179], v166 offset:1024
	ds_read_b128 v[180:183], v166 offset:2048
	ds_read_b128 v[184:187], v166 offset:3072
	s_add_u32 s4, s36, 0x80000
	s_addc_u32 s5, s37, 0
	s_mov_b32 m0, s38
	v_lshl_add_u64 v[224:225], s[4:5], 0, v[128:129]
	ds_read_b128 v[188:191], v157 offset:32768
	ds_read_b128 v[192:195], v157 offset:33792
	ds_read_b128 v[196:199], v157 offset:34816
	ds_read_b128 v[200:203], v157 offset:35840
	ds_read_b128 v[204:207], v157 offset:36864
	ds_read_b128 v[208:211], v157 offset:37888
	ds_read_b128 v[212:215], v157 offset:38912
	ds_read_b128 v[216:219], v157 offset:39936
	global_load_lds_dwordx4 v[224:225], off
	v_lshl_add_u64 v[224:225], s[4:5], 0, v[132:133]
	s_mov_b32 m0, s39
	s_nop 0
	global_load_lds_dwordx4 v[224:225], off
	s_waitcnt vmcnt(8)
	s_waitcnt lgkmcnt(0)
	s_barrier
	s_setprio 1
	v_mfma_f32_16x16x32_bf16 v[124:127], v[144:147], v[188:191], v[124:127]
	v_mfma_f32_16x16x32_bf16 v[120:123], v[160:163], v[188:191], v[120:123]
	v_mfma_f32_16x16x32_bf16 v[108:111], v[144:147], v[196:199], v[108:111]
	v_mfma_f32_16x16x32_bf16 v[104:107], v[160:163], v[196:199], v[104:107]
	v_mfma_f32_16x16x32_bf16 v[92:95], v[144:147], v[204:207], v[92:95]
	v_mfma_f32_16x16x32_bf16 v[88:91], v[160:163], v[204:207], v[88:91]
	v_mfma_f32_16x16x32_bf16 v[76:79], v[144:147], v[212:215], v[76:79]
	v_mfma_f32_16x16x32_bf16 v[72:75], v[160:163], v[212:215], v[72:75]
	v_mfma_f32_16x16x32_bf16 v[124:127], v[148:151], v[192:195], v[124:127]
	v_mfma_f32_16x16x32_bf16 v[120:123], v[168:171], v[192:195], v[120:123]
	v_mfma_f32_16x16x32_bf16 v[108:111], v[148:151], v[200:203], v[108:111]
	v_mfma_f32_16x16x32_bf16 v[104:107], v[168:171], v[200:203], v[104:107]
	v_mfma_f32_16x16x32_bf16 v[92:95], v[148:151], v[208:211], v[92:95]
	v_mfma_f32_16x16x32_bf16 v[88:91], v[168:171], v[208:211], v[88:91]
	v_mfma_f32_16x16x32_bf16 v[76:79], v[148:151], v[216:219], v[76:79]
	v_mfma_f32_16x16x32_bf16 v[72:75], v[168:171], v[216:219], v[72:75]
	v_mfma_f32_16x16x32_bf16 v[116:119], v[172:175], v[188:191], v[116:119]
	v_mfma_f32_16x16x32_bf16 v[112:115], v[180:183], v[188:191], v[112:115]
	v_mfma_f32_16x16x32_bf16 v[100:103], v[172:175], v[196:199], v[100:103]
	v_mfma_f32_16x16x32_bf16 v[96:99], v[180:183], v[196:199], v[96:99]
	v_mfma_f32_16x16x32_bf16 v[84:87], v[172:175], v[204:207], v[84:87]
	v_mfma_f32_16x16x32_bf16 v[80:83], v[180:183], v[204:207], v[80:83]
	v_mfma_f32_16x16x32_bf16 v[68:71], v[172:175], v[212:215], v[68:71]
	v_mfma_f32_16x16x32_bf16 v[64:67], v[180:183], v[212:215], v[64:67]
	v_mfma_f32_16x16x32_bf16 v[116:119], v[176:179], v[192:195], v[116:119]
	v_mfma_f32_16x16x32_bf16 v[112:115], v[184:187], v[192:195], v[112:115]
	v_mfma_f32_16x16x32_bf16 v[100:103], v[176:179], v[200:203], v[100:103]
	v_mfma_f32_16x16x32_bf16 v[96:99], v[184:187], v[200:203], v[96:99]
	v_mfma_f32_16x16x32_bf16 v[84:87], v[176:179], v[208:211], v[84:87]
	v_mfma_f32_16x16x32_bf16 v[80:83], v[184:187], v[208:211], v[80:83]
	v_mfma_f32_16x16x32_bf16 v[68:71], v[176:179], v[216:219], v[68:71]
	v_mfma_f32_16x16x32_bf16 v[64:67], v[184:187], v[216:219], v[64:67]
	s_setprio 0
	s_barrier
; #define PG8_STAGE(bufoff, gbase, voff) do { _Pragma("unroll") for (int _i = 0; _i < 2; ++_i) \
;         __builtin_amdgcn_global_load_lds((const unsigned*)((const char*)(gbase) + (voff)[_i]), (PG8_LAS unsigned*)(lds + (bufoff) + ldsw + _i * 8192), 16, 0, 0); } while (0)
; #define PG8_LDA(dst, b, h) do { _Pragma("unroll") for (int m = 0; m < 4; ++m) _Pragma("unroll") for (int k = 0; k < 2; ++k) dst[m][k] = *(const PG8_LAS bf16x8*)(lds + PG8_SA(b, h) + aoff + m * 2048 + k * 1024); } while (0)
; #define PG8_MMA(ai, bj, At, Bt) do { __builtin_amdgcn_s_setprio(1); _Pragma("unroll") for (int m = 0; m < 4; ++m) _Pragma("unroll") for (int n = 0; n < 2; ++n) _Pragma("unroll") for (int k = 0; k < 2; ++k) \
;         acc[ai][bj][m][n] = __builtin_amdgcn_mfma_f32_16x16x32_bf16(Bt[n][k], At[m][k], acc[ai][bj][m][n], 0, 0, 0); __builtin_amdgcn_s_setprio(0); } while (0)
; #define PG8_WAIT_V(n) asm volatile("s_waitcnt vmcnt(" #n ")" ::: "memory")
; #define PG8_WAIT_L(n) asm volatile("s_waitcnt lgkmcnt(" #n ")" ::: "memory")
; #define PG8_BAR __builtin_amdgcn_s_barrier()
; #define PG8_SCHED __builtin_amdgcn_sched_barrier(0)
; template <class Epi, class Sched, bool ALIGN_EPI = false, bool SP2 = false>
; __device__ __forceinline__ void gemm_phase(PG8_LAS unsigned char* lds, const Gemm g, const Sched& S, const Epi& E) {
;     ...
;             PG8_LDA(At, 1, 1); PG8_STAGE(PG8_SB(1, 0), b3, voffB); PG8_STAGE(PG8_SB(1, 1), b3 + hstepB, voffB); PG8_STAGE(PG8_SA(1, 0), a3, voffA);
;             PG8_WAIT_V(8); PG8_WAIT_L(0); PG8_BAR; PG8_MMA(1, 0, At, B0); PG8_MMA(1, 1, At, B1); PG8_BAR; PG8_SCHED;
	s_add_i32 s4, s62, s47
	v_lshl_add_u64 v[152:153], v[152:153], 0, s[18:19]
	s_mov_b32 m0, s4
	ds_read_b128 v[188:191], v157 offset:49152
	ds_read_b128 v[192:195], v157 offset:50176
	ds_read_b128 v[196:199], v157 offset:51200
	ds_read_b128 v[200:203], v157 offset:52224
	ds_read_b128 v[204:207], v157 offset:53248
	ds_read_b128 v[208:211], v157 offset:54272
	ds_read_b128 v[212:215], v157 offset:55296
	ds_read_b128 v[216:219], v157 offset:56320
	global_load_lds_dwordx4 v[152:153], off
	s_add_i32 m0, s4, 0x2000
	s_add_u32 s4, s34, 0x80080
	v_lshl_add_u64 v[152:153], v[164:165], 0, s[18:19]
	s_addc_u32 s5, s35, 0
	s_add_i32 s34, s63, s47
	global_load_lds_dwordx4 v[152:153], off
	v_lshl_add_u64 v[152:153], s[4:5], 0, v[130:131]
	s_mov_b32 m0, s34
	s_nop 0
	global_load_lds_dwordx4 v[152:153], off
	v_lshl_add_u64 v[152:153], s[4:5], 0, v[134:135]
	s_add_i32 m0, s34, 0x2000
	s_nop 0
	global_load_lds_dwordx4 v[152:153], off
	v_lshl_add_u64 v[152:153], v[220:221], 0, s[18:19]
	s_mov_b32 m0, s41
	s_nop 0
	global_load_lds_dwordx4 v[152:153], off
	v_lshl_add_u64 v[152:153], v[222:223], 0, s[18:19]
	s_mov_b32 m0, s44
	s_nop 0
	global_load_lds_dwordx4 v[152:153], off
	s_waitcnt vmcnt(8)
	s_waitcnt lgkmcnt(0)
	s_barrier
	s_setprio 1
	v_mfma_f32_16x16x32_bf16 v[60:63], v[144:147], v[188:191], v[60:63]
	v_mfma_f32_16x16x32_bf16 v[56:59], v[160:163], v[188:191], v[56:59]
	v_mfma_f32_16x16x32_bf16 v[44:47], v[144:147], v[196:199], v[44:47]
	v_mfma_f32_16x16x32_bf16 v[40:43], v[160:163], v[196:199], v[40:43]
	v_mfma_f32_16x16x32_bf16 v[28:31], v[144:147], v[204:207], v[28:31]
	v_mfma_f32_16x16x32_bf16 v[24:27], v[160:163], v[204:207], v[24:27]
	v_mfma_f32_16x16x32_bf16 v[12:15], v[144:147], v[212:215], v[12:15]
	v_mfma_f32_16x16x32_bf16 v[8:11], v[160:163], v[212:215], v[8:11]
	v_mfma_f32_16x16x32_bf16 v[60:63], v[148:151], v[192:195], v[60:63]
	v_mfma_f32_16x16x32_bf16 v[56:59], v[168:171], v[192:195], v[56:59]
	v_mfma_f32_16x16x32_bf16 v[44:47], v[148:151], v[200:203], v[44:47]
	v_mfma_f32_16x16x32_bf16 v[40:43], v[168:171], v[200:203], v[40:43]
	v_mfma_f32_16x16x32_bf16 v[28:31], v[148:151], v[208:211], v[28:31]
	v_mfma_f32_16x16x32_bf16 v[24:27], v[168:171], v[208:211], v[24:27]
	v_mfma_f32_16x16x32_bf16 v[12:15], v[148:151], v[216:219], v[12:15]
	v_mfma_f32_16x16x32_bf16 v[8:11], v[168:171], v[216:219], v[8:11]
	v_mfma_f32_16x16x32_bf16 v[52:55], v[172:175], v[188:191], v[52:55]
	v_mfma_f32_16x16x32_bf16 v[48:51], v[180:183], v[188:191], v[48:51]
	v_mfma_f32_16x16x32_bf16 v[36:39], v[172:175], v[196:199], v[36:39]
	v_mfma_f32_16x16x32_bf16 v[32:35], v[180:183], v[196:199], v[32:35]
	v_mfma_f32_16x16x32_bf16 v[20:23], v[172:175], v[204:207], v[20:23]
	v_mfma_f32_16x16x32_bf16 v[16:19], v[180:183], v[204:207], v[16:19]
	v_mfma_f32_16x16x32_bf16 v[4:7], v[172:175], v[212:215], v[4:7]
	v_mfma_f32_16x16x32_bf16 v[0:3], v[180:183], v[212:215], v[0:3]
	v_mfma_f32_16x16x32_bf16 v[52:55], v[176:179], v[192:195], v[52:55]
	v_mfma_f32_16x16x32_bf16 v[48:51], v[184:187], v[192:195], v[48:51]
	v_mfma_f32_16x16x32_bf16 v[36:39], v[176:179], v[200:203], v[36:39]
	v_mfma_f32_16x16x32_bf16 v[32:35], v[184:187], v[200:203], v[32:35]
	v_mfma_f32_16x16x32_bf16 v[20:23], v[176:179], v[208:211], v[20:23]
	v_mfma_f32_16x16x32_bf16 v[16:19], v[184:187], v[208:211], v[16:19]
	v_mfma_f32_16x16x32_bf16 v[4:7], v[176:179], v[216:219], v[4:7]
	v_mfma_f32_16x16x32_bf16 v[0:3], v[184:187], v[216:219], v[0:3]
	s_setprio 0
	s_barrier
	s_add_i32 s61, s61, 2
	s_add_u32 s30, s30, 0x100
	s_addc_u32 s31, s31, 0
	s_add_u32 s59, s59, 0x100
	s_addc_u32 s60, s60, 0
	s_cmp_gt_u32 s61, 29
	s_cbranch_scc0 .LBB0_892
	s_and_b64 vcc, exec, s[48:49]
	s_cbranch_vccz .LBB0_895
	s_barrier

; #define PG8_STAGE(bufoff, gbase, voff) do { _Pragma("unroll") for (int _i = 0; _i < 2; ++_i) \
;         __builtin_amdgcn_global_load_lds((const unsigned*)((const char*)(gbase) + (voff)[_i]), (PG8_LAS unsigned*)(lds + (bufoff) + ldsw + _i * 8192), 16, 0, 0); } while (0)
; #define PG8_LDA(dst, b, h) do { _Pragma("unroll") for (int m = 0; m < 4; ++m) _Pragma("unroll") for (int k = 0; k < 2; ++k) dst[m][k] = *(const PG8_LAS bf16x8*)(lds + PG8_SA(b, h) + aoff + m * 2048 + k * 1024); } while (0)
; #define PG8_LDB(dst, b, h) do { _Pragma("unroll") for (int n = 0; n < 2; ++n) _Pragma("unroll") for (int k = 0; k < 2; ++k) dst[n][k] = *(const PG8_LAS bf16x8*)(lds + PG8_SB(b, h) + boff + n * 2048 + k * 1024); } while (0)
; #define PG8_MMA(ai, bj, At, Bt) do { __builtin_amdgcn_s_setprio(1); _Pragma("unroll") for (int m = 0; m < 4; ++m) _Pragma("unroll") for (int n = 0; n < 2; ++n) _Pragma("unroll") for (int k = 0; k < 2; ++k) \
;         acc[ai][bj][m][n] = __builtin_amdgcn_mfma_f32_16x16x32_bf16(Bt[n][k], At[m][k], acc[ai][bj][m][n], 0, 0, 0); __builtin_amdgcn_s_setprio(0); } while (0)
; template <class Epi, class Sched, bool ALIGN_EPI = false, bool SP2 = false>
; __device__ __forceinline__ void gemm_phase(PG8_LAS unsigned char* lds, const Gemm g, const Sched& S, const Epi& E) {
;     ...
;         const bool has_next = S.next(ui + 1, nxt);
;         const char* nA = has_next ? (const char*)g.A + (size_t)nxt.pm * tstepA + nxt.aoff : cA; const char* nB = has_next ? (const char*)g.Bt + (size_t)nxt.pn * tstepB : cB;
;         for (int t = 0; t < nt; t += 2) {
;             const bool last = (t == nt - 2);
;             const char* a1 = cA + (size_t)(t + 1) * kstep;
;             const char* a2 = last ? nA : cA + (size_t)(t + 2) * kstep; const char* b2 = last ? nB : cB + (size_t)(t + 2) * kstep;
;             const char* a3 = a2 + kstep; const char* b3 = b2 + kstep;
;             if (last && has_next) S.a_ready(nxt);
;             if constexpr (SP2) {
;             PG8_LDB(B0, 0, 0); PG8_LDB(B1, 0, 1); PG8_SCHED; PG8_LDA(At, 0, 0); PG8_STAGE(PG8_SA(1, 1), a1 + hstepA, voffA);
;             PG8_WAIT_V(8); PG8_WAIT_L(0); PG8_BAR; PG8_MMA(0, 0, At, B0); PG8_MMA(0, 1, At, B1); PG8_BAR; PG8_SCHED;
;             PG8_LDA(At, 0, 1); PG8_STAGE(PG8_SB(0, 0), b2, voffB); PG8_STAGE(PG8_SB(0, 1), b2 + hstepB, voffB); PG8_STAGE(PG8_SA(0, 0), a2, voffA);
.LBB0_1041:
	s_ashr_i32 s63, s62, 31
	s_lshl_b64 s[4:5], s[62:63], 20
	ds_read_b128 v[0:3], v168
	ds_read_b128 v[4:7], v168 offset:1024
	ds_read_b128 v[8:11], v168 offset:2048
	ds_read_b128 v[12:15], v168 offset:3072
	ds_read_b128 v[16:19], v169
	ds_read_b128 v[20:23], v169 offset:1024
	ds_read_b128 v[24:27], v169 offset:2048
	ds_read_b128 v[28:31], v169 offset:3072
	s_add_u32 s4, s20, s4
	s_addc_u32 s5, s21, s5
	s_ashr_i32 s11, s81, 31
	s_add_u32 s64, s4, s81
	s_addc_u32 s65, s5, s11
	s_and_b64 s[4:5], s[8:9], exec
	s_cselect_b32 s71, s65, s13
	s_cselect_b32 s70, s64, s12
	s_ashr_i32 s61, s60, 31
	s_lshl_b64 s[4:5], s[60:61], 17
	s_add_u32 s66, s0, s4
	s_addc_u32 s67, s1, s5
	s_and_b64 s[4:5], s[8:9], exec
	s_cselect_b32 s69, s67, s15
	s_cselect_b32 s68, s66, s14
	s_add_u32 s4, s12, 0x80080
	s_addc_u32 s5, s13, 0
	s_add_i32 s88, s3, 0xc000
	v_lshl_add_u64 v[64:65], s[4:5], 0, v[138:139]
	s_mov_b32 m0, s88
	s_add_i32 s11, s3, 0xe000
	ds_read_b128 v[32:35], v170
	ds_read_b128 v[36:39], v170 offset:1024
	ds_read_b128 v[40:43], v170 offset:2048
	ds_read_b128 v[44:47], v170 offset:3072
	ds_read_b128 v[48:51], v170 offset:4096
	ds_read_b128 v[52:55], v170 offset:5120
	ds_read_b128 v[56:59], v170 offset:6144
	ds_read_b128 v[60:63], v170 offset:7168
	global_load_lds_dwordx4 v[64:65], off
	v_lshl_add_u64 v[64:65], s[4:5], 0, v[134:135]
	s_mov_b32 m0, s11
	s_nop 0
	global_load_lds_dwordx4 v[64:65], off
	s_waitcnt vmcnt(8)
	s_waitcnt lgkmcnt(0)
	s_barrier
	s_setprio 1
	v_mfma_f32_16x16x32_bf16 v[64:67], v[0:3], v[32:35], 0
	v_mfma_f32_16x16x32_bf16 v[68:71], v[8:11], v[32:35], 0
	v_mfma_f32_16x16x32_bf16 v[72:75], v[0:3], v[40:43], 0
	v_mfma_f32_16x16x32_bf16 v[76:79], v[8:11], v[40:43], 0
	v_mfma_f32_16x16x32_bf16 v[80:83], v[0:3], v[48:51], 0
	v_mfma_f32_16x16x32_bf16 v[84:87], v[8:11], v[48:51], 0
	v_mfma_f32_16x16x32_bf16 v[88:91], v[0:3], v[56:59], 0
	v_mfma_f32_16x16x32_bf16 v[92:95], v[8:11], v[56:59], 0
	v_mfma_f32_16x16x32_bf16 v[64:67], v[4:7], v[36:39], v[64:67]
	v_mfma_f32_16x16x32_bf16 v[68:71], v[12:15], v[36:39], v[68:71]
	v_mfma_f32_16x16x32_bf16 v[72:75], v[4:7], v[44:47], v[72:75]
	v_mfma_f32_16x16x32_bf16 v[76:79], v[12:15], v[44:47], v[76:79]
	v_mfma_f32_16x16x32_bf16 v[80:83], v[4:7], v[52:55], v[80:83]
	v_mfma_f32_16x16x32_bf16 v[84:87], v[12:15], v[52:55], v[84:87]
	v_mfma_f32_16x16x32_bf16 v[88:91], v[4:7], v[60:63], v[88:91]
	v_mfma_f32_16x16x32_bf16 v[92:95], v[12:15], v[60:63], v[92:95]
	v_mfma_f32_16x16x32_bf16 v[96:99], v[16:19], v[32:35], 0
	v_mfma_f32_16x16x32_bf16 v[32:35], v[24:27], v[32:35], 0
	v_mfma_f32_16x16x32_bf16 v[96:99], v[20:23], v[36:39], v[96:99]
	v_mfma_f32_16x16x32_bf16 v[32:35], v[28:31], v[36:39], v[32:35]
	v_mfma_f32_16x16x32_bf16 v[36:39], v[16:19], v[40:43], 0
	v_mfma_f32_16x16x32_bf16 v[40:43], v[24:27], v[40:43], 0
	v_mfma_f32_16x16x32_bf16 v[36:39], v[20:23], v[44:47], v[36:39]
	v_mfma_f32_16x16x32_bf16 v[40:43], v[28:31], v[44:47], v[40:43]
	v_mfma_f32_16x16x32_bf16 v[44:47], v[16:19], v[48:51], 0
	v_mfma_f32_16x16x32_bf16 v[48:51], v[24:27], v[48:51], 0
	v_mfma_f32_16x16x32_bf16 v[44:47], v[20:23], v[52:55], v[44:47]
	v_mfma_f32_16x16x32_bf16 v[48:51], v[28:31], v[52:55], v[48:51]
	v_mfma_f32_16x16x32_bf16 v[52:55], v[16:19], v[56:59], 0
	v_mfma_f32_16x16x32_bf16 v[56:59], v[24:27], v[56:59], 0
	v_mfma_f32_16x16x32_bf16 v[52:55], v[20:23], v[60:63], v[52:55]
	v_mfma_f32_16x16x32_bf16 v[56:59], v[28:31], v[60:63], v[56:59]
	s_setprio 0
	s_barrier
	s_add_i32 s86, s45, s47
	v_lshl_add_u64 v[164:165], s[14:15], 0, v[136:137]
	s_add_i32 s61, s86, 0x2000
	v_lshl_add_u64 v[128:129], v[164:165], 0, s[36:37]
	s_mov_b32 m0, s86
	v_lshl_add_u64 v[212:213], s[14:15], 0, v[132:133]
	s_add_u32 s4, s14, 0x10100
	ds_read_b128 v[60:63], v170 offset:16384
	ds_read_b128 v[100:103], v170 offset:17408
	ds_read_b128 v[104:107], v170 offset:18432
	ds_read_b128 v[108:111], v170 offset:19456
	ds_read_b128 v[112:115], v170 offset:20480
	ds_read_b128 v[116:119], v170 offset:21504
	ds_read_b128 v[120:123], v170 offset:22528
	ds_read_b128 v[124:127], v170 offset:23552
	global_load_lds_dwordx4 v[128:129], off
	v_lshl_add_u64 v[128:129], v[212:213], 0, s[36:37]
	s_mov_b32 m0, s61
	s_addc_u32 s5, s15, 0
	s_add_i32 s63, s46, s47
	global_load_lds_dwordx4 v[128:129], off
	v_lshl_add_u64 v[128:129], s[4:5], 0, v[136:137]
	s_mov_b32 m0, s63
	s_add_i32 s85, s63, 0x2000
	global_load_lds_dwordx4 v[128:129], off
	v_lshl_add_u64 v[128:129], s[4:5], 0, v[132:133]
	s_mov_b32 m0, s85
	v_lshl_add_u64 v[214:215], s[12:13], 0, v[138:139]
	global_load_lds_dwordx4 v[128:129], off
	v_lshl_add_u64 v[128:129], v[214:215], 0, s[36:37]
	s_mov_b32 m0, s3
	v_lshl_add_u64 v[216:217], s[12:13], 0, v[134:135]
	global_load_lds_dwordx4 v[128:129], off
	v_lshl_add_u64 v[128:129], v[216:217], 0, s[36:37]
	s_mov_b32 m0, s24
	s_nop 0
	global_load_lds_dwordx4 v[128:129], off
	s_waitcnt vmcnt(8)
	s_waitcnt lgkmcnt(0)
	s_barrier
; #define PG8_STAGE(bufoff, gbase, voff) do { _Pragma("unroll") for (int _i = 0; _i < 2; ++_i) \
;         __builtin_amdgcn_global_load_lds((const unsigned*)((const char*)(gbase) + (voff)[_i]), (PG8_LAS unsigned*)(lds + (bufoff) + ldsw + _i * 8192), 16, 0, 0); } while (0)
; #define PG8_LDA(dst, b, h) do { _Pragma("unroll") for (int m = 0; m < 4; ++m) _Pragma("unroll") for (int k = 0; k < 2; ++k) dst[m][k] = *(const PG8_LAS bf16x8*)(lds + PG8_SA(b, h) + aoff + m * 2048 + k * 1024); } while (0)
; #define PG8_LDB(dst, b, h) do { _Pragma("unroll") for (int n = 0; n < 2; ++n) _Pragma("unroll") for (int k = 0; k < 2; ++k) dst[n][k] = *(const PG8_LAS bf16x8*)(lds + PG8_SB(b, h) + boff + n * 2048 + k * 1024); } while (0)
; #define PG8_MMA(ai, bj, At, Bt) do { __builtin_amdgcn_s_setprio(1); _Pragma("unroll") for (int m = 0; m < 4; ++m) _Pragma("unroll") for (int n = 0; n < 2; ++n) _Pragma("unroll") for (int k = 0; k < 2; ++k) \
;         acc[ai][bj][m][n] = __builtin_amdgcn_mfma_f32_16x16x32_bf16(Bt[n][k], At[m][k], acc[ai][bj][m][n], 0, 0, 0); __builtin_amdgcn_s_setprio(0); } while (0)
; #define PG8_WAIT_V(n) asm volatile("s_waitcnt vmcnt(" #n ")" ::: "memory")
; #define PG8_WAIT_L(n) asm volatile("s_waitcnt lgkmcnt(" #n ")" ::: "memory")
; #define PG8_BAR __builtin_amdgcn_s_barrier()
; #define PG8_SCHED __builtin_amdgcn_sched_barrier(0)
; template <class Epi, class Sched, bool ALIGN_EPI = false, bool SP2 = false>
; __device__ __forceinline__ void gemm_phase(PG8_LAS unsigned char* lds, const Gemm g, const Sched& S, const Epi& E) {
;     ...
;             PG8_WAIT_V(8); PG8_WAIT_L(0); PG8_BAR; PG8_MMA(1, 0, At, B0); PG8_MMA(1, 1, At, B1); PG8_BAR; PG8_SCHED;
;             PG8_LDB(B0, 1, 0); PG8_LDB(B1, 1, 1); PG8_SCHED; PG8_LDA(At, 1, 0); PG8_STAGE(PG8_SA(0, 1), a2 + hstepA, voffA);
;             PG8_WAIT_V(8); PG8_WAIT_L(0); PG8_BAR; PG8_MMA(0, 0, At, B0); PG8_MMA(0, 1, At, B1); PG8_BAR; PG8_SCHED;
	s_setprio 1
	v_mfma_f32_16x16x32_bf16 v[128:131], v[0:3], v[60:63], 0
	v_mfma_f32_16x16x32_bf16 v[148:151], v[0:3], v[104:107], 0
	v_mfma_f32_16x16x32_bf16 v[156:159], v[0:3], v[112:115], 0
	v_mfma_f32_16x16x32_bf16 v[0:3], v[0:3], v[120:123], 0
	v_mfma_f32_16x16x32_bf16 v[128:131], v[4:7], v[100:103], v[128:131]
	v_mfma_f32_16x16x32_bf16 v[148:151], v[4:7], v[108:111], v[148:151]
	v_mfma_f32_16x16x32_bf16 v[156:159], v[4:7], v[116:119], v[156:159]
	v_mfma_f32_16x16x32_bf16 v[0:3], v[4:7], v[124:127], v[0:3]
	v_mfma_f32_16x16x32_bf16 v[4:7], v[8:11], v[120:123], 0
	v_mfma_f32_16x16x32_bf16 v[144:147], v[8:11], v[60:63], 0
	v_mfma_f32_16x16x32_bf16 v[152:155], v[8:11], v[104:107], 0
	v_mfma_f32_16x16x32_bf16 v[160:163], v[8:11], v[112:115], 0
	v_mfma_f32_16x16x32_bf16 v[4:7], v[12:15], v[124:127], v[4:7]
	v_mfma_f32_16x16x32_bf16 v[144:147], v[12:15], v[100:103], v[144:147]
	v_mfma_f32_16x16x32_bf16 v[152:155], v[12:15], v[108:111], v[152:155]
	v_mfma_f32_16x16x32_bf16 v[160:163], v[12:15], v[116:119], v[160:163]
	v_mfma_f32_16x16x32_bf16 v[8:11], v[16:19], v[60:63], 0
	v_mfma_f32_16x16x32_bf16 v[12:15], v[24:27], v[60:63], 0
	v_mfma_f32_16x16x32_bf16 v[8:11], v[20:23], v[100:103], v[8:11]
	v_mfma_f32_16x16x32_bf16 v[12:15], v[28:31], v[100:103], v[12:15]
	v_mfma_f32_16x16x32_bf16 v[60:63], v[16:19], v[104:107], 0
	v_mfma_f32_16x16x32_bf16 v[100:103], v[24:27], v[104:107], 0
	v_mfma_f32_16x16x32_bf16 v[104:107], v[16:19], v[112:115], 0
	v_mfma_f32_16x16x32_bf16 v[16:19], v[16:19], v[120:123], 0
	v_mfma_f32_16x16x32_bf16 v[60:63], v[20:23], v[108:111], v[60:63]
	v_mfma_f32_16x16x32_bf16 v[100:103], v[28:31], v[108:111], v[100:103]
	v_mfma_f32_16x16x32_bf16 v[104:107], v[20:23], v[116:119], v[104:107]
	v_mfma_f32_16x16x32_bf16 v[108:111], v[24:27], v[112:115], 0
	v_mfma_f32_16x16x32_bf16 v[16:19], v[20:23], v[124:127], v[16:19]
	v_mfma_f32_16x16x32_bf16 v[20:23], v[24:27], v[120:123], 0
	v_mfma_f32_16x16x32_bf16 v[108:111], v[28:31], v[116:119], v[108:111]
	v_mfma_f32_16x16x32_bf16 v[20:23], v[28:31], v[124:127], v[20:23]
	s_setprio 0
	s_barrier
	s_add_i32 s89, 0, 0x18000
	s_add_i32 s90, 0, 0x1c000
	v_add_u32_e32 v220, s89, v166
	v_add_u32_e32 v221, s90, v166
	ds_read_b128 v[24:27], v220
	ds_read_b128 v[28:31], v220 offset:1024
	ds_read_b128 v[112:115], v220 offset:2048
	ds_read_b128 v[116:119], v220 offset:3072
	ds_read_b128 v[120:123], v221
	ds_read_b128 v[124:127], v221 offset:1024
	ds_read_b128 v[172:175], v221 offset:2048
	ds_read_b128 v[176:179], v221 offset:3072
	s_add_u32 s4, s12, 0x80100
	s_addc_u32 s5, s13, 0
	s_mov_b32 m0, s25
	v_lshl_add_u64 v[218:219], s[4:5], 0, v[138:139]
	ds_read_b128 v[180:183], v170 offset:32768
	ds_read_b128 v[184:187], v170 offset:33792
	ds_read_b128 v[188:191], v170 offset:34816
	s_waitcnt vmcnt(0)
	ds_read_b128 v[192:195], v170 offset:35840
	ds_read_b128 v[196:199], v170 offset:36864
	ds_read_b128 v[200:203], v170 offset:37888
	ds_read_b128 v[204:207], v170 offset:38912
	ds_read_b128 v[208:211], v170 offset:39936
	global_load_lds_dwordx4 v[218:219], off
	v_lshl_add_u64 v[218:219], s[4:5], 0, v[134:135]
	s_mov_b32 m0, s33
	s_nop 0
	global_load_lds_dwordx4 v[218:219], off
	s_waitcnt vmcnt(8)
	s_waitcnt lgkmcnt(0)
	s_barrier
	s_setprio 1
	v_mfma_f32_16x16x32_bf16 v[64:67], v[24:27], v[180:183], v[64:67]
	v_mfma_f32_16x16x32_bf16 v[68:71], v[112:115], v[180:183], v[68:71]
	v_mfma_f32_16x16x32_bf16 v[72:75], v[24:27], v[188:191], v[72:75]
	v_mfma_f32_16x16x32_bf16 v[76:79], v[112:115], v[188:191], v[76:79]
	v_mfma_f32_16x16x32_bf16 v[80:83], v[24:27], v[196:199], v[80:83]
	v_mfma_f32_16x16x32_bf16 v[84:87], v[112:115], v[196:199], v[84:87]
	v_mfma_f32_16x16x32_bf16 v[88:91], v[24:27], v[204:207], v[88:91]
	v_mfma_f32_16x16x32_bf16 v[92:95], v[112:115], v[204:207], v[92:95]
	v_mfma_f32_16x16x32_bf16 v[64:67], v[28:31], v[184:187], v[64:67]
	v_mfma_f32_16x16x32_bf16 v[68:71], v[116:119], v[184:187], v[68:71]
	v_mfma_f32_16x16x32_bf16 v[72:75], v[28:31], v[192:195], v[72:75]
	v_mfma_f32_16x16x32_bf16 v[76:79], v[116:119], v[192:195], v[76:79]
	v_mfma_f32_16x16x32_bf16 v[80:83], v[28:31], v[200:203], v[80:83]
	v_mfma_f32_16x16x32_bf16 v[84:87], v[116:119], v[200:203], v[84:87]
	v_mfma_f32_16x16x32_bf16 v[88:91], v[28:31], v[208:211], v[88:91]
	v_mfma_f32_16x16x32_bf16 v[92:95], v[116:119], v[208:211], v[92:95]
	v_mfma_f32_16x16x32_bf16 v[96:99], v[120:123], v[180:183], v[96:99]
	v_mfma_f32_16x16x32_bf16 v[32:35], v[172:175], v[180:183], v[32:35]
	v_mfma_f32_16x16x32_bf16 v[36:39], v[120:123], v[188:191], v[36:39]
	v_mfma_f32_16x16x32_bf16 v[40:43], v[172:175], v[188:191], v[40:43]
	v_mfma_f32_16x16x32_bf16 v[44:47], v[120:123], v[196:199], v[44:47]
	v_mfma_f32_16x16x32_bf16 v[48:51], v[172:175], v[196:199], v[48:51]
	v_mfma_f32_16x16x32_bf16 v[52:55], v[120:123], v[204:207], v[52:55]
	v_mfma_f32_16x16x32_bf16 v[56:59], v[172:175], v[204:207], v[56:59]
	v_mfma_f32_16x16x32_bf16 v[96:99], v[124:127], v[184:187], v[96:99]
	v_mfma_f32_16x16x32_bf16 v[32:35], v[176:179], v[184:187], v[32:35]
	v_mfma_f32_16x16x32_bf16 v[36:39], v[124:127], v[192:195], v[36:39]
	v_mfma_f32_16x16x32_bf16 v[40:43], v[176:179], v[192:195], v[40:43]
	v_mfma_f32_16x16x32_bf16 v[44:47], v[124:127], v[200:203], v[44:47]
	v_mfma_f32_16x16x32_bf16 v[48:51], v[176:179], v[200:203], v[48:51]
	v_mfma_f32_16x16x32_bf16 v[52:55], v[124:127], v[208:211], v[52:55]
	v_mfma_f32_16x16x32_bf16 v[56:59], v[176:179], v[208:211], v[56:59]
	s_setprio 0
	s_barrier
; #define PG8_STAGE(bufoff, gbase, voff) do { _Pragma("unroll") for (int _i = 0; _i < 2; ++_i) \
;         __builtin_amdgcn_global_load_lds((const unsigned*)((const char*)(gbase) + (voff)[_i]), (PG8_LAS unsigned*)(lds + (bufoff) + ldsw + _i * 8192), 16, 0, 0); } while (0)
; #define PG8_LDA(dst, b, h) do { _Pragma("unroll") for (int m = 0; m < 4; ++m) _Pragma("unroll") for (int k = 0; k < 2; ++k) dst[m][k] = *(const PG8_LAS bf16x8*)(lds + PG8_SA(b, h) + aoff + m * 2048 + k * 1024); } while (0)
; #define PG8_LDB(dst, b, h) do { _Pragma("unroll") for (int n = 0; n < 2; ++n) _Pragma("unroll") for (int k = 0; k < 2; ++k) dst[n][k] = *(const PG8_LAS bf16x8*)(lds + PG8_SB(b, h) + boff + n * 2048 + k * 1024); } while (0)
; #define PG8_MMA(ai, bj, At, Bt) do { __builtin_amdgcn_s_setprio(1); _Pragma("unroll") for (int m = 0; m < 4; ++m) _Pragma("unroll") for (int n = 0; n < 2; ++n) _Pragma("unroll") for (int k = 0; k < 2; ++k) \
;         acc[ai][bj][m][n] = __builtin_amdgcn_mfma_f32_16x16x32_bf16(Bt[n][k], At[m][k], acc[ai][bj][m][n], 0, 0, 0); __builtin_amdgcn_s_setprio(0); } while (0)
; #define PG8_WAIT_V(n) asm volatile("s_waitcnt vmcnt(" #n ")" ::: "memory")
; #define PG8_WAIT_L(n) asm volatile("s_waitcnt lgkmcnt(" #n ")" ::: "memory")
; #define PG8_BAR __builtin_amdgcn_s_barrier()
; #define PG8_SCHED __builtin_amdgcn_sched_barrier(0)
; template <class Epi, class Sched, bool ALIGN_EPI = false, bool SP2 = false>
; __device__ __forceinline__ void gemm_phase(PG8_LAS unsigned char* lds, const Gemm g, const Sched& S, const Epi& E) {
;     ...
;             PG8_LDB(B0, 0, 0); PG8_LDB(B1, 0, 1); PG8_SCHED; PG8_LDA(At, 0, 0); PG8_STAGE(PG8_SA(1, 1), a1 + hstepA, voffA);
;             PG8_WAIT_V(8); PG8_WAIT_L(0); PG8_BAR; PG8_MMA(0, 0, At, B0); PG8_MMA(0, 1, At, B1); PG8_BAR; PG8_SCHED;
;     ...
;             PG8_LDA(At, 1, 1); PG8_STAGE(PG8_SB(1, 0), b3, voffB); PG8_STAGE(PG8_SB(1, 1), b3 + hstepB, voffB); PG8_STAGE(PG8_SA(1, 0), a3, voffA);
;             PG8_WAIT_V(8); PG8_WAIT_L(0); PG8_BAR; PG8_MMA(1, 0, At, B0); PG8_MMA(1, 1, At, B1); PG8_BAR; PG8_SCHED;
	s_add_i32 s89, s89, s47
	s_add_i32 s87, s89, 0x2000
	v_lshl_add_u64 v[164:165], v[164:165], 0, s[38:39]
	s_mov_b32 m0, s89
	s_add_u32 s4, s14, 0x10180
	ds_read_b128 v[180:183], v170 offset:49152
	ds_read_b128 v[184:187], v170 offset:50176
	ds_read_b128 v[188:191], v170 offset:51200
	ds_read_b128 v[192:195], v170 offset:52224
	ds_read_b128 v[196:199], v170 offset:53248
	ds_read_b128 v[200:203], v170 offset:54272
	ds_read_b128 v[204:207], v170 offset:55296
	ds_read_b128 v[208:211], v170 offset:56320
	global_load_lds_dwordx4 v[164:165], off
	v_lshl_add_u64 v[164:165], v[212:213], 0, s[38:39]
	s_mov_b32 m0, s87
	s_addc_u32 s5, s15, 0
	s_add_i32 s14, s90, s47
	global_load_lds_dwordx4 v[164:165], off
	v_lshl_add_u64 v[164:165], s[4:5], 0, v[136:137]
	s_mov_b32 m0, s14
	s_add_i32 s15, s14, 0x2000
	global_load_lds_dwordx4 v[164:165], off
	v_lshl_add_u64 v[164:165], s[4:5], 0, v[132:133]
	s_mov_b32 m0, s15
	s_nop 0
	global_load_lds_dwordx4 v[164:165], off
	v_lshl_add_u64 v[164:165], v[214:215], 0, s[38:39]
	s_mov_b32 m0, s41
	s_nop 0
	global_load_lds_dwordx4 v[164:165], off
	v_lshl_add_u64 v[164:165], v[216:217], 0, s[38:39]
	s_mov_b32 m0, s44
	s_nop 0
	global_load_lds_dwordx4 v[164:165], off
	s_waitcnt vmcnt(8)
	s_waitcnt lgkmcnt(0)
	s_barrier
	s_setprio 1
	v_mfma_f32_16x16x32_bf16 v[0:3], v[24:27], v[204:207], v[0:3]
	v_mfma_f32_16x16x32_bf16 v[4:7], v[112:115], v[204:207], v[4:7]
	v_mfma_f32_16x16x32_bf16 v[128:131], v[24:27], v[180:183], v[128:131]
	v_mfma_f32_16x16x32_bf16 v[144:147], v[112:115], v[180:183], v[144:147]
	v_mfma_f32_16x16x32_bf16 v[148:151], v[24:27], v[188:191], v[148:151]
	v_mfma_f32_16x16x32_bf16 v[152:155], v[112:115], v[188:191], v[152:155]
	v_mfma_f32_16x16x32_bf16 v[156:159], v[24:27], v[196:199], v[156:159]
	v_mfma_f32_16x16x32_bf16 v[160:163], v[112:115], v[196:199], v[160:163]
	v_mfma_f32_16x16x32_bf16 v[0:3], v[28:31], v[208:211], v[0:3]
	v_mfma_f32_16x16x32_bf16 v[4:7], v[116:119], v[208:211], v[4:7]
	v_mfma_f32_16x16x32_bf16 v[128:131], v[28:31], v[184:187], v[128:131]
	v_mfma_f32_16x16x32_bf16 v[144:147], v[116:119], v[184:187], v[144:147]
	v_mfma_f32_16x16x32_bf16 v[148:151], v[28:31], v[192:195], v[148:151]
	v_mfma_f32_16x16x32_bf16 v[152:155], v[116:119], v[192:195], v[152:155]
	v_mfma_f32_16x16x32_bf16 v[156:159], v[28:31], v[200:203], v[156:159]
	v_mfma_f32_16x16x32_bf16 v[160:163], v[116:119], v[200:203], v[160:163]
	v_mfma_f32_16x16x32_bf16 v[8:11], v[120:123], v[180:183], v[8:11]
	v_mfma_f32_16x16x32_bf16 v[12:15], v[172:175], v[180:183], v[12:15]
	v_mfma_f32_16x16x32_bf16 v[24:27], v[120:123], v[188:191], v[60:63]
	v_mfma_f32_16x16x32_bf16 v[28:31], v[172:175], v[188:191], v[100:103]
	v_mfma_f32_16x16x32_bf16 v[60:63], v[120:123], v[196:199], v[104:107]
	v_mfma_f32_16x16x32_bf16 v[100:103], v[172:175], v[196:199], v[108:111]
	v_mfma_f32_16x16x32_bf16 v[16:19], v[120:123], v[204:207], v[16:19]
	v_mfma_f32_16x16x32_bf16 v[20:23], v[172:175], v[204:207], v[20:23]
	v_mfma_f32_16x16x32_bf16 v[8:11], v[124:127], v[184:187], v[8:11]
	v_mfma_f32_16x16x32_bf16 v[12:15], v[176:179], v[184:187], v[12:15]
	v_mfma_f32_16x16x32_bf16 v[24:27], v[124:127], v[192:195], v[24:27]
	v_mfma_f32_16x16x32_bf16 v[28:31], v[176:179], v[192:195], v[28:31]
	v_mfma_f32_16x16x32_bf16 v[60:63], v[124:127], v[200:203], v[60:63]
	v_mfma_f32_16x16x32_bf16 v[100:103], v[176:179], v[200:203], v[100:103]
	v_mfma_f32_16x16x32_bf16 v[16:19], v[124:127], v[208:211], v[16:19]
	v_mfma_f32_16x16x32_bf16 v[20:23], v[176:179], v[208:211], v[20:23]
	s_setprio 0
	s_barrier
	ds_read_b128 v[104:107], v168
	ds_read_b128 v[108:111], v168 offset:1024
	ds_read_b128 v[112:115], v168 offset:2048
	ds_read_b128 v[116:119], v168 offset:3072
	ds_read_b128 v[120:123], v169
	ds_read_b128 v[124:127], v169 offset:1024
	ds_read_b128 v[172:175], v169 offset:2048
	ds_read_b128 v[176:179], v169 offset:3072
	s_add_u32 s4, s12, 0x80180
	s_addc_u32 s5, s13, 0
	s_mov_b32 m0, s88
	v_lshl_add_u64 v[164:165], s[4:5], 0, v[138:139]
	ds_read_b128 v[180:183], v170
	ds_read_b128 v[184:187], v170 offset:1024
	ds_read_b128 v[188:191], v170 offset:2048
	ds_read_b128 v[192:195], v170 offset:3072
	ds_read_b128 v[196:199], v170 offset:4096
	ds_read_b128 v[200:203], v170 offset:5120
	ds_read_b128 v[204:207], v170 offset:6144
	ds_read_b128 v[208:211], v170 offset:7168
	global_load_lds_dwordx4 v[164:165], off
	v_lshl_add_u64 v[164:165], s[4:5], 0, v[134:135]
	s_mov_b32 m0, s11
	s_nop 0
	global_load_lds_dwordx4 v[164:165], off
	s_waitcnt vmcnt(8)
	s_waitcnt lgkmcnt(0)
	s_barrier
	s_setprio 1
	v_mfma_f32_16x16x32_bf16 v[88:91], v[104:107], v[204:207], v[88:91]
	v_mfma_f32_16x16x32_bf16 v[64:67], v[104:107], v[180:183], v[64:67]
	v_mfma_f32_16x16x32_bf16 v[68:71], v[112:115], v[180:183], v[68:71]
	v_mfma_f32_16x16x32_bf16 v[72:75], v[104:107], v[188:191], v[72:75]
	v_mfma_f32_16x16x32_bf16 v[76:79], v[112:115], v[188:191], v[76:79]
	v_mfma_f32_16x16x32_bf16 v[80:83], v[104:107], v[196:199], v[80:83]
	v_mfma_f32_16x16x32_bf16 v[84:87], v[112:115], v[196:199], v[84:87]
	v_mfma_f32_16x16x32_bf16 v[212:215], v[108:111], v[208:211], v[88:91]
	v_mfma_f32_16x16x32_bf16 v[88:91], v[112:115], v[204:207], v[92:95]
	v_mfma_f32_16x16x32_bf16 v[64:67], v[108:111], v[184:187], v[64:67]
	v_mfma_f32_16x16x32_bf16 v[68:71], v[116:119], v[184:187], v[68:71]
	v_mfma_f32_16x16x32_bf16 v[72:75], v[108:111], v[192:195], v[72:75]
	v_mfma_f32_16x16x32_bf16 v[76:79], v[116:119], v[192:195], v[76:79]
	v_mfma_f32_16x16x32_bf16 v[80:83], v[108:111], v[200:203], v[80:83]
	v_mfma_f32_16x16x32_bf16 v[84:87], v[116:119], v[200:203], v[84:87]
	v_mfma_f32_16x16x32_bf16 v[92:95], v[116:119], v[208:211], v[88:91]
	v_mfma_f32_16x16x32_bf16 v[32:35], v[172:175], v[180:183], v[32:35]
	v_mfma_f32_16x16x32_bf16 v[36:39], v[120:123], v[188:191], v[36:39]
	v_mfma_f32_16x16x32_bf16 v[40:43], v[172:175], v[188:191], v[40:43]
	v_mfma_f32_16x16x32_bf16 v[44:47], v[120:123], v[196:199], v[44:47]
	v_mfma_f32_16x16x32_bf16 v[48:51], v[172:175], v[196:199], v[48:51]
	v_mfma_f32_16x16x32_bf16 v[52:55], v[120:123], v[204:207], v[52:55]
	v_mfma_f32_16x16x32_bf16 v[56:59], v[172:175], v[204:207], v[56:59]
	v_mfma_f32_16x16x32_bf16 v[88:91], v[120:123], v[180:183], v[96:99]
	v_mfma_f32_16x16x32_bf16 v[32:35], v[176:179], v[184:187], v[32:35]
	v_mfma_f32_16x16x32_bf16 v[36:39], v[124:127], v[192:195], v[36:39]
	v_mfma_f32_16x16x32_bf16 v[40:43], v[176:179], v[192:195], v[40:43]
	v_mfma_f32_16x16x32_bf16 v[44:47], v[124:127], v[200:203], v[44:47]
	v_mfma_f32_16x16x32_bf16 v[48:51], v[176:179], v[200:203], v[48:51]
	v_mfma_f32_16x16x32_bf16 v[52:55], v[124:127], v[208:211], v[52:55]
	v_mfma_f32_16x16x32_bf16 v[56:59], v[176:179], v[208:211], v[56:59]
	v_mfma_f32_16x16x32_bf16 v[216:219], v[124:127], v[184:187], v[88:91]
	s_setprio 0
	s_barrier
; #define PG8_STAGE(bufoff, gbase, voff) do { _Pragma("unroll") for (int _i = 0; _i < 2; ++_i) \
;         __builtin_amdgcn_global_load_lds((const unsigned*)((const char*)(gbase) + (voff)[_i]), (PG8_LAS unsigned*)(lds + (bufoff) + ldsw + _i * 8192), 16, 0, 0); } while (0)
; #define PG8_LDA(dst, b, h) do { _Pragma("unroll") for (int m = 0; m < 4; ++m) _Pragma("unroll") for (int k = 0; k < 2; ++k) dst[m][k] = *(const PG8_LAS bf16x8*)(lds + PG8_SA(b, h) + aoff + m * 2048 + k * 1024); } while (0)
; #define PG8_LDB(dst, b, h) do { _Pragma("unroll") for (int n = 0; n < 2; ++n) _Pragma("unroll") for (int k = 0; k < 2; ++k) dst[n][k] = *(const PG8_LAS bf16x8*)(lds + PG8_SB(b, h) + boff + n * 2048 + k * 1024); } while (0)
; #define PG8_MMA(ai, bj, At, Bt) do { __builtin_amdgcn_s_setprio(1); _Pragma("unroll") for (int m = 0; m < 4; ++m) _Pragma("unroll") for (int n = 0; n < 2; ++n) _Pragma("unroll") for (int k = 0; k < 2; ++k) \
;         acc[ai][bj][m][n] = __builtin_amdgcn_mfma_f32_16x16x32_bf16(Bt[n][k], At[m][k], acc[ai][bj][m][n], 0, 0, 0); __builtin_amdgcn_s_setprio(0); } while (0)
; #define PG8_WAIT_V(n) asm volatile("s_waitcnt vmcnt(" #n ")" ::: "memory")
; #define PG8_WAIT_L(n) asm volatile("s_waitcnt lgkmcnt(" #n ")" ::: "memory")
; #define PG8_BAR __builtin_amdgcn_s_barrier()
; #define PG8_SCHED __builtin_amdgcn_sched_barrier(0)
; template <class Epi, class Sched, bool ALIGN_EPI = false, bool SP2 = false>
; __device__ __forceinline__ void gemm_phase(PG8_LAS unsigned char* lds, const Gemm g, const Sched& S, const Epi& E) {
;     ...
;             PG8_LDA(At, 0, 1); PG8_STAGE(PG8_SB(0, 0), b2, voffB); PG8_STAGE(PG8_SB(0, 1), b2 + hstepB, voffB); PG8_STAGE(PG8_SA(0, 0), a2, voffA);
;             PG8_WAIT_V(8); PG8_WAIT_L(0); PG8_BAR; PG8_MMA(1, 0, At, B0); PG8_MMA(1, 1, At, B1); PG8_BAR; PG8_SCHED;
;             PG8_LDB(B0, 1, 0); PG8_LDB(B1, 1, 1); PG8_SCHED; PG8_LDA(At, 1, 0); PG8_STAGE(PG8_SA(0, 1), a2 + hstepA, voffA);
	s_mov_b32 m0, s86
	v_lshl_add_u64 v[164:165], s[68:69], 0, v[136:137]
	s_add_u32 s4, s68, 0x10000
	ds_read_b128 v[88:91], v170 offset:16384
	ds_read_b128 v[96:99], v170 offset:17408
	ds_read_b128 v[180:183], v170 offset:18432
	ds_read_b128 v[184:187], v170 offset:19456
	ds_read_b128 v[188:191], v170 offset:20480
	ds_read_b128 v[192:195], v170 offset:21504
	ds_read_b128 v[196:199], v170 offset:22528
	ds_read_b128 v[200:203], v170 offset:23552
	global_load_lds_dwordx4 v[164:165], off
	v_lshl_add_u64 v[244:245], s[68:69], 0, v[132:133]
	s_mov_b32 m0, s61
	s_addc_u32 s5, s69, 0
	global_load_lds_dwordx4 v[244:245], off
	v_lshl_add_u64 v[204:205], s[4:5], 0, v[136:137]
	s_mov_b32 m0, s63
	v_lshl_add_u64 v[246:247], s[70:71], 0, v[138:139]
	global_load_lds_dwordx4 v[204:205], off
	v_lshl_add_u64 v[204:205], s[4:5], 0, v[132:133]
	s_mov_b32 m0, s85
	v_lshl_add_u64 v[248:249], s[70:71], 0, v[134:135]
	global_load_lds_dwordx4 v[204:205], off
	s_mov_b32 m0, s3
	s_nop 0
	global_load_lds_dwordx4 v[246:247], off
	s_mov_b32 m0, s24
	s_nop 0
	global_load_lds_dwordx4 v[248:249], off
	s_waitcnt vmcnt(8)
	s_waitcnt lgkmcnt(0)
	s_barrier
	s_setprio 1
	v_mfma_f32_16x16x32_bf16 v[0:3], v[104:107], v[196:199], v[0:3]
	v_mfma_f32_16x16x32_bf16 v[4:7], v[112:115], v[196:199], v[4:7]
	v_mfma_f32_16x16x32_bf16 v[128:131], v[104:107], v[88:91], v[128:131]
	v_mfma_f32_16x16x32_bf16 v[144:147], v[112:115], v[88:91], v[144:147]
	v_mfma_f32_16x16x32_bf16 v[148:151], v[104:107], v[180:183], v[148:151]
	v_mfma_f32_16x16x32_bf16 v[152:155], v[112:115], v[180:183], v[152:155]
	v_mfma_f32_16x16x32_bf16 v[156:159], v[104:107], v[188:191], v[156:159]
	v_mfma_f32_16x16x32_bf16 v[160:163], v[112:115], v[188:191], v[160:163]
	v_mfma_f32_16x16x32_bf16 v[0:3], v[108:111], v[200:203], v[0:3]
	v_mfma_f32_16x16x32_bf16 v[4:7], v[116:119], v[200:203], v[4:7]
	v_mfma_f32_16x16x32_bf16 v[128:131], v[108:111], v[96:99], v[128:131]
	v_mfma_f32_16x16x32_bf16 v[144:147], v[116:119], v[96:99], v[144:147]
	v_mfma_f32_16x16x32_bf16 v[148:151], v[108:111], v[184:187], v[148:151]
	v_mfma_f32_16x16x32_bf16 v[152:155], v[116:119], v[184:187], v[152:155]
	v_mfma_f32_16x16x32_bf16 v[156:159], v[108:111], v[192:195], v[156:159]
	v_mfma_f32_16x16x32_bf16 v[160:163], v[116:119], v[192:195], v[160:163]
	v_mfma_f32_16x16x32_bf16 v[8:11], v[120:123], v[88:91], v[8:11]
	v_mfma_f32_16x16x32_bf16 v[204:207], v[124:127], v[96:99], v[8:11]
	v_mfma_f32_16x16x32_bf16 v[8:11], v[172:175], v[88:91], v[12:15]
	v_mfma_f32_16x16x32_bf16 v[12:15], v[176:179], v[96:99], v[8:11]
	v_mfma_f32_16x16x32_bf16 v[8:11], v[120:123], v[180:183], v[24:27]
	v_mfma_f32_16x16x32_bf16 v[208:211], v[124:127], v[184:187], v[8:11]
	v_mfma_f32_16x16x32_bf16 v[8:11], v[172:175], v[180:183], v[28:31]
	v_mfma_f32_16x16x32_bf16 v[28:31], v[176:179], v[184:187], v[8:11]
	v_mfma_f32_16x16x32_bf16 v[8:11], v[120:123], v[188:191], v[60:63]
	v_mfma_f32_16x16x32_bf16 v[180:183], v[124:127], v[192:195], v[8:11]
	v_mfma_f32_16x16x32_bf16 v[8:11], v[172:175], v[188:191], v[100:103]
	v_mfma_f32_16x16x32_bf16 v[184:187], v[176:179], v[192:195], v[8:11]
	v_mfma_f32_16x16x32_bf16 v[8:11], v[120:123], v[196:199], v[16:19]
	v_mfma_f32_16x16x32_bf16 v[188:191], v[124:127], v[200:203], v[8:11]
	v_mfma_f32_16x16x32_bf16 v[8:11], v[172:175], v[196:199], v[20:23]
	v_mfma_f32_16x16x32_bf16 v[172:175], v[176:179], v[200:203], v[8:11]
	s_setprio 0
	s_barrier
	s_nop 4
	ds_read_b128 v[8:11], v220
	ds_read_b128 v[20:23], v220 offset:1024
	ds_read_b128 v[60:63], v220 offset:2048
	ds_read_b128 v[176:179], v220 offset:3072
	ds_read_b128 v[192:195], v221
	ds_read_b128 v[196:199], v221 offset:1024
	ds_read_b128 v[200:203], v221 offset:2048
	ds_read_b128 v[220:223], v221 offset:3072
	s_add_u32 s4, s70, 0x80000
	s_addc_u32 s5, s71, 0
	s_mov_b32 m0, s25
	v_lshl_add_u64 v[88:89], s[4:5], 0, v[138:139]
	ds_read_b128 v[16:19], v170 offset:32768
	ds_read_b128 v[24:27], v170 offset:33792
	ds_read_b128 v[100:103], v170 offset:34816
	ds_read_b128 v[224:227], v170 offset:35840
	ds_read_b128 v[228:231], v170 offset:36864
	ds_read_b128 v[232:235], v170 offset:37888
	ds_read_b128 v[236:239], v170 offset:38912
	ds_read_b128 v[240:243], v170 offset:39936
	global_load_lds_dwordx4 v[88:89], off
	v_lshl_add_u64 v[88:89], s[4:5], 0, v[134:135]
	s_mov_b32 m0, s33
	s_nop 0
	global_load_lds_dwordx4 v[88:89], off
	s_waitcnt vmcnt(8)
	s_waitcnt lgkmcnt(0)
	s_barrier
; #define PG8_STAGE(bufoff, gbase, voff) do { _Pragma("unroll") for (int _i = 0; _i < 2; ++_i) \
;         __builtin_amdgcn_global_load_lds((const unsigned*)((const char*)(gbase) + (voff)[_i]), (PG8_LAS unsigned*)(lds + (bufoff) + ldsw + _i * 8192), 16, 0, 0); } while (0)
; #define PG8_LDA(dst, b, h) do { _Pragma("unroll") for (int m = 0; m < 4; ++m) _Pragma("unroll") for (int k = 0; k < 2; ++k) dst[m][k] = *(const PG8_LAS bf16x8*)(lds + PG8_SA(b, h) + aoff + m * 2048 + k * 1024); } while (0)
; #define PG8_MMA(ai, bj, At, Bt) do { __builtin_amdgcn_s_setprio(1); _Pragma("unroll") for (int m = 0; m < 4; ++m) _Pragma("unroll") for (int n = 0; n < 2; ++n) _Pragma("unroll") for (int k = 0; k < 2; ++k) \
;         acc[ai][bj][m][n] = __builtin_amdgcn_mfma_f32_16x16x32_bf16(Bt[n][k], At[m][k], acc[ai][bj][m][n], 0, 0, 0); __builtin_amdgcn_s_setprio(0); } while (0)
; #define PG8_WAIT_V(n) asm volatile("s_waitcnt vmcnt(" #n ")" ::: "memory")
; #define PG8_WAIT_L(n) asm volatile("s_waitcnt lgkmcnt(" #n ")" ::: "memory")
; #define PG8_BAR __builtin_amdgcn_s_barrier()
; #define PG8_SCHED __builtin_amdgcn_sched_barrier(0)
; template <class Epi, class Sched, bool ALIGN_EPI = false, bool SP2 = false>
; __device__ __forceinline__ void gemm_phase(PG8_LAS unsigned char* lds, const Gemm g, const Sched& S, const Epi& E) {
;     ...
;             PG8_WAIT_V(8); PG8_WAIT_L(0); PG8_BAR; PG8_MMA(0, 0, At, B0); PG8_MMA(0, 1, At, B1); PG8_BAR; PG8_SCHED;
;             PG8_LDA(At, 1, 1); PG8_STAGE(PG8_SB(1, 0), b3, voffB); PG8_STAGE(PG8_SB(1, 1), b3 + hstepB, voffB); PG8_STAGE(PG8_SA(1, 0), a3, voffA);
;             PG8_WAIT_V(8); PG8_WAIT_L(0); PG8_BAR; PG8_MMA(1, 0, At, B0); PG8_MMA(1, 1, At, B1); PG8_BAR; PG8_SCHED;
;     ...
;         if constexpr (ALIGN_EPI) { if (wr == 0) PG8_BAR; }
	s_setprio 1
	v_mfma_f32_16x16x32_bf16 v[64:67], v[8:11], v[16:19], v[64:67]
	v_mfma_f32_16x16x32_bf16 v[120:123], v[20:23], v[24:27], v[64:67]
	v_mfma_f32_16x16x32_bf16 v[64:67], v[60:63], v[16:19], v[68:71]
	v_mfma_f32_16x16x32_bf16 v[112:115], v[176:179], v[24:27], v[64:67]
	v_mfma_f32_16x16x32_bf16 v[64:67], v[8:11], v[100:103], v[72:75]
	v_mfma_f32_16x16x32_bf16 v[104:107], v[20:23], v[224:227], v[64:67]
	v_mfma_f32_16x16x32_bf16 v[64:67], v[60:63], v[100:103], v[76:79]
	v_mfma_f32_16x16x32_bf16 v[96:99], v[176:179], v[224:227], v[64:67]
	v_mfma_f32_16x16x32_bf16 v[64:67], v[8:11], v[228:231], v[80:83]
	v_mfma_f32_16x16x32_bf16 v[88:91], v[20:23], v[232:235], v[64:67]
	v_mfma_f32_16x16x32_bf16 v[64:67], v[60:63], v[228:231], v[84:87]
	v_mfma_f32_16x16x32_bf16 v[80:83], v[176:179], v[232:235], v[64:67]
	v_mfma_f32_16x16x32_bf16 v[64:67], v[8:11], v[236:239], v[212:215]
	v_mfma_f32_16x16x32_bf16 v[72:75], v[20:23], v[240:243], v[64:67]
	v_mfma_f32_16x16x32_bf16 v[64:67], v[60:63], v[236:239], v[92:95]
	v_mfma_f32_16x16x32_bf16 v[64:67], v[176:179], v[240:243], v[64:67]
	v_mfma_f32_16x16x32_bf16 v[68:71], v[192:195], v[16:19], v[216:219]
	v_mfma_f32_16x16x32_bf16 v[16:19], v[200:203], v[16:19], v[32:35]
	v_mfma_f32_16x16x32_bf16 v[116:119], v[220:223], v[24:27], v[16:19]
	v_mfma_f32_16x16x32_bf16 v[16:19], v[192:195], v[100:103], v[36:39]
	v_mfma_f32_16x16x32_bf16 v[108:111], v[196:199], v[224:227], v[16:19]
	v_mfma_f32_16x16x32_bf16 v[16:19], v[200:203], v[100:103], v[40:43]
	v_mfma_f32_16x16x32_bf16 v[100:103], v[220:223], v[224:227], v[16:19]
	v_mfma_f32_16x16x32_bf16 v[16:19], v[192:195], v[228:231], v[44:47]
	v_mfma_f32_16x16x32_bf16 v[92:95], v[196:199], v[232:235], v[16:19]
	v_mfma_f32_16x16x32_bf16 v[16:19], v[200:203], v[228:231], v[48:51]
	v_mfma_f32_16x16x32_bf16 v[84:87], v[220:223], v[232:235], v[16:19]
	v_mfma_f32_16x16x32_bf16 v[16:19], v[192:195], v[236:239], v[52:55]
	v_mfma_f32_16x16x32_bf16 v[76:79], v[196:199], v[240:243], v[16:19]
	v_mfma_f32_16x16x32_bf16 v[16:19], v[200:203], v[236:239], v[56:59]
	v_mfma_f32_16x16x32_bf16 v[124:127], v[196:199], v[24:27], v[68:71]
	v_mfma_f32_16x16x32_bf16 v[68:71], v[220:223], v[240:243], v[16:19]
	s_setprio 0
	s_barrier
	s_mov_b32 m0, s89
	s_nop 2
	v_lshl_add_u64 v[16:17], v[164:165], 0, s[30:31]
	s_add_u32 s4, s68, 0x10080
	ds_read_b128 v[36:39], v170 offset:49152
	ds_read_b128 v[44:47], v170 offset:50176
	ds_read_b128 v[212:215], v170 offset:51200
	ds_read_b128 v[216:219], v170 offset:52224
	ds_read_b128 v[224:227], v170 offset:53248
	ds_read_b128 v[228:231], v170 offset:54272
	ds_read_b128 v[232:235], v170 offset:55296
	ds_read_b128 v[236:239], v170 offset:56320
	global_load_lds_dwordx4 v[16:17], off
	v_lshl_add_u64 v[16:17], v[244:245], 0, s[30:31]
	s_mov_b32 m0, s87
	s_addc_u32 s5, s69, 0
	global_load_lds_dwordx4 v[16:17], off
	v_lshl_add_u64 v[16:17], s[4:5], 0, v[136:137]
	s_mov_b32 m0, s14
	s_nop 0
	global_load_lds_dwordx4 v[16:17], off
	v_lshl_add_u64 v[16:17], s[4:5], 0, v[132:133]
	s_mov_b32 m0, s15
	s_nop 0
	global_load_lds_dwordx4 v[16:17], off
	v_lshl_add_u64 v[16:17], v[246:247], 0, s[30:31]
	s_mov_b32 m0, s41
	s_nop 0
	global_load_lds_dwordx4 v[16:17], off
	v_lshl_add_u64 v[16:17], v[248:249], 0, s[30:31]
	s_mov_b32 m0, s44
	s_nop 0
	global_load_lds_dwordx4 v[16:17], off
	s_waitcnt vmcnt(8)
	s_waitcnt lgkmcnt(0)
	s_barrier
	s_setprio 1
	v_mfma_f32_16x16x32_bf16 v[16:19], v[8:11], v[36:39], v[128:131]
	v_mfma_f32_16x16x32_bf16 v[56:59], v[20:23], v[44:47], v[16:19]
	v_mfma_f32_16x16x32_bf16 v[16:19], v[60:63], v[36:39], v[144:147]
	v_mfma_f32_16x16x32_bf16 v[48:51], v[176:179], v[44:47], v[16:19]
	v_mfma_f32_16x16x32_bf16 v[16:19], v[8:11], v[212:215], v[148:151]
	v_mfma_f32_16x16x32_bf16 v[40:43], v[20:23], v[216:219], v[16:19]
	v_mfma_f32_16x16x32_bf16 v[16:19], v[60:63], v[212:215], v[152:155]
	v_mfma_f32_16x16x32_bf16 v[32:35], v[176:179], v[216:219], v[16:19]
	v_mfma_f32_16x16x32_bf16 v[16:19], v[8:11], v[224:227], v[156:159]
	v_mfma_f32_16x16x32_bf16 v[0:3], v[8:11], v[232:235], v[0:3]
	v_mfma_f32_16x16x32_bf16 v[24:27], v[20:23], v[228:231], v[16:19]
	v_mfma_f32_16x16x32_bf16 v[16:19], v[60:63], v[224:227], v[160:163]
	v_mfma_f32_16x16x32_bf16 v[8:11], v[20:23], v[236:239], v[0:3]
	v_mfma_f32_16x16x32_bf16 v[0:3], v[60:63], v[232:235], v[4:7]
	v_mfma_f32_16x16x32_bf16 v[16:19], v[176:179], v[228:231], v[16:19]
	v_mfma_f32_16x16x32_bf16 v[0:3], v[176:179], v[236:239], v[0:3]
	v_mfma_f32_16x16x32_bf16 v[4:7], v[192:195], v[36:39], v[204:207]
	v_mfma_f32_16x16x32_bf16 v[60:63], v[196:199], v[44:47], v[4:7]
	v_mfma_f32_16x16x32_bf16 v[4:7], v[200:203], v[36:39], v[12:15]
	v_mfma_f32_16x16x32_bf16 v[52:55], v[220:223], v[44:47], v[4:7]
	v_mfma_f32_16x16x32_bf16 v[4:7], v[192:195], v[212:215], v[208:211]
	v_mfma_f32_16x16x32_bf16 v[44:47], v[196:199], v[216:219], v[4:7]
	v_mfma_f32_16x16x32_bf16 v[4:7], v[200:203], v[212:215], v[28:31]
	v_mfma_f32_16x16x32_bf16 v[36:39], v[220:223], v[216:219], v[4:7]
	v_mfma_f32_16x16x32_bf16 v[4:7], v[192:195], v[224:227], v[180:183]
	v_mfma_f32_16x16x32_bf16 v[28:31], v[196:199], v[228:231], v[4:7]
	v_mfma_f32_16x16x32_bf16 v[4:7], v[200:203], v[224:227], v[184:187]
	v_mfma_f32_16x16x32_bf16 v[20:23], v[220:223], v[228:231], v[4:7]
	v_mfma_f32_16x16x32_bf16 v[4:7], v[192:195], v[232:235], v[188:191]
	v_mfma_f32_16x16x32_bf16 v[12:15], v[196:199], v[236:239], v[4:7]
	v_mfma_f32_16x16x32_bf16 v[4:7], v[200:203], v[232:235], v[172:175]
	v_mfma_f32_16x16x32_bf16 v[4:7], v[220:223], v[236:239], v[4:7]
	s_setprio 0
	s_barrier
	s_andn2_b64 vcc, exec, s[48:49]
	s_cbranch_vccnz .LBB0_1043
	s_barrier

; #define PG8_STAGE(bufoff, gbase, voff) do { _Pragma("unroll") for (int _i = 0; _i < 2; ++_i) \
;         __builtin_amdgcn_global_load_lds((const unsigned*)((const char*)(gbase) + (voff)[_i]), (PG8_LAS unsigned*)(lds + (bufoff) + ldsw + _i * 8192), 16, 0, 0); } while (0)
; #define PG8_LDA(dst, b, h) do { _Pragma("unroll") for (int m = 0; m < 4; ++m) _Pragma("unroll") for (int k = 0; k < 2; ++k) dst[m][k] = *(const PG8_LAS bf16x8*)(lds + PG8_SA(b, h) + aoff + m * 2048 + k * 1024); } while (0)
; #define PG8_LDB(dst, b, h) do { _Pragma("unroll") for (int n = 0; n < 2; ++n) _Pragma("unroll") for (int k = 0; k < 2; ++k) dst[n][k] = *(const PG8_LAS bf16x8*)(lds + PG8_SB(b, h) + boff + n * 2048 + k * 1024); } while (0)
; #define PG8_MMA(ai, bj, At, Bt) do { __builtin_amdgcn_s_setprio(1); _Pragma("unroll") for (int m = 0; m < 4; ++m) _Pragma("unroll") for (int n = 0; n < 2; ++n) _Pragma("unroll") for (int k = 0; k < 2; ++k) \
;         acc[ai][bj][m][n] = __builtin_amdgcn_mfma_f32_16x16x32_bf16(Bt[n][k], At[m][k], acc[ai][bj][m][n], 0, 0, 0); __builtin_amdgcn_s_setprio(0); } while (0)
; #define PG8_WAIT_V(n) asm volatile("s_waitcnt vmcnt(" #n ")" ::: "memory")
; #define PG8_WAIT_L(n) asm volatile("s_waitcnt lgkmcnt(" #n ")" ::: "memory")
; #define PG8_BAR __builtin_amdgcn_s_barrier()
; #define PG8_SCHED __builtin_amdgcn_sched_barrier(0)
; template <class Epi, class Sched, bool ALIGN_EPI = false, bool SP2 = false>
; __device__ __forceinline__ void gemm_phase(PG8_LAS unsigned char* lds, const Gemm g, const Sched& S, const Epi& E) {
;     ...
;             const bool last = (t == nt - 2);
;             const char* a1 = cA + (size_t)(t + 1) * kstep;
;             const char* a2 = last ? nA : cA + (size_t)(t + 2) * kstep; const char* b2 = last ? nB : cB + (size_t)(t + 2) * kstep;
;             const char* a3 = a2 + kstep; const char* b3 = b2 + kstep;
;             if (last && has_next) S.a_ready(nxt);
;             if constexpr (SP2) {
;             PG8_LDB(B0, 0, 0); PG8_LDB(B1, 0, 1); PG8_SCHED; PG8_LDA(At, 0, 0); PG8_STAGE(PG8_SA(1, 1), a1 + hstepA, voffA);
;             PG8_WAIT_V(8); PG8_WAIT_L(0); PG8_BAR; PG8_MMA(0, 0, At, B0); PG8_MMA(0, 1, At, B1); PG8_BAR; PG8_SCHED;
;             PG8_LDA(At, 0, 1); PG8_STAGE(PG8_SB(0, 0), b2, voffB); PG8_STAGE(PG8_SB(0, 1), b2 + hstepB, voffB); PG8_STAGE(PG8_SA(0, 0), a2, voffA);
.LBB0_1211:
	ds_read_b128 v[144:147], v149
	ds_read_b128 v[152:155], v149 offset:1024
	ds_read_b128 v[156:159], v149 offset:2048
	ds_read_b128 v[160:163], v149 offset:3072
	ds_read_b128 v[168:171], v150
	ds_read_b128 v[172:175], v150 offset:1024
	ds_read_b128 v[176:179], v150 offset:2048
	ds_read_b128 v[180:183], v150 offset:3072
	s_add_u32 s4, s30, 0xfff80080
	s_addc_u32 s5, s31, -1
	s_cmp_eq_u32 s58, 28
	s_cselect_b32 s37, s21, s5
	s_cselect_b32 s36, s29, s4
	s_cselect_b32 s35, s19, s57
	s_cselect_b32 s34, s55, s56
	v_lshl_add_u64 v[164:165], s[30:31], 0, v[136:137]
	s_add_i32 m0, s25, 0xc000
	ds_read_b128 v[184:187], v151
	ds_read_b128 v[188:191], v151 offset:1024
	ds_read_b128 v[192:195], v151 offset:2048
	ds_read_b128 v[196:199], v151 offset:3072
	ds_read_b128 v[200:203], v151 offset:4096
	ds_read_b128 v[204:207], v151 offset:5120
	ds_read_b128 v[208:211], v151 offset:6144
	ds_read_b128 v[212:215], v151 offset:7168
	global_load_lds_dwordx4 v[164:165], off
	v_lshl_add_u64 v[164:165], s[30:31], 0, v[138:139]
	s_add_i32 m0, s25, 0xe000
	s_nop 0
	global_load_lds_dwordx4 v[164:165], off
	s_waitcnt vmcnt(8)
	s_waitcnt lgkmcnt(0)
	s_barrier
	s_setprio 1
	v_mfma_f32_16x16x32_bf16 v[124:127], v[144:147], v[184:187], v[124:127]
	v_mfma_f32_16x16x32_bf16 v[120:123], v[156:159], v[184:187], v[120:123]
	v_mfma_f32_16x16x32_bf16 v[108:111], v[144:147], v[192:195], v[108:111]
	v_mfma_f32_16x16x32_bf16 v[104:107], v[156:159], v[192:195], v[104:107]
	v_mfma_f32_16x16x32_bf16 v[92:95], v[144:147], v[200:203], v[92:95]
	v_mfma_f32_16x16x32_bf16 v[88:91], v[156:159], v[200:203], v[88:91]
	v_mfma_f32_16x16x32_bf16 v[76:79], v[144:147], v[208:211], v[76:79]
	v_mfma_f32_16x16x32_bf16 v[72:75], v[156:159], v[208:211], v[72:75]
	v_mfma_f32_16x16x32_bf16 v[124:127], v[152:155], v[188:191], v[124:127]
	v_mfma_f32_16x16x32_bf16 v[120:123], v[160:163], v[188:191], v[120:123]
	v_mfma_f32_16x16x32_bf16 v[108:111], v[152:155], v[196:199], v[108:111]
	v_mfma_f32_16x16x32_bf16 v[104:107], v[160:163], v[196:199], v[104:107]
	v_mfma_f32_16x16x32_bf16 v[92:95], v[152:155], v[204:207], v[92:95]
	v_mfma_f32_16x16x32_bf16 v[88:91], v[160:163], v[204:207], v[88:91]
	v_mfma_f32_16x16x32_bf16 v[76:79], v[152:155], v[212:215], v[76:79]
	v_mfma_f32_16x16x32_bf16 v[72:75], v[160:163], v[212:215], v[72:75]
	v_mfma_f32_16x16x32_bf16 v[116:119], v[168:171], v[184:187], v[116:119]
	v_mfma_f32_16x16x32_bf16 v[112:115], v[176:179], v[184:187], v[112:115]
	v_mfma_f32_16x16x32_bf16 v[100:103], v[168:171], v[192:195], v[100:103]
	v_mfma_f32_16x16x32_bf16 v[96:99], v[176:179], v[192:195], v[96:99]
	v_mfma_f32_16x16x32_bf16 v[84:87], v[168:171], v[200:203], v[84:87]
	v_mfma_f32_16x16x32_bf16 v[80:83], v[176:179], v[200:203], v[80:83]
	v_mfma_f32_16x16x32_bf16 v[68:71], v[168:171], v[208:211], v[68:71]
	v_mfma_f32_16x16x32_bf16 v[64:67], v[176:179], v[208:211], v[64:67]
	v_mfma_f32_16x16x32_bf16 v[116:119], v[172:175], v[188:191], v[116:119]
	v_mfma_f32_16x16x32_bf16 v[112:115], v[180:183], v[188:191], v[112:115]
	v_mfma_f32_16x16x32_bf16 v[100:103], v[172:175], v[196:199], v[100:103]
	v_mfma_f32_16x16x32_bf16 v[96:99], v[180:183], v[196:199], v[96:99]
	v_mfma_f32_16x16x32_bf16 v[84:87], v[172:175], v[204:207], v[84:87]
	v_mfma_f32_16x16x32_bf16 v[80:83], v[180:183], v[204:207], v[80:83]
	v_mfma_f32_16x16x32_bf16 v[68:71], v[172:175], v[212:215], v[68:71]
	v_mfma_f32_16x16x32_bf16 v[64:67], v[180:183], v[212:215], v[64:67]
	s_setprio 0
	s_barrier
	s_add_i32 s4, s44, s47
	v_lshl_add_u64 v[164:165], s[34:35], 0, v[130:131]
	s_mov_b32 m0, s4
	ds_read_b128 v[184:187], v151 offset:16384
	ds_read_b128 v[188:191], v151 offset:17408
	ds_read_b128 v[192:195], v151 offset:18432
	ds_read_b128 v[196:199], v151 offset:19456
	ds_read_b128 v[200:203], v151 offset:20480
	ds_read_b128 v[204:207], v151 offset:21504
	ds_read_b128 v[208:211], v151 offset:22528
	ds_read_b128 v[212:215], v151 offset:23552
	global_load_lds_dwordx4 v[164:165], off
	s_add_i32 m0, s4, 0x2000
	s_add_u32 s4, s34, 0x80000
	v_lshl_add_u64 v[216:217], s[34:35], 0, v[134:135]
	s_addc_u32 s5, s35, 0
	s_add_i32 s59, s45, s47
	global_load_lds_dwordx4 v[216:217], off
	v_lshl_add_u64 v[218:219], s[4:5], 0, v[130:131]
	s_mov_b32 m0, s59
	v_lshl_add_u64 v[220:221], s[36:37], 0, v[132:133]
	global_load_lds_dwordx4 v[218:219], off
	v_lshl_add_u64 v[218:219], s[4:5], 0, v[134:135]
	s_add_i32 m0, s59, 0x2000
	s_nop 0
	global_load_lds_dwordx4 v[218:219], off
	v_lshl_add_u64 v[218:219], s[36:37], 0, v[128:129]
	s_mov_b32 m0, s25
	s_nop 0
	global_load_lds_dwordx4 v[218:219], off
	s_mov_b32 m0, s33
	s_nop 0
	global_load_lds_dwordx4 v[220:221], off
	s_waitcnt vmcnt(8)
	s_waitcnt lgkmcnt(0)
	s_barrier
; #define PG8_STAGE(bufoff, gbase, voff) do { _Pragma("unroll") for (int _i = 0; _i < 2; ++_i) \
;         __builtin_amdgcn_global_load_lds((const unsigned*)((const char*)(gbase) + (voff)[_i]), (PG8_LAS unsigned*)(lds + (bufoff) + ldsw + _i * 8192), 16, 0, 0); } while (0)
; #define PG8_LDA(dst, b, h) do { _Pragma("unroll") for (int m = 0; m < 4; ++m) _Pragma("unroll") for (int k = 0; k < 2; ++k) dst[m][k] = *(const PG8_LAS bf16x8*)(lds + PG8_SA(b, h) + aoff + m * 2048 + k * 1024); } while (0)
; #define PG8_LDB(dst, b, h) do { _Pragma("unroll") for (int n = 0; n < 2; ++n) _Pragma("unroll") for (int k = 0; k < 2; ++k) dst[n][k] = *(const PG8_LAS bf16x8*)(lds + PG8_SB(b, h) + boff + n * 2048 + k * 1024); } while (0)
; #define PG8_MMA(ai, bj, At, Bt) do { __builtin_amdgcn_s_setprio(1); _Pragma("unroll") for (int m = 0; m < 4; ++m) _Pragma("unroll") for (int n = 0; n < 2; ++n) _Pragma("unroll") for (int k = 0; k < 2; ++k) \
;         acc[ai][bj][m][n] = __builtin_amdgcn_mfma_f32_16x16x32_bf16(Bt[n][k], At[m][k], acc[ai][bj][m][n], 0, 0, 0); __builtin_amdgcn_s_setprio(0); } while (0)
; #define PG8_WAIT_V(n) asm volatile("s_waitcnt vmcnt(" #n ")" ::: "memory")
; #define PG8_WAIT_L(n) asm volatile("s_waitcnt lgkmcnt(" #n ")" ::: "memory")
; #define PG8_BAR __builtin_amdgcn_s_barrier()
; #define PG8_SCHED __builtin_amdgcn_sched_barrier(0)
; template <class Epi, class Sched, bool ALIGN_EPI = false, bool SP2 = false>
; __device__ __forceinline__ void gemm_phase(PG8_LAS unsigned char* lds, const Gemm g, const Sched& S, const Epi& E) {
;     ...
;             PG8_WAIT_V(8); PG8_WAIT_L(0); PG8_BAR; PG8_MMA(1, 0, At, B0); PG8_MMA(1, 1, At, B1); PG8_BAR; PG8_SCHED;
;             PG8_LDB(B0, 1, 0); PG8_LDB(B1, 1, 1); PG8_SCHED; PG8_LDA(At, 1, 0); PG8_STAGE(PG8_SA(0, 1), a2 + hstepA, voffA);
;             PG8_WAIT_V(8); PG8_WAIT_L(0); PG8_BAR; PG8_MMA(0, 0, At, B0); PG8_MMA(0, 1, At, B1); PG8_BAR; PG8_SCHED;
	s_setprio 1
	v_mfma_f32_16x16x32_bf16 v[60:63], v[144:147], v[184:187], v[60:63]
	v_mfma_f32_16x16x32_bf16 v[56:59], v[156:159], v[184:187], v[56:59]
	v_mfma_f32_16x16x32_bf16 v[44:47], v[144:147], v[192:195], v[44:47]
	v_mfma_f32_16x16x32_bf16 v[40:43], v[156:159], v[192:195], v[40:43]
	v_mfma_f32_16x16x32_bf16 v[28:31], v[144:147], v[200:203], v[28:31]
	v_mfma_f32_16x16x32_bf16 v[24:27], v[156:159], v[200:203], v[24:27]
	v_mfma_f32_16x16x32_bf16 v[12:15], v[144:147], v[208:211], v[12:15]
	v_mfma_f32_16x16x32_bf16 v[8:11], v[156:159], v[208:211], v[8:11]
	v_mfma_f32_16x16x32_bf16 v[60:63], v[152:155], v[188:191], v[60:63]
	v_mfma_f32_16x16x32_bf16 v[56:59], v[160:163], v[188:191], v[56:59]
	v_mfma_f32_16x16x32_bf16 v[44:47], v[152:155], v[196:199], v[44:47]
	v_mfma_f32_16x16x32_bf16 v[40:43], v[160:163], v[196:199], v[40:43]
	v_mfma_f32_16x16x32_bf16 v[28:31], v[152:155], v[204:207], v[28:31]
	v_mfma_f32_16x16x32_bf16 v[24:27], v[160:163], v[204:207], v[24:27]
	v_mfma_f32_16x16x32_bf16 v[12:15], v[152:155], v[212:215], v[12:15]
	v_mfma_f32_16x16x32_bf16 v[8:11], v[160:163], v[212:215], v[8:11]
	v_mfma_f32_16x16x32_bf16 v[52:55], v[168:171], v[184:187], v[52:55]
	v_mfma_f32_16x16x32_bf16 v[48:51], v[176:179], v[184:187], v[48:51]
	v_mfma_f32_16x16x32_bf16 v[36:39], v[168:171], v[192:195], v[36:39]
	v_mfma_f32_16x16x32_bf16 v[32:35], v[176:179], v[192:195], v[32:35]
	v_mfma_f32_16x16x32_bf16 v[20:23], v[168:171], v[200:203], v[20:23]
	v_mfma_f32_16x16x32_bf16 v[16:19], v[176:179], v[200:203], v[16:19]
	v_mfma_f32_16x16x32_bf16 v[4:7], v[168:171], v[208:211], v[4:7]
	v_mfma_f32_16x16x32_bf16 v[0:3], v[176:179], v[208:211], v[0:3]
	v_mfma_f32_16x16x32_bf16 v[52:55], v[172:175], v[188:191], v[52:55]
	v_mfma_f32_16x16x32_bf16 v[48:51], v[180:183], v[188:191], v[48:51]
	v_mfma_f32_16x16x32_bf16 v[36:39], v[172:175], v[196:199], v[36:39]
	v_mfma_f32_16x16x32_bf16 v[32:35], v[180:183], v[196:199], v[32:35]
	v_mfma_f32_16x16x32_bf16 v[20:23], v[172:175], v[204:207], v[20:23]
	v_mfma_f32_16x16x32_bf16 v[16:19], v[180:183], v[204:207], v[16:19]
	v_mfma_f32_16x16x32_bf16 v[4:7], v[172:175], v[212:215], v[4:7]
	v_mfma_f32_16x16x32_bf16 v[0:3], v[180:183], v[212:215], v[0:3]
	s_setprio 0
	s_barrier
	s_add_i32 s59, 0, 0x18000
	s_add_i32 s60, 0, 0x1c000
	v_add_u32_e32 v160, s59, v148
	v_add_u32_e32 v166, s60, v148
	ds_read_b128 v[144:147], v160
	ds_read_b128 v[152:155], v160 offset:1024
	ds_read_b128 v[156:159], v160 offset:2048
	ds_read_b128 v[160:163], v160 offset:3072
	ds_read_b128 v[168:171], v166
	ds_read_b128 v[172:175], v166 offset:1024
	ds_read_b128 v[176:179], v166 offset:2048
	ds_read_b128 v[180:183], v166 offset:3072
	s_add_u32 s4, s36, 0x80000
	s_addc_u32 s5, s37, 0
	s_mov_b32 m0, s38
	v_lshl_add_u64 v[222:223], s[4:5], 0, v[128:129]
	ds_read_b128 v[184:187], v151 offset:32768
	ds_read_b128 v[188:191], v151 offset:33792
	ds_read_b128 v[192:195], v151 offset:34816
	ds_read_b128 v[196:199], v151 offset:35840
	ds_read_b128 v[200:203], v151 offset:36864
	ds_read_b128 v[204:207], v151 offset:37888
	ds_read_b128 v[208:211], v151 offset:38912
	ds_read_b128 v[212:215], v151 offset:39936
	global_load_lds_dwordx4 v[222:223], off
	v_lshl_add_u64 v[222:223], s[4:5], 0, v[132:133]
	s_mov_b32 m0, s39
	s_nop 0
	global_load_lds_dwordx4 v[222:223], off
	s_waitcnt vmcnt(8)
	s_waitcnt lgkmcnt(0)
	s_barrier
	s_setprio 1
	v_mfma_f32_16x16x32_bf16 v[124:127], v[144:147], v[184:187], v[124:127]
	v_mfma_f32_16x16x32_bf16 v[120:123], v[156:159], v[184:187], v[120:123]
	v_mfma_f32_16x16x32_bf16 v[108:111], v[144:147], v[192:195], v[108:111]
	v_mfma_f32_16x16x32_bf16 v[104:107], v[156:159], v[192:195], v[104:107]
	v_mfma_f32_16x16x32_bf16 v[92:95], v[144:147], v[200:203], v[92:95]
	v_mfma_f32_16x16x32_bf16 v[88:91], v[156:159], v[200:203], v[88:91]
	v_mfma_f32_16x16x32_bf16 v[76:79], v[144:147], v[208:211], v[76:79]
	v_mfma_f32_16x16x32_bf16 v[72:75], v[156:159], v[208:211], v[72:75]
	v_mfma_f32_16x16x32_bf16 v[124:127], v[152:155], v[188:191], v[124:127]
	v_mfma_f32_16x16x32_bf16 v[120:123], v[160:163], v[188:191], v[120:123]
	v_mfma_f32_16x16x32_bf16 v[108:111], v[152:155], v[196:199], v[108:111]
	v_mfma_f32_16x16x32_bf16 v[104:107], v[160:163], v[196:199], v[104:107]
	v_mfma_f32_16x16x32_bf16 v[92:95], v[152:155], v[204:207], v[92:95]
	v_mfma_f32_16x16x32_bf16 v[88:91], v[160:163], v[204:207], v[88:91]
	v_mfma_f32_16x16x32_bf16 v[76:79], v[152:155], v[212:215], v[76:79]
	v_mfma_f32_16x16x32_bf16 v[72:75], v[160:163], v[212:215], v[72:75]
	v_mfma_f32_16x16x32_bf16 v[116:119], v[168:171], v[184:187], v[116:119]
	v_mfma_f32_16x16x32_bf16 v[112:115], v[176:179], v[184:187], v[112:115]
	v_mfma_f32_16x16x32_bf16 v[100:103], v[168:171], v[192:195], v[100:103]
	v_mfma_f32_16x16x32_bf16 v[96:99], v[176:179], v[192:195], v[96:99]
	v_mfma_f32_16x16x32_bf16 v[84:87], v[168:171], v[200:203], v[84:87]
	v_mfma_f32_16x16x32_bf16 v[80:83], v[176:179], v[200:203], v[80:83]
	v_mfma_f32_16x16x32_bf16 v[68:71], v[168:171], v[208:211], v[68:71]
	v_mfma_f32_16x16x32_bf16 v[64:67], v[176:179], v[208:211], v[64:67]
	v_mfma_f32_16x16x32_bf16 v[116:119], v[172:175], v[188:191], v[116:119]
	v_mfma_f32_16x16x32_bf16 v[112:115], v[180:183], v[188:191], v[112:115]
	v_mfma_f32_16x16x32_bf16 v[100:103], v[172:175], v[196:199], v[100:103]
	v_mfma_f32_16x16x32_bf16 v[96:99], v[180:183], v[196:199], v[96:99]
	v_mfma_f32_16x16x32_bf16 v[84:87], v[172:175], v[204:207], v[84:87]
	v_mfma_f32_16x16x32_bf16 v[80:83], v[180:183], v[204:207], v[80:83]
	v_mfma_f32_16x16x32_bf16 v[68:71], v[172:175], v[212:215], v[68:71]
	v_mfma_f32_16x16x32_bf16 v[64:67], v[180:183], v[212:215], v[64:67]
	s_setprio 0
	s_barrier
; #define PG8_STAGE(bufoff, gbase, voff) do { _Pragma("unroll") for (int _i = 0; _i < 2; ++_i) \
;         __builtin_amdgcn_global_load_lds((const unsigned*)((const char*)(gbase) + (voff)[_i]), (PG8_LAS unsigned*)(lds + (bufoff) + ldsw + _i * 8192), 16, 0, 0); } while (0)
; #define PG8_LDA(dst, b, h) do { _Pragma("unroll") for (int m = 0; m < 4; ++m) _Pragma("unroll") for (int k = 0; k < 2; ++k) dst[m][k] = *(const PG8_LAS bf16x8*)(lds + PG8_SA(b, h) + aoff + m * 2048 + k * 1024); } while (0)
; #define PG8_MMA(ai, bj, At, Bt) do { __builtin_amdgcn_s_setprio(1); _Pragma("unroll") for (int m = 0; m < 4; ++m) _Pragma("unroll") for (int n = 0; n < 2; ++n) _Pragma("unroll") for (int k = 0; k < 2; ++k) \
;         acc[ai][bj][m][n] = __builtin_amdgcn_mfma_f32_16x16x32_bf16(Bt[n][k], At[m][k], acc[ai][bj][m][n], 0, 0, 0); __builtin_amdgcn_s_setprio(0); } while (0)
; #define PG8_WAIT_V(n) asm volatile("s_waitcnt vmcnt(" #n ")" ::: "memory")
; #define PG8_WAIT_L(n) asm volatile("s_waitcnt lgkmcnt(" #n ")" ::: "memory")
; #define PG8_BAR __builtin_amdgcn_s_barrier()
; #define PG8_SCHED __builtin_amdgcn_sched_barrier(0)
; template <class Epi, class Sched, bool ALIGN_EPI = false, bool SP2 = false>
; __device__ __forceinline__ void gemm_phase(PG8_LAS unsigned char* lds, const Gemm g, const Sched& S, const Epi& E) {
;     ...
;             PG8_LDA(At, 1, 1); PG8_STAGE(PG8_SB(1, 0), b3, voffB); PG8_STAGE(PG8_SB(1, 1), b3 + hstepB, voffB); PG8_STAGE(PG8_SA(1, 0), a3, voffA);
;             PG8_WAIT_V(8); PG8_WAIT_L(0); PG8_BAR; PG8_MMA(1, 0, At, B0); PG8_MMA(1, 1, At, B1); PG8_BAR; PG8_SCHED;
	s_add_i32 s4, s59, s47
	v_lshl_add_u64 v[164:165], v[164:165], 0, s[16:17]
	s_mov_b32 m0, s4
	ds_read_b128 v[184:187], v151 offset:49152
	ds_read_b128 v[188:191], v151 offset:50176
	ds_read_b128 v[192:195], v151 offset:51200
	ds_read_b128 v[196:199], v151 offset:52224
	ds_read_b128 v[200:203], v151 offset:53248
	ds_read_b128 v[204:207], v151 offset:54272
	ds_read_b128 v[208:211], v151 offset:55296
	ds_read_b128 v[212:215], v151 offset:56320
	global_load_lds_dwordx4 v[164:165], off
	s_add_i32 m0, s4, 0x2000
	s_add_u32 s4, s34, 0x80080
	v_lshl_add_u64 v[164:165], v[216:217], 0, s[16:17]
	s_addc_u32 s5, s35, 0
	s_add_i32 s34, s60, s47
	global_load_lds_dwordx4 v[164:165], off
	v_lshl_add_u64 v[164:165], s[4:5], 0, v[130:131]
	s_mov_b32 m0, s34
	s_nop 0
	global_load_lds_dwordx4 v[164:165], off
	v_lshl_add_u64 v[164:165], s[4:5], 0, v[134:135]
	s_add_i32 m0, s34, 0x2000
	s_nop 0
	global_load_lds_dwordx4 v[164:165], off
	v_lshl_add_u64 v[164:165], v[218:219], 0, s[16:17]
	s_mov_b32 m0, s40
	s_nop 0
	global_load_lds_dwordx4 v[164:165], off
	v_lshl_add_u64 v[164:165], v[220:221], 0, s[16:17]
	s_mov_b32 m0, s41
	s_nop 0
	global_load_lds_dwordx4 v[164:165], off
	s_waitcnt vmcnt(8)
	s_waitcnt lgkmcnt(0)
	s_barrier
	s_setprio 1
	v_mfma_f32_16x16x32_bf16 v[60:63], v[144:147], v[184:187], v[60:63]
	v_mfma_f32_16x16x32_bf16 v[56:59], v[156:159], v[184:187], v[56:59]
	v_mfma_f32_16x16x32_bf16 v[44:47], v[144:147], v[192:195], v[44:47]
	v_mfma_f32_16x16x32_bf16 v[40:43], v[156:159], v[192:195], v[40:43]
	v_mfma_f32_16x16x32_bf16 v[28:31], v[144:147], v[200:203], v[28:31]
	v_mfma_f32_16x16x32_bf16 v[24:27], v[156:159], v[200:203], v[24:27]
	v_mfma_f32_16x16x32_bf16 v[12:15], v[144:147], v[208:211], v[12:15]
	v_mfma_f32_16x16x32_bf16 v[8:11], v[156:159], v[208:211], v[8:11]
	v_mfma_f32_16x16x32_bf16 v[60:63], v[152:155], v[188:191], v[60:63]
	v_mfma_f32_16x16x32_bf16 v[56:59], v[160:163], v[188:191], v[56:59]
	v_mfma_f32_16x16x32_bf16 v[44:47], v[152:155], v[196:199], v[44:47]
	v_mfma_f32_16x16x32_bf16 v[40:43], v[160:163], v[196:199], v[40:43]
	v_mfma_f32_16x16x32_bf16 v[28:31], v[152:155], v[204:207], v[28:31]
	v_mfma_f32_16x16x32_bf16 v[24:27], v[160:163], v[204:207], v[24:27]
	v_mfma_f32_16x16x32_bf16 v[12:15], v[152:155], v[212:215], v[12:15]
	v_mfma_f32_16x16x32_bf16 v[8:11], v[160:163], v[212:215], v[8:11]
	v_mfma_f32_16x16x32_bf16 v[52:55], v[168:171], v[184:187], v[52:55]
	v_mfma_f32_16x16x32_bf16 v[48:51], v[176:179], v[184:187], v[48:51]
	v_mfma_f32_16x16x32_bf16 v[36:39], v[168:171], v[192:195], v[36:39]
	v_mfma_f32_16x16x32_bf16 v[32:35], v[176:179], v[192:195], v[32:35]
	v_mfma_f32_16x16x32_bf16 v[20:23], v[168:171], v[200:203], v[20:23]
	v_mfma_f32_16x16x32_bf16 v[16:19], v[176:179], v[200:203], v[16:19]
	v_mfma_f32_16x16x32_bf16 v[4:7], v[168:171], v[208:211], v[4:7]
	v_mfma_f32_16x16x32_bf16 v[0:3], v[176:179], v[208:211], v[0:3]
	v_mfma_f32_16x16x32_bf16 v[52:55], v[172:175], v[188:191], v[52:55]
	v_mfma_f32_16x16x32_bf16 v[48:51], v[180:183], v[188:191], v[48:51]
	v_mfma_f32_16x16x32_bf16 v[36:39], v[172:175], v[196:199], v[36:39]
	v_mfma_f32_16x16x32_bf16 v[32:35], v[180:183], v[196:199], v[32:35]
	v_mfma_f32_16x16x32_bf16 v[20:23], v[172:175], v[204:207], v[20:23]
	v_mfma_f32_16x16x32_bf16 v[16:19], v[180:183], v[204:207], v[16:19]
	v_mfma_f32_16x16x32_bf16 v[4:7], v[172:175], v[212:215], v[4:7]
	v_mfma_f32_16x16x32_bf16 v[0:3], v[180:183], v[212:215], v[0:3]
	s_setprio 0
	s_barrier
	s_add_i32 s58, s58, 2
	s_add_u32 s30, s30, 0x100
	s_addc_u32 s31, s31, 0
	s_add_u32 s56, s56, 0x100
	s_addc_u32 s57, s57, 0
	s_cmp_gt_u32 s58, 29
	s_cbranch_scc0 .LBB0_1211
	s_and_b64 vcc, exec, s[48:49]
	s_cbranch_vccz .LBB0_1214
	s_barrier

; #define PG8_STAGE(bufoff, gbase, voff) do { _Pragma("unroll") for (int _i = 0; _i < 2; ++_i) \
;         __builtin_amdgcn_global_load_lds((const unsigned*)((const char*)(gbase) + (voff)[_i]), (PG8_LAS unsigned*)(lds + (bufoff) + ldsw + _i * 8192), 16, 0, 0); } while (0)
; #define PG8_LDA(dst, b, h) do { _Pragma("unroll") for (int m = 0; m < 4; ++m) _Pragma("unroll") for (int k = 0; k < 2; ++k) dst[m][k] = *(const PG8_LAS bf16x8*)(lds + PG8_SA(b, h) + aoff + m * 2048 + k * 1024); } while (0)
; #define PG8_LDB(dst, b, h) do { _Pragma("unroll") for (int n = 0; n < 2; ++n) _Pragma("unroll") for (int k = 0; k < 2; ++k) dst[n][k] = *(const PG8_LAS bf16x8*)(lds + PG8_SB(b, h) + boff + n * 2048 + k * 1024); } while (0)
; #define PG8_MMA(ai, bj, At, Bt) do { __builtin_amdgcn_s_setprio(1); _Pragma("unroll") for (int m = 0; m < 4; ++m) _Pragma("unroll") for (int n = 0; n < 2; ++n) _Pragma("unroll") for (int k = 0; k < 2; ++k) \
;         acc[ai][bj][m][n] = __builtin_amdgcn_mfma_f32_16x16x32_bf16(Bt[n][k], At[m][k], acc[ai][bj][m][n], 0, 0, 0); __builtin_amdgcn_s_setprio(0); } while (0)
; #define PG8_WAIT_V(n) asm volatile("s_waitcnt vmcnt(" #n ")" ::: "memory")
; #define PG8_WAIT_L(n) asm volatile("s_waitcnt lgkmcnt(" #n ")" ::: "memory")
; #define PG8_BAR __builtin_amdgcn_s_barrier()
; #define PG8_SCHED __builtin_amdgcn_sched_barrier(0)
; template <class Epi, class Sched, bool ALIGN_EPI = false, bool SP2 = false>
; __device__ __forceinline__ void gemm_phase(PG8_LAS unsigned char* lds, const Gemm g, const Sched& S, const Epi& E) {
;     ...
;             const bool last = (t == nt - 2);
;             const char* a1 = cA + (size_t)(t + 1) * kstep;
;             const char* a2 = last ? nA : cA + (size_t)(t + 2) * kstep; const char* b2 = last ? nB : cB + (size_t)(t + 2) * kstep;
;             const char* a3 = a2 + kstep; const char* b3 = b2 + kstep;
;             if (last && has_next) S.a_ready(nxt);
;             if constexpr (SP2) {
;             PG8_LDB(B0, 0, 0); PG8_LDB(B1, 0, 1); PG8_SCHED; PG8_LDA(At, 0, 0); PG8_STAGE(PG8_SA(1, 1), a1 + hstepA, voffA);
;             PG8_WAIT_V(8); PG8_WAIT_L(0); PG8_BAR; PG8_MMA(0, 0, At, B0); PG8_MMA(0, 1, At, B1); PG8_BAR; PG8_SCHED;
;             PG8_LDA(At, 0, 1); PG8_STAGE(PG8_SB(0, 0), b2, voffB); PG8_STAGE(PG8_SB(0, 1), b2 + hstepB, voffB); PG8_STAGE(PG8_SA(0, 0), a2, voffA);
.LBB0_1287:
	ds_read_b128 v[144:147], v149
	ds_read_b128 v[154:157], v149 offset:1024
	ds_read_b128 v[158:161], v149 offset:2048
	ds_read_b128 v[162:165], v149 offset:3072
	ds_read_b128 v[168:171], v150
	ds_read_b128 v[172:175], v150 offset:1024
	ds_read_b128 v[176:179], v150 offset:2048
	ds_read_b128 v[180:183], v150 offset:3072
	s_add_u32 s4, s28, 0xfff80080
	s_addc_u32 s5, s29, -1
	s_cmp_eq_u32 s58, 28
	s_cselect_b32 s35, s19, s5
	s_cselect_b32 s34, s54, s4
	s_cselect_b32 s31, s17, s57
	s_cselect_b32 s30, s55, s56
	v_lshl_add_u64 v[216:217], s[28:29], 0, v[136:137]
	s_add_i32 m0, s27, 0xc000
	ds_read_b128 v[184:187], v151
	ds_read_b128 v[188:191], v151 offset:1024
	ds_read_b128 v[192:195], v151 offset:2048
	ds_read_b128 v[196:199], v151 offset:3072
	ds_read_b128 v[200:203], v151 offset:4096
	ds_read_b128 v[204:207], v151 offset:5120
	ds_read_b128 v[208:211], v151 offset:6144
	ds_read_b128 v[212:215], v151 offset:7168
	global_load_lds_dwordx4 v[216:217], off
	v_lshl_add_u64 v[216:217], s[28:29], 0, v[138:139]
	s_add_i32 m0, s27, 0xe000
	s_nop 0
	global_load_lds_dwordx4 v[216:217], off
	s_waitcnt vmcnt(8)
	s_waitcnt lgkmcnt(0)
	s_barrier
	s_setprio 1
	v_mfma_f32_16x16x32_bf16 v[116:119], v[144:147], v[184:187], v[116:119]
	v_mfma_f32_16x16x32_bf16 v[112:115], v[158:161], v[184:187], v[112:115]
	v_mfma_f32_16x16x32_bf16 v[100:103], v[144:147], v[192:195], v[100:103]
	v_mfma_f32_16x16x32_bf16 v[96:99], v[158:161], v[192:195], v[96:99]
	v_mfma_f32_16x16x32_bf16 v[84:87], v[144:147], v[200:203], v[84:87]
	v_mfma_f32_16x16x32_bf16 v[80:83], v[158:161], v[200:203], v[80:83]
	v_mfma_f32_16x16x32_bf16 v[68:71], v[144:147], v[208:211], v[68:71]
	v_mfma_f32_16x16x32_bf16 v[64:67], v[158:161], v[208:211], v[64:67]
	v_mfma_f32_16x16x32_bf16 v[116:119], v[154:157], v[188:191], v[116:119]
	v_mfma_f32_16x16x32_bf16 v[112:115], v[162:165], v[188:191], v[112:115]
	v_mfma_f32_16x16x32_bf16 v[100:103], v[154:157], v[196:199], v[100:103]
	v_mfma_f32_16x16x32_bf16 v[96:99], v[162:165], v[196:199], v[96:99]
	v_mfma_f32_16x16x32_bf16 v[84:87], v[154:157], v[204:207], v[84:87]
	v_mfma_f32_16x16x32_bf16 v[80:83], v[162:165], v[204:207], v[80:83]
	v_mfma_f32_16x16x32_bf16 v[68:71], v[154:157], v[212:215], v[68:71]
	v_mfma_f32_16x16x32_bf16 v[64:67], v[162:165], v[212:215], v[64:67]
	v_mfma_f32_16x16x32_bf16 v[124:127], v[168:171], v[184:187], v[124:127]
	v_mfma_f32_16x16x32_bf16 v[120:123], v[176:179], v[184:187], v[120:123]
	v_mfma_f32_16x16x32_bf16 v[108:111], v[168:171], v[192:195], v[108:111]
	v_mfma_f32_16x16x32_bf16 v[104:107], v[176:179], v[192:195], v[104:107]
	v_mfma_f32_16x16x32_bf16 v[92:95], v[168:171], v[200:203], v[92:95]
	v_mfma_f32_16x16x32_bf16 v[88:91], v[176:179], v[200:203], v[88:91]
	v_mfma_f32_16x16x32_bf16 v[76:79], v[168:171], v[208:211], v[76:79]
	v_mfma_f32_16x16x32_bf16 v[72:75], v[176:179], v[208:211], v[72:75]
	v_mfma_f32_16x16x32_bf16 v[124:127], v[172:175], v[188:191], v[124:127]
	v_mfma_f32_16x16x32_bf16 v[120:123], v[180:183], v[188:191], v[120:123]
	v_mfma_f32_16x16x32_bf16 v[108:111], v[172:175], v[196:199], v[108:111]
	v_mfma_f32_16x16x32_bf16 v[104:107], v[180:183], v[196:199], v[104:107]
	v_mfma_f32_16x16x32_bf16 v[92:95], v[172:175], v[204:207], v[92:95]
	v_mfma_f32_16x16x32_bf16 v[88:91], v[180:183], v[204:207], v[88:91]
	v_mfma_f32_16x16x32_bf16 v[76:79], v[172:175], v[212:215], v[76:79]
	v_mfma_f32_16x16x32_bf16 v[72:75], v[180:183], v[212:215], v[72:75]
	s_setprio 0
	s_barrier
	s_add_i32 s4, s41, s47
	v_lshl_add_u64 v[216:217], s[30:31], 0, v[132:133]
	s_mov_b32 m0, s4
	ds_read_b128 v[184:187], v151 offset:16384
	ds_read_b128 v[188:191], v151 offset:17408
	ds_read_b128 v[192:195], v151 offset:18432
	ds_read_b128 v[196:199], v151 offset:19456
	ds_read_b128 v[200:203], v151 offset:20480
	ds_read_b128 v[204:207], v151 offset:21504
	ds_read_b128 v[208:211], v151 offset:22528
	ds_read_b128 v[212:215], v151 offset:23552
	global_load_lds_dwordx4 v[216:217], off
	s_add_i32 m0, s4, 0x2000
	s_add_u32 s4, s30, 0x80000
	v_lshl_add_u64 v[218:219], s[30:31], 0, v[128:129]
	s_addc_u32 s5, s31, 0
	s_add_i32 s59, s44, s47
	global_load_lds_dwordx4 v[218:219], off
	v_lshl_add_u64 v[220:221], s[4:5], 0, v[132:133]
	s_mov_b32 m0, s59
	v_lshl_add_u64 v[222:223], s[34:35], 0, v[130:131]
	global_load_lds_dwordx4 v[220:221], off
	v_lshl_add_u64 v[220:221], s[4:5], 0, v[128:129]
	s_add_i32 m0, s59, 0x2000
	s_nop 0
	global_load_lds_dwordx4 v[220:221], off
	v_lshl_add_u64 v[220:221], s[34:35], 0, v[134:135]
	s_mov_b32 m0, s27
	s_nop 0
	global_load_lds_dwordx4 v[220:221], off
	s_mov_b32 m0, s33
	s_nop 0
	global_load_lds_dwordx4 v[222:223], off
	s_waitcnt vmcnt(8)
	s_waitcnt lgkmcnt(0)
	s_barrier
; #define PG8_STAGE(bufoff, gbase, voff) do { _Pragma("unroll") for (int _i = 0; _i < 2; ++_i) \
;         __builtin_amdgcn_global_load_lds((const unsigned*)((const char*)(gbase) + (voff)[_i]), (PG8_LAS unsigned*)(lds + (bufoff) + ldsw + _i * 8192), 16, 0, 0); } while (0)
; #define PG8_LDA(dst, b, h) do { _Pragma("unroll") for (int m = 0; m < 4; ++m) _Pragma("unroll") for (int k = 0; k < 2; ++k) dst[m][k] = *(const PG8_LAS bf16x8*)(lds + PG8_SA(b, h) + aoff + m * 2048 + k * 1024); } while (0)
; #define PG8_LDB(dst, b, h) do { _Pragma("unroll") for (int n = 0; n < 2; ++n) _Pragma("unroll") for (int k = 0; k < 2; ++k) dst[n][k] = *(const PG8_LAS bf16x8*)(lds + PG8_SB(b, h) + boff + n * 2048 + k * 1024); } while (0)
; #define PG8_MMA(ai, bj, At, Bt) do { __builtin_amdgcn_s_setprio(1); _Pragma("unroll") for (int m = 0; m < 4; ++m) _Pragma("unroll") for (int n = 0; n < 2; ++n) _Pragma("unroll") for (int k = 0; k < 2; ++k) \
;         acc[ai][bj][m][n] = __builtin_amdgcn_mfma_f32_16x16x32_bf16(Bt[n][k], At[m][k], acc[ai][bj][m][n], 0, 0, 0); __builtin_amdgcn_s_setprio(0); } while (0)
; #define PG8_WAIT_V(n) asm volatile("s_waitcnt vmcnt(" #n ")" ::: "memory")
; #define PG8_WAIT_L(n) asm volatile("s_waitcnt lgkmcnt(" #n ")" ::: "memory")
; #define PG8_BAR __builtin_amdgcn_s_barrier()
; #define PG8_SCHED __builtin_amdgcn_sched_barrier(0)
; template <class Epi, class Sched, bool ALIGN_EPI = false, bool SP2 = false>
; __device__ __forceinline__ void gemm_phase(PG8_LAS unsigned char* lds, const Gemm g, const Sched& S, const Epi& E) {
;     ...
;             PG8_WAIT_V(8); PG8_WAIT_L(0); PG8_BAR; PG8_MMA(1, 0, At, B0); PG8_MMA(1, 1, At, B1); PG8_BAR; PG8_SCHED;
;             PG8_LDB(B0, 1, 0); PG8_LDB(B1, 1, 1); PG8_SCHED; PG8_LDA(At, 1, 0); PG8_STAGE(PG8_SA(0, 1), a2 + hstepA, voffA);
;             PG8_WAIT_V(8); PG8_WAIT_L(0); PG8_BAR; PG8_MMA(0, 0, At, B0); PG8_MMA(0, 1, At, B1); PG8_BAR; PG8_SCHED;
	s_setprio 1
	v_mfma_f32_16x16x32_bf16 v[52:55], v[144:147], v[184:187], v[52:55]
	v_mfma_f32_16x16x32_bf16 v[48:51], v[158:161], v[184:187], v[48:51]
	v_mfma_f32_16x16x32_bf16 v[36:39], v[144:147], v[192:195], v[36:39]
	v_mfma_f32_16x16x32_bf16 v[32:35], v[158:161], v[192:195], v[32:35]
	v_mfma_f32_16x16x32_bf16 v[20:23], v[144:147], v[200:203], v[20:23]
	v_mfma_f32_16x16x32_bf16 v[16:19], v[158:161], v[200:203], v[16:19]
	v_mfma_f32_16x16x32_bf16 v[8:11], v[144:147], v[208:211], v[8:11]
	v_mfma_f32_16x16x32_bf16 v[4:7], v[158:161], v[208:211], v[4:7]
	v_mfma_f32_16x16x32_bf16 v[52:55], v[154:157], v[188:191], v[52:55]
	v_mfma_f32_16x16x32_bf16 v[48:51], v[162:165], v[188:191], v[48:51]
	v_mfma_f32_16x16x32_bf16 v[36:39], v[154:157], v[196:199], v[36:39]
	v_mfma_f32_16x16x32_bf16 v[32:35], v[162:165], v[196:199], v[32:35]
	v_mfma_f32_16x16x32_bf16 v[20:23], v[154:157], v[204:207], v[20:23]
	v_mfma_f32_16x16x32_bf16 v[16:19], v[162:165], v[204:207], v[16:19]
	v_mfma_f32_16x16x32_bf16 v[8:11], v[154:157], v[212:215], v[8:11]
	v_mfma_f32_16x16x32_bf16 v[4:7], v[162:165], v[212:215], v[4:7]
	v_mfma_f32_16x16x32_bf16 v[60:63], v[168:171], v[184:187], v[60:63]
	v_mfma_f32_16x16x32_bf16 v[56:59], v[176:179], v[184:187], v[56:59]
	v_mfma_f32_16x16x32_bf16 v[44:47], v[168:171], v[192:195], v[44:47]
	v_mfma_f32_16x16x32_bf16 v[40:43], v[176:179], v[192:195], v[40:43]
	v_mfma_f32_16x16x32_bf16 v[28:31], v[168:171], v[200:203], v[28:31]
	v_mfma_f32_16x16x32_bf16 v[24:27], v[176:179], v[200:203], v[24:27]
	v_mfma_f32_16x16x32_bf16 v[12:15], v[168:171], v[208:211], v[12:15]
	v_mfma_f32_16x16x32_bf16 v[0:3], v[176:179], v[208:211], v[0:3]
	v_mfma_f32_16x16x32_bf16 v[60:63], v[172:175], v[188:191], v[60:63]
	v_mfma_f32_16x16x32_bf16 v[56:59], v[180:183], v[188:191], v[56:59]
	v_mfma_f32_16x16x32_bf16 v[44:47], v[172:175], v[196:199], v[44:47]
	v_mfma_f32_16x16x32_bf16 v[40:43], v[180:183], v[196:199], v[40:43]
	v_mfma_f32_16x16x32_bf16 v[28:31], v[172:175], v[204:207], v[28:31]
	v_mfma_f32_16x16x32_bf16 v[24:27], v[180:183], v[204:207], v[24:27]
	v_mfma_f32_16x16x32_bf16 v[12:15], v[172:175], v[212:215], v[12:15]
	v_mfma_f32_16x16x32_bf16 v[0:3], v[180:183], v[212:215], v[0:3]
	s_setprio 0
	s_barrier
	s_add_i32 s59, 0, 0x18000
	v_add_u32_e32 v153, s59, v148
	s_add_i32 s60, 0, 0x1c000
	ds_read_b128 v[144:147], v153
	ds_read_b128 v[154:157], v153 offset:1024
	ds_read_b128 v[158:161], v153 offset:2048
	ds_read_b128 v[162:165], v153 offset:3072
	v_add_u32_e32 v153, s60, v148
	ds_read_b128 v[168:171], v153
	ds_read_b128 v[172:175], v153 offset:1024
	ds_read_b128 v[176:179], v153 offset:2048
	ds_read_b128 v[180:183], v153 offset:3072
	s_add_u32 s4, s34, 0x80000
	s_addc_u32 s5, s35, 0
	s_mov_b32 m0, s36
	v_lshl_add_u64 v[224:225], s[4:5], 0, v[134:135]
	ds_read_b128 v[184:187], v151 offset:32768
	ds_read_b128 v[188:191], v151 offset:33792
	ds_read_b128 v[192:195], v151 offset:34816
	ds_read_b128 v[196:199], v151 offset:35840
	ds_read_b128 v[200:203], v151 offset:36864
	ds_read_b128 v[204:207], v151 offset:37888
	ds_read_b128 v[208:211], v151 offset:38912
	ds_read_b128 v[212:215], v151 offset:39936
	global_load_lds_dwordx4 v[224:225], off
	v_lshl_add_u64 v[224:225], s[4:5], 0, v[130:131]
	s_mov_b32 m0, s37
	s_nop 0
	global_load_lds_dwordx4 v[224:225], off
	s_waitcnt vmcnt(8)
	s_waitcnt lgkmcnt(0)
	s_barrier
	s_setprio 1
	v_mfma_f32_16x16x32_bf16 v[116:119], v[144:147], v[184:187], v[116:119]
	v_mfma_f32_16x16x32_bf16 v[112:115], v[158:161], v[184:187], v[112:115]
	v_mfma_f32_16x16x32_bf16 v[100:103], v[144:147], v[192:195], v[100:103]
	v_mfma_f32_16x16x32_bf16 v[96:99], v[158:161], v[192:195], v[96:99]
	v_mfma_f32_16x16x32_bf16 v[84:87], v[144:147], v[200:203], v[84:87]
	v_mfma_f32_16x16x32_bf16 v[80:83], v[158:161], v[200:203], v[80:83]
	v_mfma_f32_16x16x32_bf16 v[68:71], v[144:147], v[208:211], v[68:71]
	v_mfma_f32_16x16x32_bf16 v[64:67], v[158:161], v[208:211], v[64:67]
	v_mfma_f32_16x16x32_bf16 v[116:119], v[154:157], v[188:191], v[116:119]
	v_mfma_f32_16x16x32_bf16 v[112:115], v[162:165], v[188:191], v[112:115]
	v_mfma_f32_16x16x32_bf16 v[100:103], v[154:157], v[196:199], v[100:103]
	v_mfma_f32_16x16x32_bf16 v[96:99], v[162:165], v[196:199], v[96:99]
	v_mfma_f32_16x16x32_bf16 v[84:87], v[154:157], v[204:207], v[84:87]
	v_mfma_f32_16x16x32_bf16 v[80:83], v[162:165], v[204:207], v[80:83]
	v_mfma_f32_16x16x32_bf16 v[68:71], v[154:157], v[212:215], v[68:71]
	v_mfma_f32_16x16x32_bf16 v[64:67], v[162:165], v[212:215], v[64:67]
	v_mfma_f32_16x16x32_bf16 v[124:127], v[168:171], v[184:187], v[124:127]
	v_mfma_f32_16x16x32_bf16 v[120:123], v[176:179], v[184:187], v[120:123]
	v_mfma_f32_16x16x32_bf16 v[108:111], v[168:171], v[192:195], v[108:111]
	v_mfma_f32_16x16x32_bf16 v[104:107], v[176:179], v[192:195], v[104:107]
	v_mfma_f32_16x16x32_bf16 v[92:95], v[168:171], v[200:203], v[92:95]
	v_mfma_f32_16x16x32_bf16 v[88:91], v[176:179], v[200:203], v[88:91]
	v_mfma_f32_16x16x32_bf16 v[76:79], v[168:171], v[208:211], v[76:79]
	v_mfma_f32_16x16x32_bf16 v[72:75], v[176:179], v[208:211], v[72:75]
	v_mfma_f32_16x16x32_bf16 v[124:127], v[172:175], v[188:191], v[124:127]
	v_mfma_f32_16x16x32_bf16 v[120:123], v[180:183], v[188:191], v[120:123]
	v_mfma_f32_16x16x32_bf16 v[108:111], v[172:175], v[196:199], v[108:111]
	v_mfma_f32_16x16x32_bf16 v[104:107], v[180:183], v[196:199], v[104:107]
	v_mfma_f32_16x16x32_bf16 v[92:95], v[172:175], v[204:207], v[92:95]
	v_mfma_f32_16x16x32_bf16 v[88:91], v[180:183], v[204:207], v[88:91]
	v_mfma_f32_16x16x32_bf16 v[76:79], v[172:175], v[212:215], v[76:79]
	v_mfma_f32_16x16x32_bf16 v[72:75], v[180:183], v[212:215], v[72:75]
	s_setprio 0
	s_barrier
; #define PG8_STAGE(bufoff, gbase, voff) do { _Pragma("unroll") for (int _i = 0; _i < 2; ++_i) \
;         __builtin_amdgcn_global_load_lds((const unsigned*)((const char*)(gbase) + (voff)[_i]), (PG8_LAS unsigned*)(lds + (bufoff) + ldsw + _i * 8192), 16, 0, 0); } while (0)
; #define PG8_LDA(dst, b, h) do { _Pragma("unroll") for (int m = 0; m < 4; ++m) _Pragma("unroll") for (int k = 0; k < 2; ++k) dst[m][k] = *(const PG8_LAS bf16x8*)(lds + PG8_SA(b, h) + aoff + m * 2048 + k * 1024); } while (0)
; #define PG8_MMA(ai, bj, At, Bt) do { __builtin_amdgcn_s_setprio(1); _Pragma("unroll") for (int m = 0; m < 4; ++m) _Pragma("unroll") for (int n = 0; n < 2; ++n) _Pragma("unroll") for (int k = 0; k < 2; ++k) \
;         acc[ai][bj][m][n] = __builtin_amdgcn_mfma_f32_16x16x32_bf16(Bt[n][k], At[m][k], acc[ai][bj][m][n], 0, 0, 0); __builtin_amdgcn_s_setprio(0); } while (0)
; #define PG8_WAIT_V(n) asm volatile("s_waitcnt vmcnt(" #n ")" ::: "memory")
; #define PG8_WAIT_L(n) asm volatile("s_waitcnt lgkmcnt(" #n ")" ::: "memory")
; #define PG8_BAR __builtin_amdgcn_s_barrier()
; #define PG8_SCHED __builtin_amdgcn_sched_barrier(0)
; template <class Epi, class Sched, bool ALIGN_EPI = false, bool SP2 = false>
; __device__ __forceinline__ void gemm_phase(PG8_LAS unsigned char* lds, const Gemm g, const Sched& S, const Epi& E) {
;     ...
;             PG8_LDA(At, 1, 1); PG8_STAGE(PG8_SB(1, 0), b3, voffB); PG8_STAGE(PG8_SB(1, 1), b3 + hstepB, voffB); PG8_STAGE(PG8_SA(1, 0), a3, voffA);
;             PG8_WAIT_V(8); PG8_WAIT_L(0); PG8_BAR; PG8_MMA(1, 0, At, B0); PG8_MMA(1, 1, At, B1); PG8_BAR; PG8_SCHED;
	s_add_i32 s4, s59, s47
	v_lshl_add_u64 v[216:217], v[216:217], 0, s[14:15]
	s_mov_b32 m0, s4
	ds_read_b128 v[184:187], v151 offset:49152
	ds_read_b128 v[188:191], v151 offset:50176
	ds_read_b128 v[192:195], v151 offset:51200
	ds_read_b128 v[196:199], v151 offset:52224
	ds_read_b128 v[200:203], v151 offset:53248
	ds_read_b128 v[204:207], v151 offset:54272
	ds_read_b128 v[208:211], v151 offset:55296
	ds_read_b128 v[212:215], v151 offset:56320
	global_load_lds_dwordx4 v[216:217], off
	s_add_i32 m0, s4, 0x2000
	s_add_u32 s4, s30, 0x80080
	v_lshl_add_u64 v[216:217], v[218:219], 0, s[14:15]
	s_addc_u32 s5, s31, 0
	s_add_i32 s30, s60, s47
	global_load_lds_dwordx4 v[216:217], off
	v_lshl_add_u64 v[216:217], s[4:5], 0, v[132:133]
	s_mov_b32 m0, s30
	s_nop 0
	global_load_lds_dwordx4 v[216:217], off
	v_lshl_add_u64 v[216:217], s[4:5], 0, v[128:129]
	s_add_i32 m0, s30, 0x2000
	s_nop 0
	global_load_lds_dwordx4 v[216:217], off
	v_lshl_add_u64 v[216:217], v[220:221], 0, s[14:15]
	s_mov_b32 m0, s39
	s_nop 0
	global_load_lds_dwordx4 v[216:217], off
	v_lshl_add_u64 v[216:217], v[222:223], 0, s[14:15]
	s_mov_b32 m0, s40
	s_nop 0
	global_load_lds_dwordx4 v[216:217], off
	s_waitcnt vmcnt(8)
	s_waitcnt lgkmcnt(0)
	s_barrier
	s_setprio 1
	v_mfma_f32_16x16x32_bf16 v[52:55], v[144:147], v[184:187], v[52:55]
	v_mfma_f32_16x16x32_bf16 v[48:51], v[158:161], v[184:187], v[48:51]
	v_mfma_f32_16x16x32_bf16 v[36:39], v[144:147], v[192:195], v[36:39]
	v_mfma_f32_16x16x32_bf16 v[32:35], v[158:161], v[192:195], v[32:35]
	v_mfma_f32_16x16x32_bf16 v[20:23], v[144:147], v[200:203], v[20:23]
	v_mfma_f32_16x16x32_bf16 v[16:19], v[158:161], v[200:203], v[16:19]
	v_mfma_f32_16x16x32_bf16 v[8:11], v[144:147], v[208:211], v[8:11]
	v_mfma_f32_16x16x32_bf16 v[4:7], v[158:161], v[208:211], v[4:7]
	v_mfma_f32_16x16x32_bf16 v[52:55], v[154:157], v[188:191], v[52:55]
	v_mfma_f32_16x16x32_bf16 v[48:51], v[162:165], v[188:191], v[48:51]
	v_mfma_f32_16x16x32_bf16 v[36:39], v[154:157], v[196:199], v[36:39]
	v_mfma_f32_16x16x32_bf16 v[32:35], v[162:165], v[196:199], v[32:35]
	v_mfma_f32_16x16x32_bf16 v[20:23], v[154:157], v[204:207], v[20:23]
	v_mfma_f32_16x16x32_bf16 v[16:19], v[162:165], v[204:207], v[16:19]
	v_mfma_f32_16x16x32_bf16 v[8:11], v[154:157], v[212:215], v[8:11]
	v_mfma_f32_16x16x32_bf16 v[4:7], v[162:165], v[212:215], v[4:7]
	v_mfma_f32_16x16x32_bf16 v[60:63], v[168:171], v[184:187], v[60:63]
	v_mfma_f32_16x16x32_bf16 v[56:59], v[176:179], v[184:187], v[56:59]
	v_mfma_f32_16x16x32_bf16 v[44:47], v[168:171], v[192:195], v[44:47]
	v_mfma_f32_16x16x32_bf16 v[40:43], v[176:179], v[192:195], v[40:43]
	v_mfma_f32_16x16x32_bf16 v[28:31], v[168:171], v[200:203], v[28:31]
	v_mfma_f32_16x16x32_bf16 v[24:27], v[176:179], v[200:203], v[24:27]
	v_mfma_f32_16x16x32_bf16 v[12:15], v[168:171], v[208:211], v[12:15]
	v_mfma_f32_16x16x32_bf16 v[0:3], v[176:179], v[208:211], v[0:3]
	v_mfma_f32_16x16x32_bf16 v[60:63], v[172:175], v[188:191], v[60:63]
	v_mfma_f32_16x16x32_bf16 v[56:59], v[180:183], v[188:191], v[56:59]
	v_mfma_f32_16x16x32_bf16 v[44:47], v[172:175], v[196:199], v[44:47]
	v_mfma_f32_16x16x32_bf16 v[40:43], v[180:183], v[196:199], v[40:43]
	v_mfma_f32_16x16x32_bf16 v[28:31], v[172:175], v[204:207], v[28:31]
	v_mfma_f32_16x16x32_bf16 v[24:27], v[180:183], v[204:207], v[24:27]
	v_mfma_f32_16x16x32_bf16 v[12:15], v[172:175], v[212:215], v[12:15]
	v_mfma_f32_16x16x32_bf16 v[0:3], v[180:183], v[212:215], v[0:3]
	s_setprio 0
	s_barrier
	s_add_i32 s58, s58, 2
	s_add_u32 s28, s28, 0x100
	s_addc_u32 s29, s29, 0
	s_add_u32 s56, s56, 0x100
	s_addc_u32 s57, s57, 0
	s_cmp_gt_u32 s58, 29
	s_cbranch_scc0 .LBB0_1287
	s_and_b64 vcc, exec, s[48:49]
	s_cbranch_vccz .LBB0_1290
	s_barrier

; #define PG8_STAGE(bufoff, gbase, voff) do { _Pragma("unroll") for (int _i = 0; _i < 2; ++_i) \
;         __builtin_amdgcn_global_load_lds((const unsigned*)((const char*)(gbase) + (voff)[_i]), (PG8_LAS unsigned*)(lds + (bufoff) + ldsw + _i * 8192), 16, 0, 0); } while (0)
; #define PG8_LDA(dst, b, h) do { _Pragma("unroll") for (int m = 0; m < 4; ++m) _Pragma("unroll") for (int k = 0; k < 2; ++k) dst[m][k] = *(const PG8_LAS bf16x8*)(lds + PG8_SA(b, h) + aoff + m * 2048 + k * 1024); } while (0)
; #define PG8_LDB(dst, b, h) do { _Pragma("unroll") for (int n = 0; n < 2; ++n) _Pragma("unroll") for (int k = 0; k < 2; ++k) dst[n][k] = *(const PG8_LAS bf16x8*)(lds + PG8_SB(b, h) + boff + n * 2048 + k * 1024); } while (0)
; #define PG8_MMA(ai, bj, At, Bt) do { __builtin_amdgcn_s_setprio(1); _Pragma("unroll") for (int m = 0; m < 4; ++m) _Pragma("unroll") for (int n = 0; n < 2; ++n) _Pragma("unroll") for (int k = 0; k < 2; ++k) \
;         acc[ai][bj][m][n] = __builtin_amdgcn_mfma_f32_16x16x32_bf16(Bt[n][k], At[m][k], acc[ai][bj][m][n], 0, 0, 0); __builtin_amdgcn_s_setprio(0); } while (0)
; #define PG8_WAIT_V(n) asm volatile("s_waitcnt vmcnt(" #n ")" ::: "memory")
; #define PG8_WAIT_L(n) asm volatile("s_waitcnt lgkmcnt(" #n ")" ::: "memory")
; #define PG8_BAR __builtin_amdgcn_s_barrier()
; #define PG8_SCHED __builtin_amdgcn_sched_barrier(0)
; template <class Epi, class Sched, bool ALIGN_EPI = false, bool SP2 = false>
; __device__ __forceinline__ void gemm_phase(PG8_LAS unsigned char* lds, const Gemm g, const Sched& S, const Epi& E) {
;     ...
;             const bool last = (t == nt - 2);
;             const char* a1 = cA + (size_t)(t + 1) * kstep;
;             const char* a2 = last ? nA : cA + (size_t)(t + 2) * kstep; const char* b2 = last ? nB : cB + (size_t)(t + 2) * kstep;
;             const char* a3 = a2 + kstep; const char* b3 = b2 + kstep;
;             if (last && has_next) S.a_ready(nxt);
;             if constexpr (SP2) {
;             PG8_LDB(B0, 0, 0); PG8_LDB(B1, 0, 1); PG8_SCHED; PG8_LDA(At, 0, 0); PG8_STAGE(PG8_SA(1, 1), a1 + hstepA, voffA);
;             PG8_WAIT_V(8); PG8_WAIT_L(0); PG8_BAR; PG8_MMA(0, 0, At, B0); PG8_MMA(0, 1, At, B1); PG8_BAR; PG8_SCHED;
;             PG8_LDA(At, 0, 1); PG8_STAGE(PG8_SB(0, 0), b2, voffB); PG8_STAGE(PG8_SB(0, 1), b2 + hstepB, voffB); PG8_STAGE(PG8_SA(0, 0), a2, voffA);
.LBB0_1361:
	ds_read_b128 v[144:147], v149
	ds_read_b128 v[152:155], v149 offset:1024
	ds_read_b128 v[156:159], v149 offset:2048
	ds_read_b128 v[160:163], v149 offset:3072
	ds_read_b128 v[168:171], v150
	ds_read_b128 v[172:175], v150 offset:1024
	ds_read_b128 v[176:179], v150 offset:2048
	ds_read_b128 v[180:183], v150 offset:3072
	s_add_u32 s22, s20, 0x100
	s_addc_u32 s23, s21, 0
	s_cmpk_eq_i32 s50, 0x54
	s_cselect_b32 s29, s9, s23
	s_cselect_b32 s28, s8, s22
	s_cselect_b32 s27, s19, s46
	s_cselect_b32 s26, s18, s45
	v_lshl_add_u64 v[164:165], s[20:21], 0, v[136:137]
	s_add_i32 m0, s25, 0xc000
	ds_read_b128 v[184:187], v151
	ds_read_b128 v[188:191], v151 offset:1024
	ds_read_b128 v[192:195], v151 offset:2048
	ds_read_b128 v[196:199], v151 offset:3072
	ds_read_b128 v[200:203], v151 offset:4096
	ds_read_b128 v[204:207], v151 offset:5120
	ds_read_b128 v[208:211], v151 offset:6144
	ds_read_b128 v[212:215], v151 offset:7168
	global_load_lds_dwordx4 v[164:165], off
	v_lshl_add_u64 v[164:165], s[20:21], 0, v[138:139]
	s_add_i32 m0, s25, 0xe000
	s_nop 0
	global_load_lds_dwordx4 v[164:165], off
	s_waitcnt vmcnt(8)
	s_waitcnt lgkmcnt(0)
	s_barrier
	s_setprio 1
	v_mfma_f32_16x16x32_bf16 v[124:127], v[144:147], v[184:187], v[124:127]
	v_mfma_f32_16x16x32_bf16 v[120:123], v[156:159], v[184:187], v[120:123]
	v_mfma_f32_16x16x32_bf16 v[108:111], v[144:147], v[192:195], v[108:111]
	v_mfma_f32_16x16x32_bf16 v[104:107], v[156:159], v[192:195], v[104:107]
	v_mfma_f32_16x16x32_bf16 v[92:95], v[144:147], v[200:203], v[92:95]
	v_mfma_f32_16x16x32_bf16 v[88:91], v[156:159], v[200:203], v[88:91]
	v_mfma_f32_16x16x32_bf16 v[76:79], v[144:147], v[208:211], v[76:79]
	v_mfma_f32_16x16x32_bf16 v[72:75], v[156:159], v[208:211], v[72:75]
	v_mfma_f32_16x16x32_bf16 v[124:127], v[152:155], v[188:191], v[124:127]
	v_mfma_f32_16x16x32_bf16 v[120:123], v[160:163], v[188:191], v[120:123]
	v_mfma_f32_16x16x32_bf16 v[108:111], v[152:155], v[196:199], v[108:111]
	v_mfma_f32_16x16x32_bf16 v[104:107], v[160:163], v[196:199], v[104:107]
	v_mfma_f32_16x16x32_bf16 v[92:95], v[152:155], v[204:207], v[92:95]
	v_mfma_f32_16x16x32_bf16 v[88:91], v[160:163], v[204:207], v[88:91]
	v_mfma_f32_16x16x32_bf16 v[76:79], v[152:155], v[212:215], v[76:79]
	v_mfma_f32_16x16x32_bf16 v[72:75], v[160:163], v[212:215], v[72:75]
	v_mfma_f32_16x16x32_bf16 v[116:119], v[168:171], v[184:187], v[116:119]
	v_mfma_f32_16x16x32_bf16 v[112:115], v[176:179], v[184:187], v[112:115]
	v_mfma_f32_16x16x32_bf16 v[100:103], v[168:171], v[192:195], v[100:103]
	v_mfma_f32_16x16x32_bf16 v[96:99], v[176:179], v[192:195], v[96:99]
	v_mfma_f32_16x16x32_bf16 v[84:87], v[168:171], v[200:203], v[84:87]
	v_mfma_f32_16x16x32_bf16 v[80:83], v[176:179], v[200:203], v[80:83]
	v_mfma_f32_16x16x32_bf16 v[68:71], v[168:171], v[208:211], v[68:71]
	v_mfma_f32_16x16x32_bf16 v[64:67], v[176:179], v[208:211], v[64:67]
	v_mfma_f32_16x16x32_bf16 v[116:119], v[172:175], v[188:191], v[116:119]
	v_mfma_f32_16x16x32_bf16 v[112:115], v[180:183], v[188:191], v[112:115]
	v_mfma_f32_16x16x32_bf16 v[100:103], v[172:175], v[196:199], v[100:103]
	v_mfma_f32_16x16x32_bf16 v[96:99], v[180:183], v[196:199], v[96:99]
	v_mfma_f32_16x16x32_bf16 v[84:87], v[172:175], v[204:207], v[84:87]
	v_mfma_f32_16x16x32_bf16 v[80:83], v[180:183], v[204:207], v[80:83]
	v_mfma_f32_16x16x32_bf16 v[68:71], v[172:175], v[212:215], v[68:71]
	v_mfma_f32_16x16x32_bf16 v[64:67], v[180:183], v[212:215], v[64:67]
	s_setprio 0
	s_barrier
	s_add_i32 s4, s36, s47
	v_lshl_add_u64 v[164:165], s[26:27], 0, v[130:131]
	s_mov_b32 m0, s4
	ds_read_b128 v[184:187], v151 offset:16384
	ds_read_b128 v[188:191], v151 offset:17408
	ds_read_b128 v[192:195], v151 offset:18432
	ds_read_b128 v[196:199], v151 offset:19456
	ds_read_b128 v[200:203], v151 offset:20480
	ds_read_b128 v[204:207], v151 offset:21504
	ds_read_b128 v[208:211], v151 offset:22528
	ds_read_b128 v[212:215], v151 offset:23552
	global_load_lds_dwordx4 v[164:165], off
	s_add_i32 m0, s4, 0x2000
	s_add_u32 s4, s26, 0x160000
	v_lshl_add_u64 v[216:217], s[26:27], 0, v[134:135]
	s_addc_u32 s5, s27, 0
	s_add_i32 s20, s37, s47
	global_load_lds_dwordx4 v[216:217], off
	v_lshl_add_u64 v[218:219], s[4:5], 0, v[130:131]
	s_mov_b32 m0, s20
	v_lshl_add_u64 v[220:221], s[28:29], 0, v[132:133]
	global_load_lds_dwordx4 v[218:219], off
	v_lshl_add_u64 v[218:219], s[4:5], 0, v[134:135]
	s_add_i32 m0, s20, 0x2000
	s_nop 0
	global_load_lds_dwordx4 v[218:219], off
	v_lshl_add_u64 v[218:219], s[28:29], 0, v[128:129]
	s_mov_b32 m0, s25
	s_nop 0
	global_load_lds_dwordx4 v[218:219], off
	s_mov_b32 m0, s30
	s_nop 0
	global_load_lds_dwordx4 v[220:221], off
	s_waitcnt vmcnt(8)
	s_waitcnt lgkmcnt(0)
	s_barrier
; #define PG8_STAGE(bufoff, gbase, voff) do { _Pragma("unroll") for (int _i = 0; _i < 2; ++_i) \
;         __builtin_amdgcn_global_load_lds((const unsigned*)((const char*)(gbase) + (voff)[_i]), (PG8_LAS unsigned*)(lds + (bufoff) + ldsw + _i * 8192), 16, 0, 0); } while (0)
; #define PG8_LDA(dst, b, h) do { _Pragma("unroll") for (int m = 0; m < 4; ++m) _Pragma("unroll") for (int k = 0; k < 2; ++k) dst[m][k] = *(const PG8_LAS bf16x8*)(lds + PG8_SA(b, h) + aoff + m * 2048 + k * 1024); } while (0)
; #define PG8_LDB(dst, b, h) do { _Pragma("unroll") for (int n = 0; n < 2; ++n) _Pragma("unroll") for (int k = 0; k < 2; ++k) dst[n][k] = *(const PG8_LAS bf16x8*)(lds + PG8_SB(b, h) + boff + n * 2048 + k * 1024); } while (0)
; #define PG8_MMA(ai, bj, At, Bt) do { __builtin_amdgcn_s_setprio(1); _Pragma("unroll") for (int m = 0; m < 4; ++m) _Pragma("unroll") for (int n = 0; n < 2; ++n) _Pragma("unroll") for (int k = 0; k < 2; ++k) \
;         acc[ai][bj][m][n] = __builtin_amdgcn_mfma_f32_16x16x32_bf16(Bt[n][k], At[m][k], acc[ai][bj][m][n], 0, 0, 0); __builtin_amdgcn_s_setprio(0); } while (0)
; #define PG8_WAIT_V(n) asm volatile("s_waitcnt vmcnt(" #n ")" ::: "memory")
; #define PG8_WAIT_L(n) asm volatile("s_waitcnt lgkmcnt(" #n ")" ::: "memory")
; #define PG8_BAR __builtin_amdgcn_s_barrier()
; #define PG8_SCHED __builtin_amdgcn_sched_barrier(0)
; template <class Epi, class Sched, bool ALIGN_EPI = false, bool SP2 = false>
; __device__ __forceinline__ void gemm_phase(PG8_LAS unsigned char* lds, const Gemm g, const Sched& S, const Epi& E) {
;     ...
;             PG8_WAIT_V(8); PG8_WAIT_L(0); PG8_BAR; PG8_MMA(1, 0, At, B0); PG8_MMA(1, 1, At, B1); PG8_BAR; PG8_SCHED;
;             PG8_LDB(B0, 1, 0); PG8_LDB(B1, 1, 1); PG8_SCHED; PG8_LDA(At, 1, 0); PG8_STAGE(PG8_SA(0, 1), a2 + hstepA, voffA);
;             PG8_WAIT_V(8); PG8_WAIT_L(0); PG8_BAR; PG8_MMA(0, 0, At, B0); PG8_MMA(0, 1, At, B1); PG8_BAR; PG8_SCHED;
	s_setprio 1
	v_mfma_f32_16x16x32_bf16 v[60:63], v[144:147], v[184:187], v[60:63]
	v_mfma_f32_16x16x32_bf16 v[56:59], v[156:159], v[184:187], v[56:59]
	v_mfma_f32_16x16x32_bf16 v[44:47], v[144:147], v[192:195], v[44:47]
	v_mfma_f32_16x16x32_bf16 v[40:43], v[156:159], v[192:195], v[40:43]
	v_mfma_f32_16x16x32_bf16 v[28:31], v[144:147], v[200:203], v[28:31]
	v_mfma_f32_16x16x32_bf16 v[24:27], v[156:159], v[200:203], v[24:27]
	v_mfma_f32_16x16x32_bf16 v[12:15], v[144:147], v[208:211], v[12:15]
	v_mfma_f32_16x16x32_bf16 v[8:11], v[156:159], v[208:211], v[8:11]
	v_mfma_f32_16x16x32_bf16 v[60:63], v[152:155], v[188:191], v[60:63]
	v_mfma_f32_16x16x32_bf16 v[56:59], v[160:163], v[188:191], v[56:59]
	v_mfma_f32_16x16x32_bf16 v[44:47], v[152:155], v[196:199], v[44:47]
	v_mfma_f32_16x16x32_bf16 v[40:43], v[160:163], v[196:199], v[40:43]
	v_mfma_f32_16x16x32_bf16 v[28:31], v[152:155], v[204:207], v[28:31]
	v_mfma_f32_16x16x32_bf16 v[24:27], v[160:163], v[204:207], v[24:27]
	v_mfma_f32_16x16x32_bf16 v[12:15], v[152:155], v[212:215], v[12:15]
	v_mfma_f32_16x16x32_bf16 v[8:11], v[160:163], v[212:215], v[8:11]
	v_mfma_f32_16x16x32_bf16 v[52:55], v[168:171], v[184:187], v[52:55]
	v_mfma_f32_16x16x32_bf16 v[48:51], v[176:179], v[184:187], v[48:51]
	v_mfma_f32_16x16x32_bf16 v[36:39], v[168:171], v[192:195], v[36:39]
	v_mfma_f32_16x16x32_bf16 v[32:35], v[176:179], v[192:195], v[32:35]
	v_mfma_f32_16x16x32_bf16 v[20:23], v[168:171], v[200:203], v[20:23]
	v_mfma_f32_16x16x32_bf16 v[16:19], v[176:179], v[200:203], v[16:19]
	v_mfma_f32_16x16x32_bf16 v[4:7], v[168:171], v[208:211], v[4:7]
	v_mfma_f32_16x16x32_bf16 v[0:3], v[176:179], v[208:211], v[0:3]
	v_mfma_f32_16x16x32_bf16 v[52:55], v[172:175], v[188:191], v[52:55]
	v_mfma_f32_16x16x32_bf16 v[48:51], v[180:183], v[188:191], v[48:51]
	v_mfma_f32_16x16x32_bf16 v[36:39], v[172:175], v[196:199], v[36:39]
	v_mfma_f32_16x16x32_bf16 v[32:35], v[180:183], v[196:199], v[32:35]
	v_mfma_f32_16x16x32_bf16 v[20:23], v[172:175], v[204:207], v[20:23]
	v_mfma_f32_16x16x32_bf16 v[16:19], v[180:183], v[204:207], v[16:19]
	v_mfma_f32_16x16x32_bf16 v[4:7], v[172:175], v[212:215], v[4:7]
	v_mfma_f32_16x16x32_bf16 v[0:3], v[180:183], v[212:215], v[0:3]
	s_setprio 0
	s_barrier
	s_add_i32 s20, 0, 0x18000
	s_add_i32 s21, 0, 0x1c000
	v_add_u32_e32 v160, s20, v148
	v_add_u32_e32 v166, s21, v148
	ds_read_b128 v[144:147], v160
	ds_read_b128 v[152:155], v160 offset:1024
	ds_read_b128 v[156:159], v160 offset:2048
	ds_read_b128 v[160:163], v160 offset:3072
	ds_read_b128 v[168:171], v166
	ds_read_b128 v[172:175], v166 offset:1024
	ds_read_b128 v[176:179], v166 offset:2048
	ds_read_b128 v[180:183], v166 offset:3072
	s_add_u32 s4, s28, 0x160000
	s_addc_u32 s5, s29, 0
	s_mov_b32 m0, s31
	v_lshl_add_u64 v[222:223], s[4:5], 0, v[128:129]
	ds_read_b128 v[184:187], v151 offset:32768
	ds_read_b128 v[188:191], v151 offset:33792
	ds_read_b128 v[192:195], v151 offset:34816
	ds_read_b128 v[196:199], v151 offset:35840
	ds_read_b128 v[200:203], v151 offset:36864
	ds_read_b128 v[204:207], v151 offset:37888
	ds_read_b128 v[208:211], v151 offset:38912
	ds_read_b128 v[212:215], v151 offset:39936
	global_load_lds_dwordx4 v[222:223], off
	v_lshl_add_u64 v[222:223], s[4:5], 0, v[132:133]
	s_mov_b32 m0, s33
	s_nop 0
	global_load_lds_dwordx4 v[222:223], off
	s_waitcnt vmcnt(8)
	s_waitcnt lgkmcnt(0)
	s_barrier
	s_setprio 1
	v_mfma_f32_16x16x32_bf16 v[124:127], v[144:147], v[184:187], v[124:127]
	v_mfma_f32_16x16x32_bf16 v[120:123], v[156:159], v[184:187], v[120:123]
	v_mfma_f32_16x16x32_bf16 v[108:111], v[144:147], v[192:195], v[108:111]
	v_mfma_f32_16x16x32_bf16 v[104:107], v[156:159], v[192:195], v[104:107]
	v_mfma_f32_16x16x32_bf16 v[92:95], v[144:147], v[200:203], v[92:95]
	v_mfma_f32_16x16x32_bf16 v[88:91], v[156:159], v[200:203], v[88:91]
	v_mfma_f32_16x16x32_bf16 v[76:79], v[144:147], v[208:211], v[76:79]
	v_mfma_f32_16x16x32_bf16 v[72:75], v[156:159], v[208:211], v[72:75]
	v_mfma_f32_16x16x32_bf16 v[124:127], v[152:155], v[188:191], v[124:127]
	v_mfma_f32_16x16x32_bf16 v[120:123], v[160:163], v[188:191], v[120:123]
	v_mfma_f32_16x16x32_bf16 v[108:111], v[152:155], v[196:199], v[108:111]
	v_mfma_f32_16x16x32_bf16 v[104:107], v[160:163], v[196:199], v[104:107]
	v_mfma_f32_16x16x32_bf16 v[92:95], v[152:155], v[204:207], v[92:95]
	v_mfma_f32_16x16x32_bf16 v[88:91], v[160:163], v[204:207], v[88:91]
	v_mfma_f32_16x16x32_bf16 v[76:79], v[152:155], v[212:215], v[76:79]
	v_mfma_f32_16x16x32_bf16 v[72:75], v[160:163], v[212:215], v[72:75]
	v_mfma_f32_16x16x32_bf16 v[116:119], v[168:171], v[184:187], v[116:119]
	v_mfma_f32_16x16x32_bf16 v[112:115], v[176:179], v[184:187], v[112:115]
	v_mfma_f32_16x16x32_bf16 v[100:103], v[168:171], v[192:195], v[100:103]
	v_mfma_f32_16x16x32_bf16 v[96:99], v[176:179], v[192:195], v[96:99]
	v_mfma_f32_16x16x32_bf16 v[84:87], v[168:171], v[200:203], v[84:87]
	v_mfma_f32_16x16x32_bf16 v[80:83], v[176:179], v[200:203], v[80:83]
	v_mfma_f32_16x16x32_bf16 v[68:71], v[168:171], v[208:211], v[68:71]
	v_mfma_f32_16x16x32_bf16 v[64:67], v[176:179], v[208:211], v[64:67]
	v_mfma_f32_16x16x32_bf16 v[116:119], v[172:175], v[188:191], v[116:119]
	v_mfma_f32_16x16x32_bf16 v[112:115], v[180:183], v[188:191], v[112:115]
	v_mfma_f32_16x16x32_bf16 v[100:103], v[172:175], v[196:199], v[100:103]
	v_mfma_f32_16x16x32_bf16 v[96:99], v[180:183], v[196:199], v[96:99]
	v_mfma_f32_16x16x32_bf16 v[84:87], v[172:175], v[204:207], v[84:87]
	v_mfma_f32_16x16x32_bf16 v[80:83], v[180:183], v[204:207], v[80:83]
	v_mfma_f32_16x16x32_bf16 v[68:71], v[172:175], v[212:215], v[68:71]
	v_mfma_f32_16x16x32_bf16 v[64:67], v[180:183], v[212:215], v[64:67]
	s_setprio 0
	s_barrier
; #define PG8_STAGE(bufoff, gbase, voff) do { _Pragma("unroll") for (int _i = 0; _i < 2; ++_i) \
;         __builtin_amdgcn_global_load_lds((const unsigned*)((const char*)(gbase) + (voff)[_i]), (PG8_LAS unsigned*)(lds + (bufoff) + ldsw + _i * 8192), 16, 0, 0); } while (0)
; #define PG8_LDA(dst, b, h) do { _Pragma("unroll") for (int m = 0; m < 4; ++m) _Pragma("unroll") for (int k = 0; k < 2; ++k) dst[m][k] = *(const PG8_LAS bf16x8*)(lds + PG8_SA(b, h) + aoff + m * 2048 + k * 1024); } while (0)
; #define PG8_MMA(ai, bj, At, Bt) do { __builtin_amdgcn_s_setprio(1); _Pragma("unroll") for (int m = 0; m < 4; ++m) _Pragma("unroll") for (int n = 0; n < 2; ++n) _Pragma("unroll") for (int k = 0; k < 2; ++k) \
;         acc[ai][bj][m][n] = __builtin_amdgcn_mfma_f32_16x16x32_bf16(Bt[n][k], At[m][k], acc[ai][bj][m][n], 0, 0, 0); __builtin_amdgcn_s_setprio(0); } while (0)
; #define PG8_WAIT_V(n) asm volatile("s_waitcnt vmcnt(" #n ")" ::: "memory")
; #define PG8_WAIT_L(n) asm volatile("s_waitcnt lgkmcnt(" #n ")" ::: "memory")
; #define PG8_BAR __builtin_amdgcn_s_barrier()
; #define PG8_SCHED __builtin_amdgcn_sched_barrier(0)
; template <class Epi, class Sched, bool ALIGN_EPI = false, bool SP2 = false>
; __device__ __forceinline__ void gemm_phase(PG8_LAS unsigned char* lds, const Gemm g, const Sched& S, const Epi& E) {
;     ...
;             PG8_LDA(At, 1, 1); PG8_STAGE(PG8_SB(1, 0), b3, voffB); PG8_STAGE(PG8_SB(1, 1), b3 + hstepB, voffB); PG8_STAGE(PG8_SA(1, 0), a3, voffA);
;             PG8_WAIT_V(8); PG8_WAIT_L(0); PG8_BAR; PG8_MMA(1, 0, At, B0); PG8_MMA(1, 1, At, B1); PG8_BAR; PG8_SCHED;
	s_add_i32 s4, s20, s47
	v_lshl_add_u64 v[164:165], v[164:165], 0, s[16:17]
	s_mov_b32 m0, s4
	ds_read_b128 v[184:187], v151 offset:49152
	ds_read_b128 v[188:191], v151 offset:50176
	ds_read_b128 v[192:195], v151 offset:51200
	ds_read_b128 v[196:199], v151 offset:52224
	ds_read_b128 v[200:203], v151 offset:53248
	ds_read_b128 v[204:207], v151 offset:54272
	ds_read_b128 v[208:211], v151 offset:55296
	ds_read_b128 v[212:215], v151 offset:56320
	global_load_lds_dwordx4 v[164:165], off
	s_add_i32 m0, s4, 0x2000
	s_add_u32 s4, s26, 0x160080
	v_lshl_add_u64 v[164:165], v[216:217], 0, s[16:17]
	s_addc_u32 s5, s27, 0
	s_add_i32 s20, s21, s47
	global_load_lds_dwordx4 v[164:165], off
	v_lshl_add_u64 v[164:165], s[4:5], 0, v[130:131]
	s_mov_b32 m0, s20
	s_nop 0
	global_load_lds_dwordx4 v[164:165], off
	v_lshl_add_u64 v[164:165], s[4:5], 0, v[134:135]
	s_add_i32 m0, s20, 0x2000
	s_nop 0
	global_load_lds_dwordx4 v[164:165], off
	v_lshl_add_u64 v[164:165], v[218:219], 0, s[16:17]
	s_mov_b32 m0, s34
	s_nop 0
	global_load_lds_dwordx4 v[164:165], off
	v_lshl_add_u64 v[164:165], v[220:221], 0, s[16:17]
	s_mov_b32 m0, s35
	s_nop 0
	global_load_lds_dwordx4 v[164:165], off
	s_waitcnt vmcnt(8)
	s_waitcnt lgkmcnt(0)
	s_barrier
	s_setprio 1
	v_mfma_f32_16x16x32_bf16 v[60:63], v[144:147], v[184:187], v[60:63]
	v_mfma_f32_16x16x32_bf16 v[56:59], v[156:159], v[184:187], v[56:59]
	v_mfma_f32_16x16x32_bf16 v[44:47], v[144:147], v[192:195], v[44:47]
	v_mfma_f32_16x16x32_bf16 v[40:43], v[156:159], v[192:195], v[40:43]
	v_mfma_f32_16x16x32_bf16 v[28:31], v[144:147], v[200:203], v[28:31]
	v_mfma_f32_16x16x32_bf16 v[24:27], v[156:159], v[200:203], v[24:27]
	v_mfma_f32_16x16x32_bf16 v[12:15], v[144:147], v[208:211], v[12:15]
	v_mfma_f32_16x16x32_bf16 v[8:11], v[156:159], v[208:211], v[8:11]
	v_mfma_f32_16x16x32_bf16 v[60:63], v[152:155], v[188:191], v[60:63]
	v_mfma_f32_16x16x32_bf16 v[56:59], v[160:163], v[188:191], v[56:59]
	v_mfma_f32_16x16x32_bf16 v[44:47], v[152:155], v[196:199], v[44:47]
	v_mfma_f32_16x16x32_bf16 v[40:43], v[160:163], v[196:199], v[40:43]
	v_mfma_f32_16x16x32_bf16 v[28:31], v[152:155], v[204:207], v[28:31]
	v_mfma_f32_16x16x32_bf16 v[24:27], v[160:163], v[204:207], v[24:27]
	v_mfma_f32_16x16x32_bf16 v[12:15], v[152:155], v[212:215], v[12:15]
	v_mfma_f32_16x16x32_bf16 v[8:11], v[160:163], v[212:215], v[8:11]
	v_mfma_f32_16x16x32_bf16 v[52:55], v[168:171], v[184:187], v[52:55]
	v_mfma_f32_16x16x32_bf16 v[48:51], v[176:179], v[184:187], v[48:51]
	v_mfma_f32_16x16x32_bf16 v[36:39], v[168:171], v[192:195], v[36:39]
	v_mfma_f32_16x16x32_bf16 v[32:35], v[176:179], v[192:195], v[32:35]
	v_mfma_f32_16x16x32_bf16 v[20:23], v[168:171], v[200:203], v[20:23]
	v_mfma_f32_16x16x32_bf16 v[16:19], v[176:179], v[200:203], v[16:19]
	v_mfma_f32_16x16x32_bf16 v[4:7], v[168:171], v[208:211], v[4:7]
	v_mfma_f32_16x16x32_bf16 v[0:3], v[176:179], v[208:211], v[0:3]
	v_mfma_f32_16x16x32_bf16 v[52:55], v[172:175], v[188:191], v[52:55]
	v_mfma_f32_16x16x32_bf16 v[48:51], v[180:183], v[188:191], v[48:51]
	v_mfma_f32_16x16x32_bf16 v[36:39], v[172:175], v[196:199], v[36:39]
	v_mfma_f32_16x16x32_bf16 v[32:35], v[180:183], v[196:199], v[32:35]
	v_mfma_f32_16x16x32_bf16 v[20:23], v[172:175], v[204:207], v[20:23]
	v_mfma_f32_16x16x32_bf16 v[16:19], v[180:183], v[204:207], v[16:19]
	v_mfma_f32_16x16x32_bf16 v[4:7], v[172:175], v[212:215], v[4:7]
	v_mfma_f32_16x16x32_bf16 v[0:3], v[180:183], v[212:215], v[0:3]
	s_setprio 0
	s_barrier
	s_add_i32 s50, s50, 2
	s_add_u32 s45, s45, 0x100
	s_addc_u32 s46, s46, 0
	s_cmpk_gt_u32 s50, 0x55
	s_mov_b64 s[20:21], s[22:23]
	s_cbranch_scc0 .LBB0_1361
	s_and_b64 vcc, exec, s[48:49]
	s_cbranch_vccz .LBB0_1364
	s_barrier
